# GEMM loops: first K-iteration peeled with srcC=0 MFMAs, accumulator zeroing (128 v_mov per tile) removed
# speedup vs baseline: 1.0080x; 1.0080x over previous
.LBB0_110:
	s_ashr_i32 s35, s34, 31
	s_lshl_b64 s[12:13], s[34:35], 19
	s_add_u32 s38, s82, s12
	s_addc_u32 s39, s83, s13
	s_and_b64 s[12:13], s[4:5], exec
	s_cselect_b32 s12, s39, s41
	s_cselect_b32 s13, s38, s40
	s_ashr_i32 s37, s36, 31
	s_lshl_b64 s[14:15], s[36:37], 19
	s_add_u32 s86, s42, s14
	s_addc_u32 s87, s43, s15
	s_and_b64 s[14:15], s[4:5], exec
	s_cselect_b32 s14, s87, s81
	s_cselect_b32 s15, s86, s80
	s_add_u32 s40, s40, 0x40080
	s_addc_u32 s41, s41, 0
	s_add_u32 s16, s80, 0x100
	s_addc_u32 s17, s81, 0
	s_mov_b32 s18, -2
	ds_read_b128 v[162:165], v155
	ds_read_b128 v[166:169], v155 offset:1024
	ds_read_b128 v[170:173], v155 offset:2048
	ds_read_b128 v[174:177], v155 offset:3072
	ds_read_b128 v[178:181], v157
	ds_read_b128 v[186:189], v157 offset:1024
	ds_read_b128 v[190:193], v157 offset:2048
	ds_read_b128 v[194:197], v157 offset:3072
	s_add_u32 s19, s40, 0xfffc0080
	s_addc_u32 s20, s41, -1
	s_cmp_eq_u32 s18, 12
	s_cselect_b32 s89, s12, s20
	s_cselect_b32 s88, s13, s19
	s_cselect_b32 s81, s14, s17
	s_cselect_b32 s80, s15, s16
	s_add_i32 m0, s62, 0xc000
	ds_read_b128 v[198:201], v159
	ds_read_b128 v[202:205], v159 offset:1024
	ds_read_b128 v[206:209], v159 offset:2048
	ds_read_b128 v[210:213], v159 offset:3072
	ds_read_b128 v[214:217], v159 offset:4096
	ds_read_b128 v[218:221], v159 offset:5120
	ds_read_b128 v[222:225], v159 offset:6144
	ds_read_b128 v[226:229], v159 offset:7168
	global_load_lds_dwordx4 v136, s[40:41]
	s_add_i32 m0, s62, 0xe000
	s_nop 0
	global_load_lds_dwordx4 v138, s[40:41]
	s_waitcnt vmcnt(8)
	s_waitcnt lgkmcnt(0)
	s_barrier
	s_waitcnt lgkmcnt(0)
	v_mfma_f32_16x16x32_bf16 v[124:127], v[162:165], v[198:201], 0
	v_mfma_f32_16x16x32_bf16 v[120:123], v[170:173], v[198:201], 0
	v_mfma_f32_16x16x32_bf16 v[108:111], v[162:165], v[206:209], 0
	v_mfma_f32_16x16x32_bf16 v[100:103], v[170:173], v[206:209], 0
	v_mfma_f32_16x16x32_bf16 v[92:95], v[162:165], v[214:217], 0
	v_mfma_f32_16x16x32_bf16 v[84:87], v[170:173], v[214:217], 0
	v_mfma_f32_16x16x32_bf16 v[76:79], v[162:165], v[222:225], 0
	v_mfma_f32_16x16x32_bf16 v[68:71], v[170:173], v[222:225], 0
	v_mfma_f32_16x16x32_bf16 v[124:127], v[166:169], v[202:205], v[124:127]
	v_mfma_f32_16x16x32_bf16 v[120:123], v[174:177], v[202:205], v[120:123]
	v_mfma_f32_16x16x32_bf16 v[108:111], v[166:169], v[210:213], v[108:111]
	v_mfma_f32_16x16x32_bf16 v[100:103], v[174:177], v[210:213], v[100:103]
	v_mfma_f32_16x16x32_bf16 v[92:95], v[166:169], v[218:221], v[92:95]
	v_mfma_f32_16x16x32_bf16 v[84:87], v[174:177], v[218:221], v[84:87]
	v_mfma_f32_16x16x32_bf16 v[76:79], v[166:169], v[226:229], v[76:79]
	v_mfma_f32_16x16x32_bf16 v[68:71], v[174:177], v[226:229], v[68:71]
	v_mfma_f32_16x16x32_bf16 v[116:119], v[178:181], v[198:201], 0
	v_mfma_f32_16x16x32_bf16 v[112:115], v[190:193], v[198:201], 0
	v_mfma_f32_16x16x32_bf16 v[104:107], v[178:181], v[206:209], 0
	v_mfma_f32_16x16x32_bf16 v[96:99], v[190:193], v[206:209], 0
	v_mfma_f32_16x16x32_bf16 v[88:91], v[178:181], v[214:217], 0
	v_mfma_f32_16x16x32_bf16 v[80:83], v[190:193], v[214:217], 0
	v_mfma_f32_16x16x32_bf16 v[72:75], v[178:181], v[222:225], 0
	v_mfma_f32_16x16x32_bf16 v[64:67], v[190:193], v[222:225], 0
	v_mfma_f32_16x16x32_bf16 v[116:119], v[186:189], v[202:205], v[116:119]
	v_mfma_f32_16x16x32_bf16 v[112:115], v[194:197], v[202:205], v[112:115]
	v_mfma_f32_16x16x32_bf16 v[104:107], v[186:189], v[210:213], v[104:107]
	v_mfma_f32_16x16x32_bf16 v[96:99], v[194:197], v[210:213], v[96:99]
	v_mfma_f32_16x16x32_bf16 v[88:91], v[186:189], v[218:221], v[88:91]
	v_mfma_f32_16x16x32_bf16 v[80:83], v[194:197], v[218:221], v[80:83]
	v_mfma_f32_16x16x32_bf16 v[72:75], v[186:189], v[226:229], v[72:75]
	v_mfma_f32_16x16x32_bf16 v[64:67], v[194:197], v[226:229], v[64:67]
	s_barrier
	s_add_i32 s19, s73, s3
	s_mov_b32 m0, s19
	ds_read_b128 v[198:201], v159 offset:16384
	ds_read_b128 v[202:205], v159 offset:17408
	ds_read_b128 v[206:209], v159 offset:18432
	ds_read_b128 v[210:213], v159 offset:19456
	ds_read_b128 v[214:217], v159 offset:20480
	ds_read_b128 v[218:221], v159 offset:21504
	ds_read_b128 v[222:225], v159 offset:22528
	ds_read_b128 v[226:229], v159 offset:23552
	global_load_lds_dwordx4 v132, s[80:81]
	s_add_i32 m0, s19, 0x2000
	s_add_u32 s20, s80, 0x40000
	s_addc_u32 s21, s81, 0
	s_add_i32 s19, s74, s3
	global_load_lds_dwordx4 v128, s[80:81]
	s_mov_b32 m0, s19
	global_load_lds_dwordx4 v132, s[20:21]
	s_add_i32 m0, s19, 0x2000
	s_nop 0
	global_load_lds_dwordx4 v128, s[20:21]
	s_mov_b32 m0, s62
	s_nop 0
	global_load_lds_dwordx4 v134, s[88:89]
	s_mov_b32 m0, s63
	s_nop 0
	global_load_lds_dwordx4 v130, s[88:89]
	s_add_u32 s98, s80, s28
	s_addc_u32 s99, s81, s29
	s_add_u32 s100, s88, s28
	s_addc_u32 s101, s89, s29
	s_waitcnt vmcnt(8)
	s_waitcnt lgkmcnt(0)
	s_barrier
	s_waitcnt lgkmcnt(0)
	v_mfma_f32_16x16x32_bf16 v[60:63], v[162:165], v[198:201], 0
	v_mfma_f32_16x16x32_bf16 v[52:55], v[170:173], v[198:201], 0
	v_mfma_f32_16x16x32_bf16 v[44:47], v[162:165], v[206:209], 0
	v_mfma_f32_16x16x32_bf16 v[36:39], v[170:173], v[206:209], 0
	v_mfma_f32_16x16x32_bf16 v[28:31], v[162:165], v[214:217], 0
	v_mfma_f32_16x16x32_bf16 v[20:23], v[170:173], v[214:217], 0
	v_mfma_f32_16x16x32_bf16 v[12:15], v[162:165], v[222:225], 0
	v_mfma_f32_16x16x32_bf16 v[4:7], v[170:173], v[222:225], 0
	v_mfma_f32_16x16x32_bf16 v[60:63], v[166:169], v[202:205], v[60:63]
	v_mfma_f32_16x16x32_bf16 v[52:55], v[174:177], v[202:205], v[52:55]
	v_mfma_f32_16x16x32_bf16 v[44:47], v[166:169], v[210:213], v[44:47]
	v_mfma_f32_16x16x32_bf16 v[36:39], v[174:177], v[210:213], v[36:39]
	v_mfma_f32_16x16x32_bf16 v[28:31], v[166:169], v[218:221], v[28:31]
	v_mfma_f32_16x16x32_bf16 v[20:23], v[174:177], v[218:221], v[20:23]
	v_mfma_f32_16x16x32_bf16 v[12:15], v[166:169], v[226:229], v[12:15]
	v_mfma_f32_16x16x32_bf16 v[4:7], v[174:177], v[226:229], v[4:7]
	v_mfma_f32_16x16x32_bf16 v[56:59], v[178:181], v[198:201], 0
	v_mfma_f32_16x16x32_bf16 v[48:51], v[190:193], v[198:201], 0
	v_mfma_f32_16x16x32_bf16 v[40:43], v[178:181], v[206:209], 0
	v_mfma_f32_16x16x32_bf16 v[32:35], v[190:193], v[206:209], 0
	v_mfma_f32_16x16x32_bf16 v[24:27], v[178:181], v[214:217], 0
	v_mfma_f32_16x16x32_bf16 v[16:19], v[190:193], v[214:217], 0
	v_mfma_f32_16x16x32_bf16 v[8:11], v[178:181], v[222:225], 0
	v_mfma_f32_16x16x32_bf16 v[0:3], v[190:193], v[222:225], 0
	v_mfma_f32_16x16x32_bf16 v[56:59], v[186:189], v[202:205], v[56:59]
	v_mfma_f32_16x16x32_bf16 v[48:51], v[194:197], v[202:205], v[48:51]
	v_mfma_f32_16x16x32_bf16 v[40:43], v[186:189], v[210:213], v[40:43]
	v_mfma_f32_16x16x32_bf16 v[32:35], v[194:197], v[210:213], v[32:35]
	v_mfma_f32_16x16x32_bf16 v[24:27], v[186:189], v[218:221], v[24:27]
	v_mfma_f32_16x16x32_bf16 v[16:19], v[194:197], v[218:221], v[16:19]
	v_mfma_f32_16x16x32_bf16 v[8:11], v[186:189], v[226:229], v[8:11]
	v_mfma_f32_16x16x32_bf16 v[0:3], v[194:197], v[226:229], v[0:3]
	s_barrier
	s_add_i32 s19, 0, 0x18000
	v_add_u32_e32 v146, s19, v151
	s_add_i32 s22, 0, 0x1c000
	ds_read_b128 v[162:165], v146
	ds_read_b128 v[166:169], v146 offset:1024
	ds_read_b128 v[170:173], v146 offset:2048
	ds_read_b128 v[174:177], v146 offset:3072
	v_add_u32_e32 v146, s22, v151
	ds_read_b128 v[178:181], v146
	ds_read_b128 v[186:189], v146 offset:1024
	ds_read_b128 v[190:193], v146 offset:2048
	ds_read_b128 v[194:197], v146 offset:3072
	s_add_u32 s20, s88, 0x40000
	s_addc_u32 s21, s89, 0
	s_mov_b32 m0, s64
	ds_read_b128 v[198:201], v159 offset:32768
	ds_read_b128 v[202:205], v159 offset:33792
	ds_read_b128 v[206:209], v159 offset:34816
	ds_read_b128 v[210:213], v159 offset:35840
	ds_read_b128 v[214:217], v159 offset:36864
	ds_read_b128 v[218:221], v159 offset:37888
	ds_read_b128 v[222:225], v159 offset:38912
	ds_read_b128 v[226:229], v159 offset:39936
	global_load_lds_dwordx4 v134, s[20:21]
	s_mov_b32 m0, s65
	s_nop 0
	global_load_lds_dwordx4 v130, s[20:21]
	s_waitcnt vmcnt(8)
	s_waitcnt lgkmcnt(0)
	s_barrier
	s_waitcnt lgkmcnt(0)
	v_mfma_f32_16x16x32_bf16 v[124:127], v[162:165], v[198:201], v[124:127]
	v_mfma_f32_16x16x32_bf16 v[120:123], v[170:173], v[198:201], v[120:123]
	v_mfma_f32_16x16x32_bf16 v[108:111], v[162:165], v[206:209], v[108:111]
	v_mfma_f32_16x16x32_bf16 v[100:103], v[170:173], v[206:209], v[100:103]
	v_mfma_f32_16x16x32_bf16 v[92:95], v[162:165], v[214:217], v[92:95]
	v_mfma_f32_16x16x32_bf16 v[84:87], v[170:173], v[214:217], v[84:87]
	v_mfma_f32_16x16x32_bf16 v[76:79], v[162:165], v[222:225], v[76:79]
	v_mfma_f32_16x16x32_bf16 v[68:71], v[170:173], v[222:225], v[68:71]
	v_mfma_f32_16x16x32_bf16 v[124:127], v[166:169], v[202:205], v[124:127]
	v_mfma_f32_16x16x32_bf16 v[120:123], v[174:177], v[202:205], v[120:123]
	v_mfma_f32_16x16x32_bf16 v[108:111], v[166:169], v[210:213], v[108:111]
	v_mfma_f32_16x16x32_bf16 v[100:103], v[174:177], v[210:213], v[100:103]
	v_mfma_f32_16x16x32_bf16 v[92:95], v[166:169], v[218:221], v[92:95]
	v_mfma_f32_16x16x32_bf16 v[84:87], v[174:177], v[218:221], v[84:87]
	v_mfma_f32_16x16x32_bf16 v[76:79], v[166:169], v[226:229], v[76:79]
	v_mfma_f32_16x16x32_bf16 v[68:71], v[174:177], v[226:229], v[68:71]
	v_mfma_f32_16x16x32_bf16 v[116:119], v[178:181], v[198:201], v[116:119]
	v_mfma_f32_16x16x32_bf16 v[112:115], v[190:193], v[198:201], v[112:115]
	v_mfma_f32_16x16x32_bf16 v[104:107], v[178:181], v[206:209], v[104:107]
	v_mfma_f32_16x16x32_bf16 v[96:99], v[190:193], v[206:209], v[96:99]
	v_mfma_f32_16x16x32_bf16 v[88:91], v[178:181], v[214:217], v[88:91]
	v_mfma_f32_16x16x32_bf16 v[80:83], v[190:193], v[214:217], v[80:83]
	v_mfma_f32_16x16x32_bf16 v[72:75], v[178:181], v[222:225], v[72:75]
	v_mfma_f32_16x16x32_bf16 v[64:67], v[190:193], v[222:225], v[64:67]
	v_mfma_f32_16x16x32_bf16 v[116:119], v[186:189], v[202:205], v[116:119]
	v_mfma_f32_16x16x32_bf16 v[112:115], v[194:197], v[202:205], v[112:115]
	v_mfma_f32_16x16x32_bf16 v[104:107], v[186:189], v[210:213], v[104:107]
	v_mfma_f32_16x16x32_bf16 v[96:99], v[194:197], v[210:213], v[96:99]
	v_mfma_f32_16x16x32_bf16 v[88:91], v[186:189], v[218:221], v[88:91]
	v_mfma_f32_16x16x32_bf16 v[80:83], v[194:197], v[218:221], v[80:83]
	v_mfma_f32_16x16x32_bf16 v[72:75], v[186:189], v[226:229], v[72:75]
	v_mfma_f32_16x16x32_bf16 v[64:67], v[194:197], v[226:229], v[64:67]
	s_barrier
	s_add_i32 s19, s19, s3
	s_mov_b32 m0, s19
	ds_read_b128 v[198:201], v159 offset:49152
	ds_read_b128 v[202:205], v159 offset:50176
	ds_read_b128 v[206:209], v159 offset:51200
	ds_read_b128 v[210:213], v159 offset:52224
	ds_read_b128 v[214:217], v159 offset:53248
	ds_read_b128 v[218:221], v159 offset:54272
	ds_read_b128 v[222:225], v159 offset:55296
	ds_read_b128 v[226:229], v159 offset:56320
	global_load_lds_dwordx4 v132, s[98:99]
	s_add_i32 m0, s19, 0x2000
	s_add_u32 s20, s80, 0x40080
	s_addc_u32 s21, s81, 0
	s_add_i32 s19, s22, s3
	global_load_lds_dwordx4 v128, s[98:99]
	s_mov_b32 m0, s19
	s_nop 0
	global_load_lds_dwordx4 v132, s[20:21]
	s_add_i32 m0, s19, 0x2000
	s_nop 0
	global_load_lds_dwordx4 v128, s[20:21]
	s_mov_b32 m0, s67
	s_nop 0
	global_load_lds_dwordx4 v134, s[100:101]
	s_mov_b32 m0, s70
	s_nop 0
	global_load_lds_dwordx4 v130, s[100:101]
	s_waitcnt vmcnt(8)
	s_waitcnt lgkmcnt(0)
	s_barrier
	s_waitcnt lgkmcnt(0)
	v_mfma_f32_16x16x32_bf16 v[60:63], v[162:165], v[198:201], v[60:63]
	v_mfma_f32_16x16x32_bf16 v[52:55], v[170:173], v[198:201], v[52:55]
	v_mfma_f32_16x16x32_bf16 v[44:47], v[162:165], v[206:209], v[44:47]
	v_mfma_f32_16x16x32_bf16 v[36:39], v[170:173], v[206:209], v[36:39]
	v_mfma_f32_16x16x32_bf16 v[28:31], v[162:165], v[214:217], v[28:31]
	v_mfma_f32_16x16x32_bf16 v[20:23], v[170:173], v[214:217], v[20:23]
	v_mfma_f32_16x16x32_bf16 v[12:15], v[162:165], v[222:225], v[12:15]
	v_mfma_f32_16x16x32_bf16 v[4:7], v[170:173], v[222:225], v[4:7]
	v_mfma_f32_16x16x32_bf16 v[60:63], v[166:169], v[202:205], v[60:63]
	v_mfma_f32_16x16x32_bf16 v[52:55], v[174:177], v[202:205], v[52:55]
	v_mfma_f32_16x16x32_bf16 v[44:47], v[166:169], v[210:213], v[44:47]
	v_mfma_f32_16x16x32_bf16 v[36:39], v[174:177], v[210:213], v[36:39]
	v_mfma_f32_16x16x32_bf16 v[28:31], v[166:169], v[218:221], v[28:31]
	v_mfma_f32_16x16x32_bf16 v[20:23], v[174:177], v[218:221], v[20:23]
	v_mfma_f32_16x16x32_bf16 v[12:15], v[166:169], v[226:229], v[12:15]
	v_mfma_f32_16x16x32_bf16 v[4:7], v[174:177], v[226:229], v[4:7]
	v_mfma_f32_16x16x32_bf16 v[56:59], v[178:181], v[198:201], v[56:59]
	v_mfma_f32_16x16x32_bf16 v[48:51], v[190:193], v[198:201], v[48:51]
	v_mfma_f32_16x16x32_bf16 v[40:43], v[178:181], v[206:209], v[40:43]
	v_mfma_f32_16x16x32_bf16 v[32:35], v[190:193], v[206:209], v[32:35]
	v_mfma_f32_16x16x32_bf16 v[24:27], v[178:181], v[214:217], v[24:27]
	v_mfma_f32_16x16x32_bf16 v[16:19], v[190:193], v[214:217], v[16:19]
	v_mfma_f32_16x16x32_bf16 v[8:11], v[178:181], v[222:225], v[8:11]
	v_mfma_f32_16x16x32_bf16 v[0:3], v[190:193], v[222:225], v[0:3]
	v_mfma_f32_16x16x32_bf16 v[56:59], v[186:189], v[202:205], v[56:59]
	v_mfma_f32_16x16x32_bf16 v[48:51], v[194:197], v[202:205], v[48:51]
	v_mfma_f32_16x16x32_bf16 v[40:43], v[186:189], v[210:213], v[40:43]
	v_mfma_f32_16x16x32_bf16 v[32:35], v[194:197], v[210:213], v[32:35]
	v_mfma_f32_16x16x32_bf16 v[24:27], v[186:189], v[218:221], v[24:27]
	v_mfma_f32_16x16x32_bf16 v[16:19], v[194:197], v[218:221], v[16:19]
	v_mfma_f32_16x16x32_bf16 v[8:11], v[186:189], v[226:229], v[8:11]
	v_mfma_f32_16x16x32_bf16 v[0:3], v[194:197], v[226:229], v[0:3]
	s_barrier
	s_add_i32 s18, s18, 2
	s_add_u32 s40, s40, 0x100
	s_addc_u32 s41, s41, 0
	s_add_u32 s16, s16, 0x100
	s_addc_u32 s17, s17, 0
	s_cmp_gt_u32 s18, 13
	s_cbranch_scc1 .Lpeel_exit_111
.LBB0_111:
	ds_read_b128 v[162:165], v155
	ds_read_b128 v[166:169], v155 offset:1024
	ds_read_b128 v[170:173], v155 offset:2048
	ds_read_b128 v[174:177], v155 offset:3072
	ds_read_b128 v[178:181], v157
	ds_read_b128 v[186:189], v157 offset:1024
	ds_read_b128 v[190:193], v157 offset:2048
	ds_read_b128 v[194:197], v157 offset:3072
	s_add_u32 s19, s40, 0xfffc0080
	s_addc_u32 s20, s41, -1
	s_cmp_eq_u32 s18, 12
	s_cselect_b32 s89, s12, s20
	s_cselect_b32 s88, s13, s19
	s_cselect_b32 s81, s14, s17
	s_cselect_b32 s80, s15, s16
	s_add_i32 m0, s62, 0xc000
	ds_read_b128 v[198:201], v159
	ds_read_b128 v[202:205], v159 offset:1024
	ds_read_b128 v[206:209], v159 offset:2048
	ds_read_b128 v[210:213], v159 offset:3072
	ds_read_b128 v[214:217], v159 offset:4096
	ds_read_b128 v[218:221], v159 offset:5120
	ds_read_b128 v[222:225], v159 offset:6144
	ds_read_b128 v[226:229], v159 offset:7168
	global_load_lds_dwordx4 v136, s[40:41]
	s_add_i32 m0, s62, 0xe000
	s_nop 0
	global_load_lds_dwordx4 v138, s[40:41]
	s_waitcnt vmcnt(8)
	s_waitcnt lgkmcnt(0)
	s_barrier
	s_waitcnt lgkmcnt(0)
	v_mfma_f32_16x16x32_bf16 v[124:127], v[162:165], v[198:201], v[124:127]
	v_mfma_f32_16x16x32_bf16 v[120:123], v[170:173], v[198:201], v[120:123]
	v_mfma_f32_16x16x32_bf16 v[108:111], v[162:165], v[206:209], v[108:111]
	v_mfma_f32_16x16x32_bf16 v[100:103], v[170:173], v[206:209], v[100:103]
	v_mfma_f32_16x16x32_bf16 v[92:95], v[162:165], v[214:217], v[92:95]
	v_mfma_f32_16x16x32_bf16 v[84:87], v[170:173], v[214:217], v[84:87]
	v_mfma_f32_16x16x32_bf16 v[76:79], v[162:165], v[222:225], v[76:79]
	v_mfma_f32_16x16x32_bf16 v[68:71], v[170:173], v[222:225], v[68:71]
	v_mfma_f32_16x16x32_bf16 v[124:127], v[166:169], v[202:205], v[124:127]
	v_mfma_f32_16x16x32_bf16 v[120:123], v[174:177], v[202:205], v[120:123]
	v_mfma_f32_16x16x32_bf16 v[108:111], v[166:169], v[210:213], v[108:111]
	v_mfma_f32_16x16x32_bf16 v[100:103], v[174:177], v[210:213], v[100:103]
	v_mfma_f32_16x16x32_bf16 v[92:95], v[166:169], v[218:221], v[92:95]
	v_mfma_f32_16x16x32_bf16 v[84:87], v[174:177], v[218:221], v[84:87]
	v_mfma_f32_16x16x32_bf16 v[76:79], v[166:169], v[226:229], v[76:79]
	v_mfma_f32_16x16x32_bf16 v[68:71], v[174:177], v[226:229], v[68:71]
	v_mfma_f32_16x16x32_bf16 v[116:119], v[178:181], v[198:201], v[116:119]
	v_mfma_f32_16x16x32_bf16 v[112:115], v[190:193], v[198:201], v[112:115]
	v_mfma_f32_16x16x32_bf16 v[104:107], v[178:181], v[206:209], v[104:107]
	v_mfma_f32_16x16x32_bf16 v[96:99], v[190:193], v[206:209], v[96:99]
	v_mfma_f32_16x16x32_bf16 v[88:91], v[178:181], v[214:217], v[88:91]
	v_mfma_f32_16x16x32_bf16 v[80:83], v[190:193], v[214:217], v[80:83]
	v_mfma_f32_16x16x32_bf16 v[72:75], v[178:181], v[222:225], v[72:75]
	v_mfma_f32_16x16x32_bf16 v[64:67], v[190:193], v[222:225], v[64:67]
	v_mfma_f32_16x16x32_bf16 v[116:119], v[186:189], v[202:205], v[116:119]
	v_mfma_f32_16x16x32_bf16 v[112:115], v[194:197], v[202:205], v[112:115]
	v_mfma_f32_16x16x32_bf16 v[104:107], v[186:189], v[210:213], v[104:107]
	v_mfma_f32_16x16x32_bf16 v[96:99], v[194:197], v[210:213], v[96:99]
	v_mfma_f32_16x16x32_bf16 v[88:91], v[186:189], v[218:221], v[88:91]
	v_mfma_f32_16x16x32_bf16 v[80:83], v[194:197], v[218:221], v[80:83]
	v_mfma_f32_16x16x32_bf16 v[72:75], v[186:189], v[226:229], v[72:75]
	v_mfma_f32_16x16x32_bf16 v[64:67], v[194:197], v[226:229], v[64:67]
	s_barrier
	s_add_i32 s19, s73, s3
	s_mov_b32 m0, s19
	ds_read_b128 v[198:201], v159 offset:16384
	ds_read_b128 v[202:205], v159 offset:17408
	ds_read_b128 v[206:209], v159 offset:18432
	ds_read_b128 v[210:213], v159 offset:19456
	ds_read_b128 v[214:217], v159 offset:20480
	ds_read_b128 v[218:221], v159 offset:21504
	ds_read_b128 v[222:225], v159 offset:22528
	ds_read_b128 v[226:229], v159 offset:23552
	global_load_lds_dwordx4 v132, s[80:81]
	s_add_i32 m0, s19, 0x2000
	s_add_u32 s20, s80, 0x40000
	s_addc_u32 s21, s81, 0
	s_add_i32 s19, s74, s3
	global_load_lds_dwordx4 v128, s[80:81]
	s_mov_b32 m0, s19
	global_load_lds_dwordx4 v132, s[20:21]
	s_add_i32 m0, s19, 0x2000
	s_nop 0
	global_load_lds_dwordx4 v128, s[20:21]
	s_mov_b32 m0, s62
	s_nop 0
	global_load_lds_dwordx4 v134, s[88:89]
	s_mov_b32 m0, s63
	s_nop 0
	global_load_lds_dwordx4 v130, s[88:89]
	s_add_u32 s98, s80, s28
	s_addc_u32 s99, s81, s29
	s_add_u32 s100, s88, s28
	s_addc_u32 s101, s89, s29
	s_waitcnt vmcnt(8)
	s_waitcnt lgkmcnt(0)
	s_barrier
	s_waitcnt lgkmcnt(0)
	v_mfma_f32_16x16x32_bf16 v[60:63], v[162:165], v[198:201], v[60:63]
	v_mfma_f32_16x16x32_bf16 v[52:55], v[170:173], v[198:201], v[52:55]
	v_mfma_f32_16x16x32_bf16 v[44:47], v[162:165], v[206:209], v[44:47]
	v_mfma_f32_16x16x32_bf16 v[36:39], v[170:173], v[206:209], v[36:39]
	v_mfma_f32_16x16x32_bf16 v[28:31], v[162:165], v[214:217], v[28:31]
	v_mfma_f32_16x16x32_bf16 v[20:23], v[170:173], v[214:217], v[20:23]
	v_mfma_f32_16x16x32_bf16 v[12:15], v[162:165], v[222:225], v[12:15]
	v_mfma_f32_16x16x32_bf16 v[4:7], v[170:173], v[222:225], v[4:7]
	v_mfma_f32_16x16x32_bf16 v[60:63], v[166:169], v[202:205], v[60:63]
	v_mfma_f32_16x16x32_bf16 v[52:55], v[174:177], v[202:205], v[52:55]
	v_mfma_f32_16x16x32_bf16 v[44:47], v[166:169], v[210:213], v[44:47]
	v_mfma_f32_16x16x32_bf16 v[36:39], v[174:177], v[210:213], v[36:39]
	v_mfma_f32_16x16x32_bf16 v[28:31], v[166:169], v[218:221], v[28:31]
	v_mfma_f32_16x16x32_bf16 v[20:23], v[174:177], v[218:221], v[20:23]
	v_mfma_f32_16x16x32_bf16 v[12:15], v[166:169], v[226:229], v[12:15]
	v_mfma_f32_16x16x32_bf16 v[4:7], v[174:177], v[226:229], v[4:7]
	v_mfma_f32_16x16x32_bf16 v[56:59], v[178:181], v[198:201], v[56:59]
	v_mfma_f32_16x16x32_bf16 v[48:51], v[190:193], v[198:201], v[48:51]
	v_mfma_f32_16x16x32_bf16 v[40:43], v[178:181], v[206:209], v[40:43]
	v_mfma_f32_16x16x32_bf16 v[32:35], v[190:193], v[206:209], v[32:35]
	v_mfma_f32_16x16x32_bf16 v[24:27], v[178:181], v[214:217], v[24:27]
	v_mfma_f32_16x16x32_bf16 v[16:19], v[190:193], v[214:217], v[16:19]
	v_mfma_f32_16x16x32_bf16 v[8:11], v[178:181], v[222:225], v[8:11]
	v_mfma_f32_16x16x32_bf16 v[0:3], v[190:193], v[222:225], v[0:3]
	v_mfma_f32_16x16x32_bf16 v[56:59], v[186:189], v[202:205], v[56:59]
	v_mfma_f32_16x16x32_bf16 v[48:51], v[194:197], v[202:205], v[48:51]
	v_mfma_f32_16x16x32_bf16 v[40:43], v[186:189], v[210:213], v[40:43]
	v_mfma_f32_16x16x32_bf16 v[32:35], v[194:197], v[210:213], v[32:35]
	v_mfma_f32_16x16x32_bf16 v[24:27], v[186:189], v[218:221], v[24:27]
	v_mfma_f32_16x16x32_bf16 v[16:19], v[194:197], v[218:221], v[16:19]
	v_mfma_f32_16x16x32_bf16 v[8:11], v[186:189], v[226:229], v[8:11]
	v_mfma_f32_16x16x32_bf16 v[0:3], v[194:197], v[226:229], v[0:3]
	s_barrier
	s_add_i32 s19, 0, 0x18000
	v_add_u32_e32 v146, s19, v151
	s_add_i32 s22, 0, 0x1c000
	ds_read_b128 v[162:165], v146
	ds_read_b128 v[166:169], v146 offset:1024
	ds_read_b128 v[170:173], v146 offset:2048
	ds_read_b128 v[174:177], v146 offset:3072
	v_add_u32_e32 v146, s22, v151
	ds_read_b128 v[178:181], v146
	ds_read_b128 v[186:189], v146 offset:1024
	ds_read_b128 v[190:193], v146 offset:2048
	ds_read_b128 v[194:197], v146 offset:3072
	s_add_u32 s20, s88, 0x40000
	s_addc_u32 s21, s89, 0
	s_mov_b32 m0, s64
	ds_read_b128 v[198:201], v159 offset:32768
	ds_read_b128 v[202:205], v159 offset:33792
	ds_read_b128 v[206:209], v159 offset:34816
	ds_read_b128 v[210:213], v159 offset:35840
	ds_read_b128 v[214:217], v159 offset:36864
	ds_read_b128 v[218:221], v159 offset:37888
	ds_read_b128 v[222:225], v159 offset:38912
	ds_read_b128 v[226:229], v159 offset:39936
	global_load_lds_dwordx4 v134, s[20:21]
	s_mov_b32 m0, s65
	s_nop 0
	global_load_lds_dwordx4 v130, s[20:21]
	s_waitcnt vmcnt(8)
	s_waitcnt lgkmcnt(0)
	s_barrier
	s_waitcnt lgkmcnt(0)
	v_mfma_f32_16x16x32_bf16 v[124:127], v[162:165], v[198:201], v[124:127]
	v_mfma_f32_16x16x32_bf16 v[120:123], v[170:173], v[198:201], v[120:123]
	v_mfma_f32_16x16x32_bf16 v[108:111], v[162:165], v[206:209], v[108:111]
	v_mfma_f32_16x16x32_bf16 v[100:103], v[170:173], v[206:209], v[100:103]
	v_mfma_f32_16x16x32_bf16 v[92:95], v[162:165], v[214:217], v[92:95]
	v_mfma_f32_16x16x32_bf16 v[84:87], v[170:173], v[214:217], v[84:87]
	v_mfma_f32_16x16x32_bf16 v[76:79], v[162:165], v[222:225], v[76:79]
	v_mfma_f32_16x16x32_bf16 v[68:71], v[170:173], v[222:225], v[68:71]
	v_mfma_f32_16x16x32_bf16 v[124:127], v[166:169], v[202:205], v[124:127]
	v_mfma_f32_16x16x32_bf16 v[120:123], v[174:177], v[202:205], v[120:123]
	v_mfma_f32_16x16x32_bf16 v[108:111], v[166:169], v[210:213], v[108:111]
	v_mfma_f32_16x16x32_bf16 v[100:103], v[174:177], v[210:213], v[100:103]
	v_mfma_f32_16x16x32_bf16 v[92:95], v[166:169], v[218:221], v[92:95]
	v_mfma_f32_16x16x32_bf16 v[84:87], v[174:177], v[218:221], v[84:87]
	v_mfma_f32_16x16x32_bf16 v[76:79], v[166:169], v[226:229], v[76:79]
	v_mfma_f32_16x16x32_bf16 v[68:71], v[174:177], v[226:229], v[68:71]
	v_mfma_f32_16x16x32_bf16 v[116:119], v[178:181], v[198:201], v[116:119]
	v_mfma_f32_16x16x32_bf16 v[112:115], v[190:193], v[198:201], v[112:115]
	v_mfma_f32_16x16x32_bf16 v[104:107], v[178:181], v[206:209], v[104:107]
	v_mfma_f32_16x16x32_bf16 v[96:99], v[190:193], v[206:209], v[96:99]
	v_mfma_f32_16x16x32_bf16 v[88:91], v[178:181], v[214:217], v[88:91]
	v_mfma_f32_16x16x32_bf16 v[80:83], v[190:193], v[214:217], v[80:83]
	v_mfma_f32_16x16x32_bf16 v[72:75], v[178:181], v[222:225], v[72:75]
	v_mfma_f32_16x16x32_bf16 v[64:67], v[190:193], v[222:225], v[64:67]
	v_mfma_f32_16x16x32_bf16 v[116:119], v[186:189], v[202:205], v[116:119]
	v_mfma_f32_16x16x32_bf16 v[112:115], v[194:197], v[202:205], v[112:115]
	v_mfma_f32_16x16x32_bf16 v[104:107], v[186:189], v[210:213], v[104:107]
	v_mfma_f32_16x16x32_bf16 v[96:99], v[194:197], v[210:213], v[96:99]
	v_mfma_f32_16x16x32_bf16 v[88:91], v[186:189], v[218:221], v[88:91]
	v_mfma_f32_16x16x32_bf16 v[80:83], v[194:197], v[218:221], v[80:83]
	v_mfma_f32_16x16x32_bf16 v[72:75], v[186:189], v[226:229], v[72:75]
	v_mfma_f32_16x16x32_bf16 v[64:67], v[194:197], v[226:229], v[64:67]
	s_barrier
	s_add_i32 s19, s19, s3
	s_mov_b32 m0, s19
	ds_read_b128 v[198:201], v159 offset:49152
	ds_read_b128 v[202:205], v159 offset:50176
	ds_read_b128 v[206:209], v159 offset:51200
	ds_read_b128 v[210:213], v159 offset:52224
	ds_read_b128 v[214:217], v159 offset:53248
	ds_read_b128 v[218:221], v159 offset:54272
	ds_read_b128 v[222:225], v159 offset:55296
	ds_read_b128 v[226:229], v159 offset:56320
	global_load_lds_dwordx4 v132, s[98:99]
	s_add_i32 m0, s19, 0x2000
	s_add_u32 s20, s80, 0x40080
	s_addc_u32 s21, s81, 0
	s_add_i32 s19, s22, s3
	global_load_lds_dwordx4 v128, s[98:99]
	s_mov_b32 m0, s19
	s_nop 0
	global_load_lds_dwordx4 v132, s[20:21]
	s_add_i32 m0, s19, 0x2000
	s_nop 0
	global_load_lds_dwordx4 v128, s[20:21]
	s_mov_b32 m0, s67
	s_nop 0
	global_load_lds_dwordx4 v134, s[100:101]
	s_mov_b32 m0, s70
	s_nop 0
	global_load_lds_dwordx4 v130, s[100:101]
	s_waitcnt vmcnt(8)
	s_waitcnt lgkmcnt(0)
	s_barrier
	s_waitcnt lgkmcnt(0)
	v_mfma_f32_16x16x32_bf16 v[60:63], v[162:165], v[198:201], v[60:63]
	v_mfma_f32_16x16x32_bf16 v[52:55], v[170:173], v[198:201], v[52:55]
	v_mfma_f32_16x16x32_bf16 v[44:47], v[162:165], v[206:209], v[44:47]
	v_mfma_f32_16x16x32_bf16 v[36:39], v[170:173], v[206:209], v[36:39]
	v_mfma_f32_16x16x32_bf16 v[28:31], v[162:165], v[214:217], v[28:31]
	v_mfma_f32_16x16x32_bf16 v[20:23], v[170:173], v[214:217], v[20:23]
	v_mfma_f32_16x16x32_bf16 v[12:15], v[162:165], v[222:225], v[12:15]
	v_mfma_f32_16x16x32_bf16 v[4:7], v[170:173], v[222:225], v[4:7]
	v_mfma_f32_16x16x32_bf16 v[60:63], v[166:169], v[202:205], v[60:63]
	v_mfma_f32_16x16x32_bf16 v[52:55], v[174:177], v[202:205], v[52:55]
	v_mfma_f32_16x16x32_bf16 v[44:47], v[166:169], v[210:213], v[44:47]
	v_mfma_f32_16x16x32_bf16 v[36:39], v[174:177], v[210:213], v[36:39]
	v_mfma_f32_16x16x32_bf16 v[28:31], v[166:169], v[218:221], v[28:31]
	v_mfma_f32_16x16x32_bf16 v[20:23], v[174:177], v[218:221], v[20:23]
	v_mfma_f32_16x16x32_bf16 v[12:15], v[166:169], v[226:229], v[12:15]
	v_mfma_f32_16x16x32_bf16 v[4:7], v[174:177], v[226:229], v[4:7]
	v_mfma_f32_16x16x32_bf16 v[56:59], v[178:181], v[198:201], v[56:59]
	v_mfma_f32_16x16x32_bf16 v[48:51], v[190:193], v[198:201], v[48:51]
	v_mfma_f32_16x16x32_bf16 v[40:43], v[178:181], v[206:209], v[40:43]
	v_mfma_f32_16x16x32_bf16 v[32:35], v[190:193], v[206:209], v[32:35]
	v_mfma_f32_16x16x32_bf16 v[24:27], v[178:181], v[214:217], v[24:27]
	v_mfma_f32_16x16x32_bf16 v[16:19], v[190:193], v[214:217], v[16:19]
	v_mfma_f32_16x16x32_bf16 v[8:11], v[178:181], v[222:225], v[8:11]
	v_mfma_f32_16x16x32_bf16 v[0:3], v[190:193], v[222:225], v[0:3]
	v_mfma_f32_16x16x32_bf16 v[56:59], v[186:189], v[202:205], v[56:59]
	v_mfma_f32_16x16x32_bf16 v[48:51], v[194:197], v[202:205], v[48:51]
	v_mfma_f32_16x16x32_bf16 v[40:43], v[186:189], v[210:213], v[40:43]
	v_mfma_f32_16x16x32_bf16 v[32:35], v[194:197], v[210:213], v[32:35]
	v_mfma_f32_16x16x32_bf16 v[24:27], v[186:189], v[218:221], v[24:27]
	v_mfma_f32_16x16x32_bf16 v[16:19], v[194:197], v[218:221], v[16:19]
	v_mfma_f32_16x16x32_bf16 v[8:11], v[186:189], v[226:229], v[8:11]
	v_mfma_f32_16x16x32_bf16 v[0:3], v[194:197], v[226:229], v[0:3]
	s_barrier
	s_add_i32 s18, s18, 2
	s_add_u32 s40, s40, 0x100
	s_addc_u32 s41, s41, 0
	s_add_u32 s16, s16, 0x100
	s_addc_u32 s17, s17, 0
	s_cmp_gt_u32 s18, 13
	s_cbranch_scc0 .LBB0_111
.Lpeel_exit_111:
	s_and_b64 vcc, exec, s[30:31]
	s_cbranch_vccz .LBB0_114
	s_barrier

.LBB0_444:
	s_add_u32 s40, s40, 0xb0080
	s_addc_u32 s41, s41, 0
	s_add_u32 s39, s42, 0x100
	s_addc_u32 s61, s43, 0
	s_mov_b32 s62, -2
	s_waitcnt lgkmcnt(0)
	ds_read_b128 v[128:131], v213
	ds_read_b128 v[132:135], v213 offset:1024
	ds_read_b128 v[136:139], v213 offset:2048
	ds_read_b128 v[140:143], v213 offset:3072
	ds_read_b128 v[144:147], v214
	ds_read_b128 v[148:151], v214 offset:1024
	ds_read_b128 v[152:155], v214 offset:2048
	ds_read_b128 v[156:159], v214 offset:3072
	s_add_u32 s42, s40, 0xfff50080
	s_addc_u32 s43, s41, -1
	s_cmp_eq_u32 s62, 40
	s_cselect_b32 s81, s1, s43
	s_cselect_b32 s80, s0, s42
	s_cselect_b32 s43, s37, s61
	s_cselect_b32 s42, s36, s39
	s_add_i32 m0, s14, 0xc000
	ds_read_b128 v[160:163], v215
	ds_read_b128 v[164:167], v215 offset:1024
	ds_read_b128 v[168:171], v215 offset:2048
	ds_read_b128 v[172:175], v215 offset:3072
	ds_read_b128 v[198:201], v215 offset:4096
	ds_read_b128 v[202:205], v215 offset:5120
	ds_read_b128 v[206:209], v215 offset:6144
	ds_read_b128 v[218:221], v215 offset:7168
	global_load_lds_dwordx4 v190, s[40:41]
	s_add_i32 m0, s14, 0xe000
	s_nop 0
	global_load_lds_dwordx4 v192, s[40:41]
	s_waitcnt vmcnt(8)
	s_waitcnt lgkmcnt(0)
	s_barrier
	s_waitcnt lgkmcnt(0)
	v_mfma_f32_16x16x32_bf16 v[124:127], v[128:131], v[160:163], 0
	v_mfma_f32_16x16x32_bf16 v[120:123], v[136:139], v[160:163], 0
	v_mfma_f32_16x16x32_bf16 v[108:111], v[128:131], v[168:171], 0
	v_mfma_f32_16x16x32_bf16 v[104:107], v[136:139], v[168:171], 0
	v_mfma_f32_16x16x32_bf16 v[92:95], v[128:131], v[198:201], 0
	v_mfma_f32_16x16x32_bf16 v[88:91], v[136:139], v[198:201], 0
	v_mfma_f32_16x16x32_bf16 v[76:79], v[128:131], v[206:209], 0
	v_mfma_f32_16x16x32_bf16 v[72:75], v[136:139], v[206:209], 0
	v_mfma_f32_16x16x32_bf16 v[124:127], v[132:135], v[164:167], v[124:127]
	v_mfma_f32_16x16x32_bf16 v[120:123], v[140:143], v[164:167], v[120:123]
	v_mfma_f32_16x16x32_bf16 v[108:111], v[132:135], v[172:175], v[108:111]
	v_mfma_f32_16x16x32_bf16 v[104:107], v[140:143], v[172:175], v[104:107]
	v_mfma_f32_16x16x32_bf16 v[92:95], v[132:135], v[202:205], v[92:95]
	v_mfma_f32_16x16x32_bf16 v[88:91], v[140:143], v[202:205], v[88:91]
	v_mfma_f32_16x16x32_bf16 v[76:79], v[132:135], v[218:221], v[76:79]
	v_mfma_f32_16x16x32_bf16 v[72:75], v[140:143], v[218:221], v[72:75]
	v_mfma_f32_16x16x32_bf16 v[116:119], v[144:147], v[160:163], 0
	v_mfma_f32_16x16x32_bf16 v[112:115], v[152:155], v[160:163], 0
	v_mfma_f32_16x16x32_bf16 v[100:103], v[144:147], v[168:171], 0
	v_mfma_f32_16x16x32_bf16 v[96:99], v[152:155], v[168:171], 0
	v_mfma_f32_16x16x32_bf16 v[84:87], v[144:147], v[198:201], 0
	v_mfma_f32_16x16x32_bf16 v[80:83], v[152:155], v[198:201], 0
	v_mfma_f32_16x16x32_bf16 v[68:71], v[144:147], v[206:209], 0
	v_mfma_f32_16x16x32_bf16 v[64:67], v[152:155], v[206:209], 0
	v_mfma_f32_16x16x32_bf16 v[116:119], v[148:151], v[164:167], v[116:119]
	v_mfma_f32_16x16x32_bf16 v[112:115], v[156:159], v[164:167], v[112:115]
	v_mfma_f32_16x16x32_bf16 v[100:103], v[148:151], v[172:175], v[100:103]
	v_mfma_f32_16x16x32_bf16 v[96:99], v[156:159], v[172:175], v[96:99]
	v_mfma_f32_16x16x32_bf16 v[84:87], v[148:151], v[202:205], v[84:87]
	v_mfma_f32_16x16x32_bf16 v[80:83], v[156:159], v[202:205], v[80:83]
	v_mfma_f32_16x16x32_bf16 v[68:71], v[148:151], v[218:221], v[68:71]
	v_mfma_f32_16x16x32_bf16 v[64:67], v[156:159], v[218:221], v[64:67]
	s_barrier
	s_add_i32 s63, s24, s13
	s_mov_b32 m0, s63
	ds_read_b128 v[160:163], v215 offset:16384
	ds_read_b128 v[164:167], v215 offset:17408
	ds_read_b128 v[168:171], v215 offset:18432
	ds_read_b128 v[172:175], v215 offset:19456
	ds_read_b128 v[198:201], v215 offset:20480
	ds_read_b128 v[202:205], v215 offset:21504
	ds_read_b128 v[206:209], v215 offset:22528
	ds_read_b128 v[218:221], v215 offset:23552
	global_load_lds_dwordx4 v178, s[42:43]
	s_add_i32 m0, s63, 0x2000
	s_add_u32 s64, s42, 0xb0000
	s_addc_u32 s65, s43, 0
	s_add_i32 s63, s25, s13
	global_load_lds_dwordx4 v182, s[42:43]
	s_mov_b32 m0, s63
	global_load_lds_dwordx4 v178, s[64:65]
	s_add_i32 m0, s63, 0x2000
	s_nop 0
	global_load_lds_dwordx4 v182, s[64:65]
	s_mov_b32 m0, s14
	s_nop 0
	global_load_lds_dwordx4 v176, s[80:81]
	s_mov_b32 m0, s15
	s_nop 0
	global_load_lds_dwordx4 v180, s[80:81]
	s_add_u32 s98, s42, s30
	s_addc_u32 s99, s43, s31
	s_add_u32 s100, s80, s30
	s_addc_u32 s101, s81, s31
	s_waitcnt vmcnt(8)
	s_waitcnt lgkmcnt(0)
	s_barrier
	s_waitcnt lgkmcnt(0)
	v_mfma_f32_16x16x32_bf16 v[60:63], v[128:131], v[160:163], 0
	v_mfma_f32_16x16x32_bf16 v[56:59], v[136:139], v[160:163], 0
	v_mfma_f32_16x16x32_bf16 v[44:47], v[128:131], v[168:171], 0
	v_mfma_f32_16x16x32_bf16 v[40:43], v[136:139], v[168:171], 0
	v_mfma_f32_16x16x32_bf16 v[28:31], v[128:131], v[198:201], 0
	v_mfma_f32_16x16x32_bf16 v[24:27], v[136:139], v[198:201], 0
	v_mfma_f32_16x16x32_bf16 v[12:15], v[128:131], v[206:209], 0
	v_mfma_f32_16x16x32_bf16 v[8:11], v[136:139], v[206:209], 0
	v_mfma_f32_16x16x32_bf16 v[60:63], v[132:135], v[164:167], v[60:63]
	v_mfma_f32_16x16x32_bf16 v[56:59], v[140:143], v[164:167], v[56:59]
	v_mfma_f32_16x16x32_bf16 v[44:47], v[132:135], v[172:175], v[44:47]
	v_mfma_f32_16x16x32_bf16 v[40:43], v[140:143], v[172:175], v[40:43]
	v_mfma_f32_16x16x32_bf16 v[28:31], v[132:135], v[202:205], v[28:31]
	v_mfma_f32_16x16x32_bf16 v[24:27], v[140:143], v[202:205], v[24:27]
	v_mfma_f32_16x16x32_bf16 v[12:15], v[132:135], v[218:221], v[12:15]
	v_mfma_f32_16x16x32_bf16 v[8:11], v[140:143], v[218:221], v[8:11]
	v_mfma_f32_16x16x32_bf16 v[52:55], v[144:147], v[160:163], 0
	v_mfma_f32_16x16x32_bf16 v[48:51], v[152:155], v[160:163], 0
	v_mfma_f32_16x16x32_bf16 v[36:39], v[144:147], v[168:171], 0
	v_mfma_f32_16x16x32_bf16 v[32:35], v[152:155], v[168:171], 0
	v_mfma_f32_16x16x32_bf16 v[20:23], v[144:147], v[198:201], 0
	v_mfma_f32_16x16x32_bf16 v[16:19], v[152:155], v[198:201], 0
	v_mfma_f32_16x16x32_bf16 v[4:7], v[144:147], v[206:209], 0
	v_mfma_f32_16x16x32_bf16 v[0:3], v[152:155], v[206:209], 0
	v_mfma_f32_16x16x32_bf16 v[52:55], v[148:151], v[164:167], v[52:55]
	v_mfma_f32_16x16x32_bf16 v[48:51], v[156:159], v[164:167], v[48:51]
	v_mfma_f32_16x16x32_bf16 v[36:39], v[148:151], v[172:175], v[36:39]
	v_mfma_f32_16x16x32_bf16 v[32:35], v[156:159], v[172:175], v[32:35]
	v_mfma_f32_16x16x32_bf16 v[20:23], v[148:151], v[202:205], v[20:23]
	v_mfma_f32_16x16x32_bf16 v[16:19], v[156:159], v[202:205], v[16:19]
	v_mfma_f32_16x16x32_bf16 v[4:7], v[148:151], v[218:221], v[4:7]
	v_mfma_f32_16x16x32_bf16 v[0:3], v[156:159], v[218:221], v[0:3]
	s_barrier
	s_add_i32 s63, 0, 0x18000
	s_add_i32 s66, 0, 0x1c000
	v_add_u32_e32 v140, s63, v210
	v_add_u32_e32 v156, s66, v210
	ds_read_b128 v[128:131], v140
	ds_read_b128 v[132:135], v140 offset:1024
	ds_read_b128 v[136:139], v140 offset:2048
	ds_read_b128 v[140:143], v140 offset:3072
	ds_read_b128 v[144:147], v156
	ds_read_b128 v[148:151], v156 offset:1024
	ds_read_b128 v[152:155], v156 offset:2048
	ds_read_b128 v[156:159], v156 offset:3072
	s_add_u32 s64, s80, 0xb0000
	s_addc_u32 s65, s81, 0
	s_mov_b32 m0, s16
	ds_read_b128 v[160:163], v215 offset:32768
	ds_read_b128 v[164:167], v215 offset:33792
	ds_read_b128 v[168:171], v215 offset:34816
	ds_read_b128 v[172:175], v215 offset:35840
	ds_read_b128 v[198:201], v215 offset:36864
	ds_read_b128 v[202:205], v215 offset:37888
	ds_read_b128 v[206:209], v215 offset:38912
	ds_read_b128 v[218:221], v215 offset:39936
	global_load_lds_dwordx4 v176, s[64:65]
	s_mov_b32 m0, s17
	s_nop 0
	global_load_lds_dwordx4 v180, s[64:65]
	s_waitcnt vmcnt(8)
	s_waitcnt lgkmcnt(0)
	s_barrier
	s_waitcnt lgkmcnt(0)
	v_mfma_f32_16x16x32_bf16 v[124:127], v[128:131], v[160:163], v[124:127]
	v_mfma_f32_16x16x32_bf16 v[120:123], v[136:139], v[160:163], v[120:123]
	v_mfma_f32_16x16x32_bf16 v[108:111], v[128:131], v[168:171], v[108:111]
	v_mfma_f32_16x16x32_bf16 v[104:107], v[136:139], v[168:171], v[104:107]
	v_mfma_f32_16x16x32_bf16 v[92:95], v[128:131], v[198:201], v[92:95]
	v_mfma_f32_16x16x32_bf16 v[88:91], v[136:139], v[198:201], v[88:91]
	v_mfma_f32_16x16x32_bf16 v[76:79], v[128:131], v[206:209], v[76:79]
	v_mfma_f32_16x16x32_bf16 v[72:75], v[136:139], v[206:209], v[72:75]
	v_mfma_f32_16x16x32_bf16 v[124:127], v[132:135], v[164:167], v[124:127]
	v_mfma_f32_16x16x32_bf16 v[120:123], v[140:143], v[164:167], v[120:123]
	v_mfma_f32_16x16x32_bf16 v[108:111], v[132:135], v[172:175], v[108:111]
	v_mfma_f32_16x16x32_bf16 v[104:107], v[140:143], v[172:175], v[104:107]
	v_mfma_f32_16x16x32_bf16 v[92:95], v[132:135], v[202:205], v[92:95]
	v_mfma_f32_16x16x32_bf16 v[88:91], v[140:143], v[202:205], v[88:91]
	v_mfma_f32_16x16x32_bf16 v[76:79], v[132:135], v[218:221], v[76:79]
	v_mfma_f32_16x16x32_bf16 v[72:75], v[140:143], v[218:221], v[72:75]
	v_mfma_f32_16x16x32_bf16 v[116:119], v[144:147], v[160:163], v[116:119]
	v_mfma_f32_16x16x32_bf16 v[112:115], v[152:155], v[160:163], v[112:115]
	v_mfma_f32_16x16x32_bf16 v[100:103], v[144:147], v[168:171], v[100:103]
	v_mfma_f32_16x16x32_bf16 v[96:99], v[152:155], v[168:171], v[96:99]
	v_mfma_f32_16x16x32_bf16 v[84:87], v[144:147], v[198:201], v[84:87]
	v_mfma_f32_16x16x32_bf16 v[80:83], v[152:155], v[198:201], v[80:83]
	v_mfma_f32_16x16x32_bf16 v[68:71], v[144:147], v[206:209], v[68:71]
	v_mfma_f32_16x16x32_bf16 v[64:67], v[152:155], v[206:209], v[64:67]
	v_mfma_f32_16x16x32_bf16 v[116:119], v[148:151], v[164:167], v[116:119]
	v_mfma_f32_16x16x32_bf16 v[112:115], v[156:159], v[164:167], v[112:115]
	v_mfma_f32_16x16x32_bf16 v[100:103], v[148:151], v[172:175], v[100:103]
	v_mfma_f32_16x16x32_bf16 v[96:99], v[156:159], v[172:175], v[96:99]
	v_mfma_f32_16x16x32_bf16 v[84:87], v[148:151], v[202:205], v[84:87]
	v_mfma_f32_16x16x32_bf16 v[80:83], v[156:159], v[202:205], v[80:83]
	v_mfma_f32_16x16x32_bf16 v[68:71], v[148:151], v[218:221], v[68:71]
	v_mfma_f32_16x16x32_bf16 v[64:67], v[156:159], v[218:221], v[64:67]
	s_barrier
	s_add_i32 s63, s63, s13
	s_mov_b32 m0, s63
	ds_read_b128 v[160:163], v215 offset:49152
	ds_read_b128 v[164:167], v215 offset:50176
	ds_read_b128 v[168:171], v215 offset:51200
	ds_read_b128 v[172:175], v215 offset:52224
	ds_read_b128 v[198:201], v215 offset:53248
	ds_read_b128 v[202:205], v215 offset:54272
	ds_read_b128 v[206:209], v215 offset:55296
	ds_read_b128 v[218:221], v215 offset:56320
	global_load_lds_dwordx4 v178, s[98:99]
	s_add_i32 m0, s63, 0x2000
	s_add_u32 s42, s42, 0xb0080
	s_addc_u32 s43, s43, 0
	s_add_i32 s63, s66, s13
	global_load_lds_dwordx4 v182, s[98:99]
	s_mov_b32 m0, s63
	s_nop 0
	global_load_lds_dwordx4 v178, s[42:43]
	s_add_i32 m0, s63, 0x2000
	s_nop 0
	global_load_lds_dwordx4 v182, s[42:43]
	s_mov_b32 m0, s19
	s_nop 0
	global_load_lds_dwordx4 v176, s[100:101]
	s_mov_b32 m0, s20
	s_nop 0
	global_load_lds_dwordx4 v180, s[100:101]
	s_waitcnt vmcnt(8)
	s_waitcnt lgkmcnt(0)
	s_barrier
	s_waitcnt lgkmcnt(0)
	v_mfma_f32_16x16x32_bf16 v[60:63], v[128:131], v[160:163], v[60:63]
	v_mfma_f32_16x16x32_bf16 v[56:59], v[136:139], v[160:163], v[56:59]
	v_mfma_f32_16x16x32_bf16 v[44:47], v[128:131], v[168:171], v[44:47]
	v_mfma_f32_16x16x32_bf16 v[40:43], v[136:139], v[168:171], v[40:43]
	v_mfma_f32_16x16x32_bf16 v[28:31], v[128:131], v[198:201], v[28:31]
	v_mfma_f32_16x16x32_bf16 v[24:27], v[136:139], v[198:201], v[24:27]
	v_mfma_f32_16x16x32_bf16 v[12:15], v[128:131], v[206:209], v[12:15]
	v_mfma_f32_16x16x32_bf16 v[8:11], v[136:139], v[206:209], v[8:11]
	v_mfma_f32_16x16x32_bf16 v[60:63], v[132:135], v[164:167], v[60:63]
	v_mfma_f32_16x16x32_bf16 v[56:59], v[140:143], v[164:167], v[56:59]
	v_mfma_f32_16x16x32_bf16 v[44:47], v[132:135], v[172:175], v[44:47]
	v_mfma_f32_16x16x32_bf16 v[40:43], v[140:143], v[172:175], v[40:43]
	v_mfma_f32_16x16x32_bf16 v[28:31], v[132:135], v[202:205], v[28:31]
	v_mfma_f32_16x16x32_bf16 v[24:27], v[140:143], v[202:205], v[24:27]
	v_mfma_f32_16x16x32_bf16 v[12:15], v[132:135], v[218:221], v[12:15]
	v_mfma_f32_16x16x32_bf16 v[8:11], v[140:143], v[218:221], v[8:11]
	v_mfma_f32_16x16x32_bf16 v[52:55], v[144:147], v[160:163], v[52:55]
	v_mfma_f32_16x16x32_bf16 v[48:51], v[152:155], v[160:163], v[48:51]
	v_mfma_f32_16x16x32_bf16 v[36:39], v[144:147], v[168:171], v[36:39]
	v_mfma_f32_16x16x32_bf16 v[32:35], v[152:155], v[168:171], v[32:35]
	v_mfma_f32_16x16x32_bf16 v[20:23], v[144:147], v[198:201], v[20:23]
	v_mfma_f32_16x16x32_bf16 v[16:19], v[152:155], v[198:201], v[16:19]
	v_mfma_f32_16x16x32_bf16 v[4:7], v[144:147], v[206:209], v[4:7]
	v_mfma_f32_16x16x32_bf16 v[0:3], v[152:155], v[206:209], v[0:3]
	v_mfma_f32_16x16x32_bf16 v[52:55], v[148:151], v[164:167], v[52:55]
	v_mfma_f32_16x16x32_bf16 v[48:51], v[156:159], v[164:167], v[48:51]
	v_mfma_f32_16x16x32_bf16 v[36:39], v[148:151], v[172:175], v[36:39]
	v_mfma_f32_16x16x32_bf16 v[32:35], v[156:159], v[172:175], v[32:35]
	v_mfma_f32_16x16x32_bf16 v[20:23], v[148:151], v[202:205], v[20:23]
	v_mfma_f32_16x16x32_bf16 v[16:19], v[156:159], v[202:205], v[16:19]
	v_mfma_f32_16x16x32_bf16 v[4:7], v[148:151], v[218:221], v[4:7]
	v_mfma_f32_16x16x32_bf16 v[0:3], v[156:159], v[218:221], v[0:3]
	s_barrier
	s_add_i32 s62, s62, 2
	s_add_u32 s40, s40, 0x100
	s_addc_u32 s41, s41, 0
	s_add_u32 s39, s39, 0x100
	s_addc_u32 s61, s61, 0
	s_cmp_gt_u32 s62, 41
	s_cbranch_scc1 .Lpeel_exit_445

.Lpeel_exit_445:
	s_and_b64 vcc, exec, s[34:35]
	s_cbranch_vccz .LBB0_448
	s_barrier

.LBB0_545:
	s_ashr_i32 s35, s34, 31
	s_lshl_b64 s[8:9], s[34:35], 19
	s_add_u32 s38, s82, s8
	s_addc_u32 s39, s83, s9
	s_and_b64 s[8:9], s[4:5], exec
	s_cselect_b32 s8, s39, s7
	s_cselect_b32 s9, s38, s6
	s_ashr_i32 s37, s36, 31
	s_lshl_b64 s[14:15], s[36:37], 19
	s_add_u32 s86, s60, s14
	s_addc_u32 s87, s61, s15
	s_and_b64 s[14:15], s[4:5], exec
	s_cselect_b32 s14, s87, s43
	s_cselect_b32 s15, s86, s42
	s_add_u32 s6, s6, 0x40080
	s_addc_u32 s7, s7, 0
	s_add_u32 s16, s42, 0x100
	s_addc_u32 s17, s43, 0
	s_mov_b32 s18, -2
	ds_read_b128 v[144:147], v155
	ds_read_b128 v[148:151], v155 offset:1024
	ds_read_b128 v[160:163], v155 offset:2048
	ds_read_b128 v[164:167], v155 offset:3072
	ds_read_b128 v[168:171], v156
	ds_read_b128 v[172:175], v156 offset:1024
	ds_read_b128 v[176:179], v156 offset:2048
	ds_read_b128 v[180:183], v156 offset:3072
	s_add_u32 s19, s6, 0xfffc0080
	s_addc_u32 s20, s7, -1
	s_cmp_eq_u32 s18, 12
	s_cselect_b32 s89, s8, s20
	s_cselect_b32 s88, s9, s19
	s_cselect_b32 s43, s14, s17
	s_cselect_b32 s42, s15, s16
	s_add_i32 m0, s63, 0xc000
	ds_read_b128 v[186:189], v157
	ds_read_b128 v[190:193], v157 offset:1024
	ds_read_b128 v[194:197], v157 offset:2048
	ds_read_b128 v[198:201], v157 offset:3072
	ds_read_b128 v[202:205], v157 offset:4096
	ds_read_b128 v[206:209], v157 offset:5120
	ds_read_b128 v[210:213], v157 offset:6144
	ds_read_b128 v[214:217], v157 offset:7168
	global_load_lds_dwordx4 v136, s[6:7]
	s_add_i32 m0, s63, 0xe000
	s_nop 0
	global_load_lds_dwordx4 v138, s[6:7]
	s_waitcnt vmcnt(8)
	s_waitcnt lgkmcnt(0)
	s_barrier
	s_waitcnt lgkmcnt(0)
	v_mfma_f32_16x16x32_bf16 v[124:127], v[144:147], v[186:189], 0
	v_mfma_f32_16x16x32_bf16 v[120:123], v[160:163], v[186:189], 0
	v_mfma_f32_16x16x32_bf16 v[108:111], v[144:147], v[194:197], 0
	v_mfma_f32_16x16x32_bf16 v[104:107], v[160:163], v[194:197], 0
	v_mfma_f32_16x16x32_bf16 v[92:95], v[144:147], v[202:205], 0
	v_mfma_f32_16x16x32_bf16 v[88:91], v[160:163], v[202:205], 0
	v_mfma_f32_16x16x32_bf16 v[76:79], v[144:147], v[210:213], 0
	v_mfma_f32_16x16x32_bf16 v[72:75], v[160:163], v[210:213], 0
	v_mfma_f32_16x16x32_bf16 v[124:127], v[148:151], v[190:193], v[124:127]
	v_mfma_f32_16x16x32_bf16 v[120:123], v[164:167], v[190:193], v[120:123]
	v_mfma_f32_16x16x32_bf16 v[108:111], v[148:151], v[198:201], v[108:111]
	v_mfma_f32_16x16x32_bf16 v[104:107], v[164:167], v[198:201], v[104:107]
	v_mfma_f32_16x16x32_bf16 v[92:95], v[148:151], v[206:209], v[92:95]
	v_mfma_f32_16x16x32_bf16 v[88:91], v[164:167], v[206:209], v[88:91]
	v_mfma_f32_16x16x32_bf16 v[76:79], v[148:151], v[214:217], v[76:79]
	v_mfma_f32_16x16x32_bf16 v[72:75], v[164:167], v[214:217], v[72:75]
	v_mfma_f32_16x16x32_bf16 v[116:119], v[168:171], v[186:189], 0
	v_mfma_f32_16x16x32_bf16 v[112:115], v[176:179], v[186:189], 0
	v_mfma_f32_16x16x32_bf16 v[100:103], v[168:171], v[194:197], 0
	v_mfma_f32_16x16x32_bf16 v[96:99], v[176:179], v[194:197], 0
	v_mfma_f32_16x16x32_bf16 v[84:87], v[168:171], v[202:205], 0
	v_mfma_f32_16x16x32_bf16 v[80:83], v[176:179], v[202:205], 0
	v_mfma_f32_16x16x32_bf16 v[68:71], v[168:171], v[210:213], 0
	v_mfma_f32_16x16x32_bf16 v[64:67], v[176:179], v[210:213], 0
	v_mfma_f32_16x16x32_bf16 v[116:119], v[172:175], v[190:193], v[116:119]
	v_mfma_f32_16x16x32_bf16 v[112:115], v[180:183], v[190:193], v[112:115]
	v_mfma_f32_16x16x32_bf16 v[100:103], v[172:175], v[198:201], v[100:103]
	v_mfma_f32_16x16x32_bf16 v[96:99], v[180:183], v[198:201], v[96:99]
	v_mfma_f32_16x16x32_bf16 v[84:87], v[172:175], v[206:209], v[84:87]
	v_mfma_f32_16x16x32_bf16 v[80:83], v[180:183], v[206:209], v[80:83]
	v_mfma_f32_16x16x32_bf16 v[68:71], v[172:175], v[214:217], v[68:71]
	v_mfma_f32_16x16x32_bf16 v[64:67], v[180:183], v[214:217], v[64:67]
	s_barrier
	s_add_i32 s19, s72, s62
	s_mov_b32 m0, s19
	ds_read_b128 v[186:189], v157 offset:16384
	ds_read_b128 v[190:193], v157 offset:17408
	ds_read_b128 v[194:197], v157 offset:18432
	ds_read_b128 v[198:201], v157 offset:19456
	ds_read_b128 v[202:205], v157 offset:20480
	ds_read_b128 v[206:209], v157 offset:21504
	ds_read_b128 v[210:213], v157 offset:22528
	ds_read_b128 v[214:217], v157 offset:23552
	global_load_lds_dwordx4 v130, s[42:43]
	s_add_i32 m0, s19, 0x2000
	s_add_u32 s20, s42, 0x40000
	s_addc_u32 s21, s43, 0
	s_add_i32 s19, s73, s62
	global_load_lds_dwordx4 v134, s[42:43]
	s_mov_b32 m0, s19
	global_load_lds_dwordx4 v130, s[20:21]
	s_add_i32 m0, s19, 0x2000
	s_nop 0
	global_load_lds_dwordx4 v134, s[20:21]
	s_mov_b32 m0, s63
	s_nop 0
	global_load_lds_dwordx4 v128, s[88:89]
	s_mov_b32 m0, s64
	s_nop 0
	global_load_lds_dwordx4 v132, s[88:89]
	s_add_u32 s98, s42, s28
	s_addc_u32 s99, s43, s29
	s_add_u32 s100, s88, s28
	s_addc_u32 s101, s89, s29
	s_waitcnt vmcnt(8)
	s_waitcnt lgkmcnt(0)
	s_barrier
	s_waitcnt lgkmcnt(0)
	v_mfma_f32_16x16x32_bf16 v[60:63], v[144:147], v[186:189], 0
	v_mfma_f32_16x16x32_bf16 v[56:59], v[160:163], v[186:189], 0
	v_mfma_f32_16x16x32_bf16 v[44:47], v[144:147], v[194:197], 0
	v_mfma_f32_16x16x32_bf16 v[40:43], v[160:163], v[194:197], 0
	v_mfma_f32_16x16x32_bf16 v[28:31], v[144:147], v[202:205], 0
	v_mfma_f32_16x16x32_bf16 v[24:27], v[160:163], v[202:205], 0
	v_mfma_f32_16x16x32_bf16 v[12:15], v[144:147], v[210:213], 0
	v_mfma_f32_16x16x32_bf16 v[8:11], v[160:163], v[210:213], 0
	v_mfma_f32_16x16x32_bf16 v[60:63], v[148:151], v[190:193], v[60:63]
	v_mfma_f32_16x16x32_bf16 v[56:59], v[164:167], v[190:193], v[56:59]
	v_mfma_f32_16x16x32_bf16 v[44:47], v[148:151], v[198:201], v[44:47]
	v_mfma_f32_16x16x32_bf16 v[40:43], v[164:167], v[198:201], v[40:43]
	v_mfma_f32_16x16x32_bf16 v[28:31], v[148:151], v[206:209], v[28:31]
	v_mfma_f32_16x16x32_bf16 v[24:27], v[164:167], v[206:209], v[24:27]
	v_mfma_f32_16x16x32_bf16 v[12:15], v[148:151], v[214:217], v[12:15]
	v_mfma_f32_16x16x32_bf16 v[8:11], v[164:167], v[214:217], v[8:11]
	v_mfma_f32_16x16x32_bf16 v[52:55], v[168:171], v[186:189], 0
	v_mfma_f32_16x16x32_bf16 v[48:51], v[176:179], v[186:189], 0
	v_mfma_f32_16x16x32_bf16 v[36:39], v[168:171], v[194:197], 0
	v_mfma_f32_16x16x32_bf16 v[32:35], v[176:179], v[194:197], 0
	v_mfma_f32_16x16x32_bf16 v[20:23], v[168:171], v[202:205], 0
	v_mfma_f32_16x16x32_bf16 v[16:19], v[176:179], v[202:205], 0
	v_mfma_f32_16x16x32_bf16 v[4:7], v[168:171], v[210:213], 0
	v_mfma_f32_16x16x32_bf16 v[0:3], v[176:179], v[210:213], 0
	v_mfma_f32_16x16x32_bf16 v[52:55], v[172:175], v[190:193], v[52:55]
	v_mfma_f32_16x16x32_bf16 v[48:51], v[180:183], v[190:193], v[48:51]
	v_mfma_f32_16x16x32_bf16 v[36:39], v[172:175], v[198:201], v[36:39]
	v_mfma_f32_16x16x32_bf16 v[32:35], v[180:183], v[198:201], v[32:35]
	v_mfma_f32_16x16x32_bf16 v[20:23], v[172:175], v[206:209], v[20:23]
	v_mfma_f32_16x16x32_bf16 v[16:19], v[180:183], v[206:209], v[16:19]
	v_mfma_f32_16x16x32_bf16 v[4:7], v[172:175], v[214:217], v[4:7]
	v_mfma_f32_16x16x32_bf16 v[0:3], v[180:183], v[214:217], v[0:3]
	s_barrier
	s_add_i32 s19, 0, 0x18000
	v_add_u32_e32 v159, s19, v153
	s_add_i32 s22, 0, 0x1c000
	ds_read_b128 v[144:147], v159
	ds_read_b128 v[148:151], v159 offset:1024
	ds_read_b128 v[160:163], v159 offset:2048
	ds_read_b128 v[164:167], v159 offset:3072
	v_add_u32_e32 v159, s22, v153
	ds_read_b128 v[168:171], v159
	ds_read_b128 v[172:175], v159 offset:1024
	ds_read_b128 v[176:179], v159 offset:2048
	ds_read_b128 v[180:183], v159 offset:3072
	s_add_u32 s20, s88, 0x40000
	s_addc_u32 s21, s89, 0
	s_mov_b32 m0, s65
	ds_read_b128 v[186:189], v157 offset:32768
	ds_read_b128 v[190:193], v157 offset:33792
	ds_read_b128 v[194:197], v157 offset:34816
	ds_read_b128 v[198:201], v157 offset:35840
	ds_read_b128 v[202:205], v157 offset:36864
	ds_read_b128 v[206:209], v157 offset:37888
	ds_read_b128 v[210:213], v157 offset:38912
	ds_read_b128 v[214:217], v157 offset:39936
	global_load_lds_dwordx4 v128, s[20:21]
	s_mov_b32 m0, s66
	s_nop 0
	global_load_lds_dwordx4 v132, s[20:21]
	s_waitcnt vmcnt(8)
	s_waitcnt lgkmcnt(0)
	s_barrier
	s_waitcnt lgkmcnt(0)
	v_mfma_f32_16x16x32_bf16 v[124:127], v[144:147], v[186:189], v[124:127]
	v_mfma_f32_16x16x32_bf16 v[120:123], v[160:163], v[186:189], v[120:123]
	v_mfma_f32_16x16x32_bf16 v[108:111], v[144:147], v[194:197], v[108:111]
	v_mfma_f32_16x16x32_bf16 v[104:107], v[160:163], v[194:197], v[104:107]
	v_mfma_f32_16x16x32_bf16 v[92:95], v[144:147], v[202:205], v[92:95]
	v_mfma_f32_16x16x32_bf16 v[88:91], v[160:163], v[202:205], v[88:91]
	v_mfma_f32_16x16x32_bf16 v[76:79], v[144:147], v[210:213], v[76:79]
	v_mfma_f32_16x16x32_bf16 v[72:75], v[160:163], v[210:213], v[72:75]
	v_mfma_f32_16x16x32_bf16 v[124:127], v[148:151], v[190:193], v[124:127]
	v_mfma_f32_16x16x32_bf16 v[120:123], v[164:167], v[190:193], v[120:123]
	v_mfma_f32_16x16x32_bf16 v[108:111], v[148:151], v[198:201], v[108:111]
	v_mfma_f32_16x16x32_bf16 v[104:107], v[164:167], v[198:201], v[104:107]
	v_mfma_f32_16x16x32_bf16 v[92:95], v[148:151], v[206:209], v[92:95]
	v_mfma_f32_16x16x32_bf16 v[88:91], v[164:167], v[206:209], v[88:91]
	v_mfma_f32_16x16x32_bf16 v[76:79], v[148:151], v[214:217], v[76:79]
	v_mfma_f32_16x16x32_bf16 v[72:75], v[164:167], v[214:217], v[72:75]
	v_mfma_f32_16x16x32_bf16 v[116:119], v[168:171], v[186:189], v[116:119]
	v_mfma_f32_16x16x32_bf16 v[112:115], v[176:179], v[186:189], v[112:115]
	v_mfma_f32_16x16x32_bf16 v[100:103], v[168:171], v[194:197], v[100:103]
	v_mfma_f32_16x16x32_bf16 v[96:99], v[176:179], v[194:197], v[96:99]
	v_mfma_f32_16x16x32_bf16 v[84:87], v[168:171], v[202:205], v[84:87]
	v_mfma_f32_16x16x32_bf16 v[80:83], v[176:179], v[202:205], v[80:83]
	v_mfma_f32_16x16x32_bf16 v[68:71], v[168:171], v[210:213], v[68:71]
	v_mfma_f32_16x16x32_bf16 v[64:67], v[176:179], v[210:213], v[64:67]
	v_mfma_f32_16x16x32_bf16 v[116:119], v[172:175], v[190:193], v[116:119]
	v_mfma_f32_16x16x32_bf16 v[112:115], v[180:183], v[190:193], v[112:115]
	v_mfma_f32_16x16x32_bf16 v[100:103], v[172:175], v[198:201], v[100:103]
	v_mfma_f32_16x16x32_bf16 v[96:99], v[180:183], v[198:201], v[96:99]
	v_mfma_f32_16x16x32_bf16 v[84:87], v[172:175], v[206:209], v[84:87]
	v_mfma_f32_16x16x32_bf16 v[80:83], v[180:183], v[206:209], v[80:83]
	v_mfma_f32_16x16x32_bf16 v[68:71], v[172:175], v[214:217], v[68:71]
	v_mfma_f32_16x16x32_bf16 v[64:67], v[180:183], v[214:217], v[64:67]
	s_barrier
	s_add_i32 s19, s19, s62
	s_mov_b32 m0, s19
	ds_read_b128 v[186:189], v157 offset:49152
	ds_read_b128 v[190:193], v157 offset:50176
	ds_read_b128 v[194:197], v157 offset:51200
	ds_read_b128 v[198:201], v157 offset:52224
	ds_read_b128 v[202:205], v157 offset:53248
	ds_read_b128 v[206:209], v157 offset:54272
	ds_read_b128 v[210:213], v157 offset:55296
	ds_read_b128 v[214:217], v157 offset:56320
	global_load_lds_dwordx4 v130, s[98:99]
	s_add_i32 m0, s19, 0x2000
	s_add_u32 s20, s42, 0x40080
	s_addc_u32 s21, s43, 0
	s_add_i32 s19, s22, s62
	global_load_lds_dwordx4 v134, s[98:99]
	s_mov_b32 m0, s19
	s_nop 0
	global_load_lds_dwordx4 v130, s[20:21]
	s_add_i32 m0, s19, 0x2000
	s_nop 0
	global_load_lds_dwordx4 v134, s[20:21]
	s_mov_b32 m0, s70
	s_nop 0
	global_load_lds_dwordx4 v128, s[100:101]
	s_mov_b32 m0, s71
	s_nop 0
	global_load_lds_dwordx4 v132, s[100:101]
	s_waitcnt vmcnt(8)
	s_waitcnt lgkmcnt(0)
	s_barrier
	s_waitcnt lgkmcnt(0)
	v_mfma_f32_16x16x32_bf16 v[60:63], v[144:147], v[186:189], v[60:63]
	v_mfma_f32_16x16x32_bf16 v[56:59], v[160:163], v[186:189], v[56:59]
	v_mfma_f32_16x16x32_bf16 v[44:47], v[144:147], v[194:197], v[44:47]
	v_mfma_f32_16x16x32_bf16 v[40:43], v[160:163], v[194:197], v[40:43]
	v_mfma_f32_16x16x32_bf16 v[28:31], v[144:147], v[202:205], v[28:31]
	v_mfma_f32_16x16x32_bf16 v[24:27], v[160:163], v[202:205], v[24:27]
	v_mfma_f32_16x16x32_bf16 v[12:15], v[144:147], v[210:213], v[12:15]
	v_mfma_f32_16x16x32_bf16 v[8:11], v[160:163], v[210:213], v[8:11]
	v_mfma_f32_16x16x32_bf16 v[60:63], v[148:151], v[190:193], v[60:63]
	v_mfma_f32_16x16x32_bf16 v[56:59], v[164:167], v[190:193], v[56:59]
	v_mfma_f32_16x16x32_bf16 v[44:47], v[148:151], v[198:201], v[44:47]
	v_mfma_f32_16x16x32_bf16 v[40:43], v[164:167], v[198:201], v[40:43]
	v_mfma_f32_16x16x32_bf16 v[28:31], v[148:151], v[206:209], v[28:31]
	v_mfma_f32_16x16x32_bf16 v[24:27], v[164:167], v[206:209], v[24:27]
	v_mfma_f32_16x16x32_bf16 v[12:15], v[148:151], v[214:217], v[12:15]
	v_mfma_f32_16x16x32_bf16 v[8:11], v[164:167], v[214:217], v[8:11]
	v_mfma_f32_16x16x32_bf16 v[52:55], v[168:171], v[186:189], v[52:55]
	v_mfma_f32_16x16x32_bf16 v[48:51], v[176:179], v[186:189], v[48:51]
	v_mfma_f32_16x16x32_bf16 v[36:39], v[168:171], v[194:197], v[36:39]
	v_mfma_f32_16x16x32_bf16 v[32:35], v[176:179], v[194:197], v[32:35]
	v_mfma_f32_16x16x32_bf16 v[20:23], v[168:171], v[202:205], v[20:23]
	v_mfma_f32_16x16x32_bf16 v[16:19], v[176:179], v[202:205], v[16:19]
	v_mfma_f32_16x16x32_bf16 v[4:7], v[168:171], v[210:213], v[4:7]
	v_mfma_f32_16x16x32_bf16 v[0:3], v[176:179], v[210:213], v[0:3]
	v_mfma_f32_16x16x32_bf16 v[52:55], v[172:175], v[190:193], v[52:55]
	v_mfma_f32_16x16x32_bf16 v[48:51], v[180:183], v[190:193], v[48:51]
	v_mfma_f32_16x16x32_bf16 v[36:39], v[172:175], v[198:201], v[36:39]
	v_mfma_f32_16x16x32_bf16 v[32:35], v[180:183], v[198:201], v[32:35]
	v_mfma_f32_16x16x32_bf16 v[20:23], v[172:175], v[206:209], v[20:23]
	v_mfma_f32_16x16x32_bf16 v[16:19], v[180:183], v[206:209], v[16:19]
	v_mfma_f32_16x16x32_bf16 v[4:7], v[172:175], v[214:217], v[4:7]
	v_mfma_f32_16x16x32_bf16 v[0:3], v[180:183], v[214:217], v[0:3]
	s_barrier
	s_add_i32 s18, s18, 2
	s_add_u32 s6, s6, 0x100
	s_addc_u32 s7, s7, 0
	s_add_u32 s16, s16, 0x100
	s_addc_u32 s17, s17, 0
	s_cmp_gt_u32 s18, 13
	s_cbranch_scc1 .Lpeel_exit_546
.LBB0_546:
	ds_read_b128 v[144:147], v155
	ds_read_b128 v[148:151], v155 offset:1024
	ds_read_b128 v[160:163], v155 offset:2048
	ds_read_b128 v[164:167], v155 offset:3072
	ds_read_b128 v[168:171], v156
	ds_read_b128 v[172:175], v156 offset:1024
	ds_read_b128 v[176:179], v156 offset:2048
	ds_read_b128 v[180:183], v156 offset:3072
	s_add_u32 s19, s6, 0xfffc0080
	s_addc_u32 s20, s7, -1
	s_cmp_eq_u32 s18, 12
	s_cselect_b32 s89, s8, s20
	s_cselect_b32 s88, s9, s19
	s_cselect_b32 s43, s14, s17
	s_cselect_b32 s42, s15, s16
	s_add_i32 m0, s63, 0xc000
	ds_read_b128 v[186:189], v157
	ds_read_b128 v[190:193], v157 offset:1024
	ds_read_b128 v[194:197], v157 offset:2048
	ds_read_b128 v[198:201], v157 offset:3072
	ds_read_b128 v[202:205], v157 offset:4096
	ds_read_b128 v[206:209], v157 offset:5120
	ds_read_b128 v[210:213], v157 offset:6144
	ds_read_b128 v[214:217], v157 offset:7168
	global_load_lds_dwordx4 v136, s[6:7]
	s_add_i32 m0, s63, 0xe000
	s_nop 0
	global_load_lds_dwordx4 v138, s[6:7]
	s_waitcnt vmcnt(8)
	s_waitcnt lgkmcnt(0)
	s_barrier
	s_waitcnt lgkmcnt(0)
	v_mfma_f32_16x16x32_bf16 v[124:127], v[144:147], v[186:189], v[124:127]
	v_mfma_f32_16x16x32_bf16 v[120:123], v[160:163], v[186:189], v[120:123]
	v_mfma_f32_16x16x32_bf16 v[108:111], v[144:147], v[194:197], v[108:111]
	v_mfma_f32_16x16x32_bf16 v[104:107], v[160:163], v[194:197], v[104:107]
	v_mfma_f32_16x16x32_bf16 v[92:95], v[144:147], v[202:205], v[92:95]
	v_mfma_f32_16x16x32_bf16 v[88:91], v[160:163], v[202:205], v[88:91]
	v_mfma_f32_16x16x32_bf16 v[76:79], v[144:147], v[210:213], v[76:79]
	v_mfma_f32_16x16x32_bf16 v[72:75], v[160:163], v[210:213], v[72:75]
	v_mfma_f32_16x16x32_bf16 v[124:127], v[148:151], v[190:193], v[124:127]
	v_mfma_f32_16x16x32_bf16 v[120:123], v[164:167], v[190:193], v[120:123]
	v_mfma_f32_16x16x32_bf16 v[108:111], v[148:151], v[198:201], v[108:111]
	v_mfma_f32_16x16x32_bf16 v[104:107], v[164:167], v[198:201], v[104:107]
	v_mfma_f32_16x16x32_bf16 v[92:95], v[148:151], v[206:209], v[92:95]
	v_mfma_f32_16x16x32_bf16 v[88:91], v[164:167], v[206:209], v[88:91]
	v_mfma_f32_16x16x32_bf16 v[76:79], v[148:151], v[214:217], v[76:79]
	v_mfma_f32_16x16x32_bf16 v[72:75], v[164:167], v[214:217], v[72:75]
	v_mfma_f32_16x16x32_bf16 v[116:119], v[168:171], v[186:189], v[116:119]
	v_mfma_f32_16x16x32_bf16 v[112:115], v[176:179], v[186:189], v[112:115]
	v_mfma_f32_16x16x32_bf16 v[100:103], v[168:171], v[194:197], v[100:103]
	v_mfma_f32_16x16x32_bf16 v[96:99], v[176:179], v[194:197], v[96:99]
	v_mfma_f32_16x16x32_bf16 v[84:87], v[168:171], v[202:205], v[84:87]
	v_mfma_f32_16x16x32_bf16 v[80:83], v[176:179], v[202:205], v[80:83]
	v_mfma_f32_16x16x32_bf16 v[68:71], v[168:171], v[210:213], v[68:71]
	v_mfma_f32_16x16x32_bf16 v[64:67], v[176:179], v[210:213], v[64:67]
	v_mfma_f32_16x16x32_bf16 v[116:119], v[172:175], v[190:193], v[116:119]
	v_mfma_f32_16x16x32_bf16 v[112:115], v[180:183], v[190:193], v[112:115]
	v_mfma_f32_16x16x32_bf16 v[100:103], v[172:175], v[198:201], v[100:103]
	v_mfma_f32_16x16x32_bf16 v[96:99], v[180:183], v[198:201], v[96:99]
	v_mfma_f32_16x16x32_bf16 v[84:87], v[172:175], v[206:209], v[84:87]
	v_mfma_f32_16x16x32_bf16 v[80:83], v[180:183], v[206:209], v[80:83]
	v_mfma_f32_16x16x32_bf16 v[68:71], v[172:175], v[214:217], v[68:71]
	v_mfma_f32_16x16x32_bf16 v[64:67], v[180:183], v[214:217], v[64:67]
	s_barrier
	s_add_i32 s19, s72, s62
	s_mov_b32 m0, s19
	ds_read_b128 v[186:189], v157 offset:16384
	ds_read_b128 v[190:193], v157 offset:17408
	ds_read_b128 v[194:197], v157 offset:18432
	ds_read_b128 v[198:201], v157 offset:19456
	ds_read_b128 v[202:205], v157 offset:20480
	ds_read_b128 v[206:209], v157 offset:21504
	ds_read_b128 v[210:213], v157 offset:22528
	ds_read_b128 v[214:217], v157 offset:23552
	global_load_lds_dwordx4 v130, s[42:43]
	s_add_i32 m0, s19, 0x2000
	s_add_u32 s20, s42, 0x40000
	s_addc_u32 s21, s43, 0
	s_add_i32 s19, s73, s62
	global_load_lds_dwordx4 v134, s[42:43]
	s_mov_b32 m0, s19
	global_load_lds_dwordx4 v130, s[20:21]
	s_add_i32 m0, s19, 0x2000
	s_nop 0
	global_load_lds_dwordx4 v134, s[20:21]
	s_mov_b32 m0, s63
	s_nop 0
	global_load_lds_dwordx4 v128, s[88:89]
	s_mov_b32 m0, s64
	s_nop 0
	global_load_lds_dwordx4 v132, s[88:89]
	s_add_u32 s98, s42, s28
	s_addc_u32 s99, s43, s29
	s_add_u32 s100, s88, s28
	s_addc_u32 s101, s89, s29
	s_waitcnt vmcnt(8)
	s_waitcnt lgkmcnt(0)
	s_barrier
	s_waitcnt lgkmcnt(0)
	v_mfma_f32_16x16x32_bf16 v[60:63], v[144:147], v[186:189], v[60:63]
	v_mfma_f32_16x16x32_bf16 v[56:59], v[160:163], v[186:189], v[56:59]
	v_mfma_f32_16x16x32_bf16 v[44:47], v[144:147], v[194:197], v[44:47]
	v_mfma_f32_16x16x32_bf16 v[40:43], v[160:163], v[194:197], v[40:43]
	v_mfma_f32_16x16x32_bf16 v[28:31], v[144:147], v[202:205], v[28:31]
	v_mfma_f32_16x16x32_bf16 v[24:27], v[160:163], v[202:205], v[24:27]
	v_mfma_f32_16x16x32_bf16 v[12:15], v[144:147], v[210:213], v[12:15]
	v_mfma_f32_16x16x32_bf16 v[8:11], v[160:163], v[210:213], v[8:11]
	v_mfma_f32_16x16x32_bf16 v[60:63], v[148:151], v[190:193], v[60:63]
	v_mfma_f32_16x16x32_bf16 v[56:59], v[164:167], v[190:193], v[56:59]
	v_mfma_f32_16x16x32_bf16 v[44:47], v[148:151], v[198:201], v[44:47]
	v_mfma_f32_16x16x32_bf16 v[40:43], v[164:167], v[198:201], v[40:43]
	v_mfma_f32_16x16x32_bf16 v[28:31], v[148:151], v[206:209], v[28:31]
	v_mfma_f32_16x16x32_bf16 v[24:27], v[164:167], v[206:209], v[24:27]
	v_mfma_f32_16x16x32_bf16 v[12:15], v[148:151], v[214:217], v[12:15]
	v_mfma_f32_16x16x32_bf16 v[8:11], v[164:167], v[214:217], v[8:11]
	v_mfma_f32_16x16x32_bf16 v[52:55], v[168:171], v[186:189], v[52:55]
	v_mfma_f32_16x16x32_bf16 v[48:51], v[176:179], v[186:189], v[48:51]
	v_mfma_f32_16x16x32_bf16 v[36:39], v[168:171], v[194:197], v[36:39]
	v_mfma_f32_16x16x32_bf16 v[32:35], v[176:179], v[194:197], v[32:35]
	v_mfma_f32_16x16x32_bf16 v[20:23], v[168:171], v[202:205], v[20:23]
	v_mfma_f32_16x16x32_bf16 v[16:19], v[176:179], v[202:205], v[16:19]
	v_mfma_f32_16x16x32_bf16 v[4:7], v[168:171], v[210:213], v[4:7]
	v_mfma_f32_16x16x32_bf16 v[0:3], v[176:179], v[210:213], v[0:3]
	v_mfma_f32_16x16x32_bf16 v[52:55], v[172:175], v[190:193], v[52:55]
	v_mfma_f32_16x16x32_bf16 v[48:51], v[180:183], v[190:193], v[48:51]
	v_mfma_f32_16x16x32_bf16 v[36:39], v[172:175], v[198:201], v[36:39]
	v_mfma_f32_16x16x32_bf16 v[32:35], v[180:183], v[198:201], v[32:35]
	v_mfma_f32_16x16x32_bf16 v[20:23], v[172:175], v[206:209], v[20:23]
	v_mfma_f32_16x16x32_bf16 v[16:19], v[180:183], v[206:209], v[16:19]
	v_mfma_f32_16x16x32_bf16 v[4:7], v[172:175], v[214:217], v[4:7]
	v_mfma_f32_16x16x32_bf16 v[0:3], v[180:183], v[214:217], v[0:3]
	s_barrier
	s_add_i32 s19, 0, 0x18000
	v_add_u32_e32 v159, s19, v153
	s_add_i32 s22, 0, 0x1c000
	ds_read_b128 v[144:147], v159
	ds_read_b128 v[148:151], v159 offset:1024
	ds_read_b128 v[160:163], v159 offset:2048
	ds_read_b128 v[164:167], v159 offset:3072
	v_add_u32_e32 v159, s22, v153
	ds_read_b128 v[168:171], v159
	ds_read_b128 v[172:175], v159 offset:1024
	ds_read_b128 v[176:179], v159 offset:2048
	ds_read_b128 v[180:183], v159 offset:3072
	s_add_u32 s20, s88, 0x40000
	s_addc_u32 s21, s89, 0
	s_mov_b32 m0, s65
	ds_read_b128 v[186:189], v157 offset:32768
	ds_read_b128 v[190:193], v157 offset:33792
	ds_read_b128 v[194:197], v157 offset:34816
	ds_read_b128 v[198:201], v157 offset:35840
	ds_read_b128 v[202:205], v157 offset:36864
	ds_read_b128 v[206:209], v157 offset:37888
	ds_read_b128 v[210:213], v157 offset:38912
	ds_read_b128 v[214:217], v157 offset:39936
	global_load_lds_dwordx4 v128, s[20:21]
	s_mov_b32 m0, s66
	s_nop 0
	global_load_lds_dwordx4 v132, s[20:21]
	s_waitcnt vmcnt(8)
	s_waitcnt lgkmcnt(0)
	s_barrier
	s_waitcnt lgkmcnt(0)
	v_mfma_f32_16x16x32_bf16 v[124:127], v[144:147], v[186:189], v[124:127]
	v_mfma_f32_16x16x32_bf16 v[120:123], v[160:163], v[186:189], v[120:123]
	v_mfma_f32_16x16x32_bf16 v[108:111], v[144:147], v[194:197], v[108:111]
	v_mfma_f32_16x16x32_bf16 v[104:107], v[160:163], v[194:197], v[104:107]
	v_mfma_f32_16x16x32_bf16 v[92:95], v[144:147], v[202:205], v[92:95]
	v_mfma_f32_16x16x32_bf16 v[88:91], v[160:163], v[202:205], v[88:91]
	v_mfma_f32_16x16x32_bf16 v[76:79], v[144:147], v[210:213], v[76:79]
	v_mfma_f32_16x16x32_bf16 v[72:75], v[160:163], v[210:213], v[72:75]
	v_mfma_f32_16x16x32_bf16 v[124:127], v[148:151], v[190:193], v[124:127]
	v_mfma_f32_16x16x32_bf16 v[120:123], v[164:167], v[190:193], v[120:123]
	v_mfma_f32_16x16x32_bf16 v[108:111], v[148:151], v[198:201], v[108:111]
	v_mfma_f32_16x16x32_bf16 v[104:107], v[164:167], v[198:201], v[104:107]
	v_mfma_f32_16x16x32_bf16 v[92:95], v[148:151], v[206:209], v[92:95]
	v_mfma_f32_16x16x32_bf16 v[88:91], v[164:167], v[206:209], v[88:91]
	v_mfma_f32_16x16x32_bf16 v[76:79], v[148:151], v[214:217], v[76:79]
	v_mfma_f32_16x16x32_bf16 v[72:75], v[164:167], v[214:217], v[72:75]
	v_mfma_f32_16x16x32_bf16 v[116:119], v[168:171], v[186:189], v[116:119]
	v_mfma_f32_16x16x32_bf16 v[112:115], v[176:179], v[186:189], v[112:115]
	v_mfma_f32_16x16x32_bf16 v[100:103], v[168:171], v[194:197], v[100:103]
	v_mfma_f32_16x16x32_bf16 v[96:99], v[176:179], v[194:197], v[96:99]
	v_mfma_f32_16x16x32_bf16 v[84:87], v[168:171], v[202:205], v[84:87]
	v_mfma_f32_16x16x32_bf16 v[80:83], v[176:179], v[202:205], v[80:83]
	v_mfma_f32_16x16x32_bf16 v[68:71], v[168:171], v[210:213], v[68:71]
	v_mfma_f32_16x16x32_bf16 v[64:67], v[176:179], v[210:213], v[64:67]
	v_mfma_f32_16x16x32_bf16 v[116:119], v[172:175], v[190:193], v[116:119]
	v_mfma_f32_16x16x32_bf16 v[112:115], v[180:183], v[190:193], v[112:115]
	v_mfma_f32_16x16x32_bf16 v[100:103], v[172:175], v[198:201], v[100:103]
	v_mfma_f32_16x16x32_bf16 v[96:99], v[180:183], v[198:201], v[96:99]
	v_mfma_f32_16x16x32_bf16 v[84:87], v[172:175], v[206:209], v[84:87]
	v_mfma_f32_16x16x32_bf16 v[80:83], v[180:183], v[206:209], v[80:83]
	v_mfma_f32_16x16x32_bf16 v[68:71], v[172:175], v[214:217], v[68:71]
	v_mfma_f32_16x16x32_bf16 v[64:67], v[180:183], v[214:217], v[64:67]
	s_barrier
	s_add_i32 s19, s19, s62
	s_mov_b32 m0, s19
	ds_read_b128 v[186:189], v157 offset:49152
	ds_read_b128 v[190:193], v157 offset:50176
	ds_read_b128 v[194:197], v157 offset:51200
	ds_read_b128 v[198:201], v157 offset:52224
	ds_read_b128 v[202:205], v157 offset:53248
	ds_read_b128 v[206:209], v157 offset:54272
	ds_read_b128 v[210:213], v157 offset:55296
	ds_read_b128 v[214:217], v157 offset:56320
	global_load_lds_dwordx4 v130, s[98:99]
	s_add_i32 m0, s19, 0x2000
	s_add_u32 s20, s42, 0x40080
	s_addc_u32 s21, s43, 0
	s_add_i32 s19, s22, s62
	global_load_lds_dwordx4 v134, s[98:99]
	s_mov_b32 m0, s19
	s_nop 0
	global_load_lds_dwordx4 v130, s[20:21]
	s_add_i32 m0, s19, 0x2000
	s_nop 0
	global_load_lds_dwordx4 v134, s[20:21]
	s_mov_b32 m0, s70
	s_nop 0
	global_load_lds_dwordx4 v128, s[100:101]
	s_mov_b32 m0, s71
	s_nop 0
	global_load_lds_dwordx4 v132, s[100:101]
	s_waitcnt vmcnt(8)
	s_waitcnt lgkmcnt(0)
	s_barrier
	s_waitcnt lgkmcnt(0)
	v_mfma_f32_16x16x32_bf16 v[60:63], v[144:147], v[186:189], v[60:63]
	v_mfma_f32_16x16x32_bf16 v[56:59], v[160:163], v[186:189], v[56:59]
	v_mfma_f32_16x16x32_bf16 v[44:47], v[144:147], v[194:197], v[44:47]
	v_mfma_f32_16x16x32_bf16 v[40:43], v[160:163], v[194:197], v[40:43]
	v_mfma_f32_16x16x32_bf16 v[28:31], v[144:147], v[202:205], v[28:31]
	v_mfma_f32_16x16x32_bf16 v[24:27], v[160:163], v[202:205], v[24:27]
	v_mfma_f32_16x16x32_bf16 v[12:15], v[144:147], v[210:213], v[12:15]
	v_mfma_f32_16x16x32_bf16 v[8:11], v[160:163], v[210:213], v[8:11]
	v_mfma_f32_16x16x32_bf16 v[60:63], v[148:151], v[190:193], v[60:63]
	v_mfma_f32_16x16x32_bf16 v[56:59], v[164:167], v[190:193], v[56:59]
	v_mfma_f32_16x16x32_bf16 v[44:47], v[148:151], v[198:201], v[44:47]
	v_mfma_f32_16x16x32_bf16 v[40:43], v[164:167], v[198:201], v[40:43]
	v_mfma_f32_16x16x32_bf16 v[28:31], v[148:151], v[206:209], v[28:31]
	v_mfma_f32_16x16x32_bf16 v[24:27], v[164:167], v[206:209], v[24:27]
	v_mfma_f32_16x16x32_bf16 v[12:15], v[148:151], v[214:217], v[12:15]
	v_mfma_f32_16x16x32_bf16 v[8:11], v[164:167], v[214:217], v[8:11]
	v_mfma_f32_16x16x32_bf16 v[52:55], v[168:171], v[186:189], v[52:55]
	v_mfma_f32_16x16x32_bf16 v[48:51], v[176:179], v[186:189], v[48:51]
	v_mfma_f32_16x16x32_bf16 v[36:39], v[168:171], v[194:197], v[36:39]
	v_mfma_f32_16x16x32_bf16 v[32:35], v[176:179], v[194:197], v[32:35]
	v_mfma_f32_16x16x32_bf16 v[20:23], v[168:171], v[202:205], v[20:23]
	v_mfma_f32_16x16x32_bf16 v[16:19], v[176:179], v[202:205], v[16:19]
	v_mfma_f32_16x16x32_bf16 v[4:7], v[168:171], v[210:213], v[4:7]
	v_mfma_f32_16x16x32_bf16 v[0:3], v[176:179], v[210:213], v[0:3]
	v_mfma_f32_16x16x32_bf16 v[52:55], v[172:175], v[190:193], v[52:55]
	v_mfma_f32_16x16x32_bf16 v[48:51], v[180:183], v[190:193], v[48:51]
	v_mfma_f32_16x16x32_bf16 v[36:39], v[172:175], v[198:201], v[36:39]
	v_mfma_f32_16x16x32_bf16 v[32:35], v[180:183], v[198:201], v[32:35]
	v_mfma_f32_16x16x32_bf16 v[20:23], v[172:175], v[206:209], v[20:23]
	v_mfma_f32_16x16x32_bf16 v[16:19], v[180:183], v[206:209], v[16:19]
	v_mfma_f32_16x16x32_bf16 v[4:7], v[172:175], v[214:217], v[4:7]
	v_mfma_f32_16x16x32_bf16 v[0:3], v[180:183], v[214:217], v[0:3]
	s_barrier
	s_add_i32 s18, s18, 2
	s_add_u32 s6, s6, 0x100
	s_addc_u32 s7, s7, 0
	s_add_u32 s16, s16, 0x100
	s_addc_u32 s17, s17, 0
	s_cmp_gt_u32 s18, 13
	s_cbranch_scc0 .LBB0_546

.LBB0_1025:
	s_ashr_i32 s27, s26, 31
	s_lshl_b64 s[30:31], s[26:27], 19
	s_add_u32 s30, s3, s30
	s_addc_u32 s31, s14, s31
	s_and_b64 s[34:35], s[8:9], exec
	s_cselect_b32 s27, s31, s41
	s_cselect_b32 s37, s30, s40
	s_ashr_i32 s29, s28, 31
	s_lshl_b64 s[34:35], s[28:29], 19
	s_add_u32 s34, s15, s34
	s_addc_u32 s35, s16, s35
	s_and_b64 s[62:63], s[8:9], exec
	s_cselect_b32 s29, s35, s43
	s_cselect_b32 s39, s34, s42
	s_add_u32 s40, s40, 0x40080
	s_addc_u32 s41, s41, 0
	s_add_u32 s70, s42, 0x100
	s_addc_u32 s71, s43, 0
	s_mov_b32 s72, -2
	s_waitcnt lgkmcnt(0)
	ds_read_b128 v[128:131], v189
	ds_read_b128 v[132:135], v189 offset:1024
	ds_read_b128 v[136:139], v189 offset:2048
	ds_read_b128 v[140:143], v189 offset:3072
	ds_read_b128 v[144:147], v190
	ds_read_b128 v[148:151], v190 offset:1024
	ds_read_b128 v[172:175], v190 offset:2048
	ds_read_b128 v[176:179], v190 offset:3072
	s_add_u32 s42, s40, 0xfffc0080
	s_addc_u32 s43, s41, -1
	s_cmp_eq_u32 s72, 12
	s_cselect_b32 s63, s27, s43
	s_cselect_b32 s62, s37, s42
	s_cselect_b32 s43, s29, s71
	s_cselect_b32 s42, s39, s70
	s_add_i32 m0, s18, 0xc000
	ds_read_b128 v[180:183], v191
	ds_read_b128 v[194:197], v191 offset:1024
	ds_read_b128 v[198:201], v191 offset:2048
	ds_read_b128 v[202:205], v191 offset:3072
	ds_read_b128 v[206:209], v191 offset:4096
	ds_read_b128 v[210:213], v191 offset:5120
	ds_read_b128 v[214:217], v191 offset:6144
	ds_read_b128 v[218:221], v191 offset:7168
	global_load_lds_dwordx4 v164, s[40:41]
	s_add_i32 m0, s18, 0xe000
	s_nop 0
	global_load_lds_dwordx4 v166, s[40:41]
	s_waitcnt vmcnt(8)
	s_waitcnt lgkmcnt(0)
	s_barrier
	s_waitcnt lgkmcnt(0)
	v_mfma_f32_16x16x32_bf16 v[124:127], v[128:131], v[180:183], 0
	v_mfma_f32_16x16x32_bf16 v[120:123], v[136:139], v[180:183], 0
	v_mfma_f32_16x16x32_bf16 v[108:111], v[128:131], v[198:201], 0
	v_mfma_f32_16x16x32_bf16 v[104:107], v[136:139], v[198:201], 0
	v_mfma_f32_16x16x32_bf16 v[92:95], v[128:131], v[206:209], 0
	v_mfma_f32_16x16x32_bf16 v[88:91], v[136:139], v[206:209], 0
	v_mfma_f32_16x16x32_bf16 v[76:79], v[128:131], v[214:217], 0
	v_mfma_f32_16x16x32_bf16 v[72:75], v[136:139], v[214:217], 0
	v_mfma_f32_16x16x32_bf16 v[124:127], v[132:135], v[194:197], v[124:127]
	v_mfma_f32_16x16x32_bf16 v[120:123], v[140:143], v[194:197], v[120:123]
	v_mfma_f32_16x16x32_bf16 v[108:111], v[132:135], v[202:205], v[108:111]
	v_mfma_f32_16x16x32_bf16 v[104:107], v[140:143], v[202:205], v[104:107]
	v_mfma_f32_16x16x32_bf16 v[92:95], v[132:135], v[210:213], v[92:95]
	v_mfma_f32_16x16x32_bf16 v[88:91], v[140:143], v[210:213], v[88:91]
	v_mfma_f32_16x16x32_bf16 v[76:79], v[132:135], v[218:221], v[76:79]
	v_mfma_f32_16x16x32_bf16 v[72:75], v[140:143], v[218:221], v[72:75]
	v_mfma_f32_16x16x32_bf16 v[116:119], v[144:147], v[180:183], 0
	v_mfma_f32_16x16x32_bf16 v[112:115], v[172:175], v[180:183], 0
	v_mfma_f32_16x16x32_bf16 v[100:103], v[144:147], v[198:201], 0
	v_mfma_f32_16x16x32_bf16 v[96:99], v[172:175], v[198:201], 0
	v_mfma_f32_16x16x32_bf16 v[84:87], v[144:147], v[206:209], 0
	v_mfma_f32_16x16x32_bf16 v[80:83], v[172:175], v[206:209], 0
	v_mfma_f32_16x16x32_bf16 v[68:71], v[144:147], v[214:217], 0
	v_mfma_f32_16x16x32_bf16 v[64:67], v[172:175], v[214:217], 0
	v_mfma_f32_16x16x32_bf16 v[116:119], v[148:151], v[194:197], v[116:119]
	v_mfma_f32_16x16x32_bf16 v[112:115], v[176:179], v[194:197], v[112:115]
	v_mfma_f32_16x16x32_bf16 v[100:103], v[148:151], v[202:205], v[100:103]
	v_mfma_f32_16x16x32_bf16 v[96:99], v[176:179], v[202:205], v[96:99]
	v_mfma_f32_16x16x32_bf16 v[84:87], v[148:151], v[210:213], v[84:87]
	v_mfma_f32_16x16x32_bf16 v[80:83], v[176:179], v[210:213], v[80:83]
	v_mfma_f32_16x16x32_bf16 v[68:71], v[148:151], v[218:221], v[68:71]
	v_mfma_f32_16x16x32_bf16 v[64:67], v[176:179], v[218:221], v[64:67]
	s_barrier
	s_add_i32 s73, s66, s17
	s_mov_b32 m0, s73
	ds_read_b128 v[180:183], v191 offset:16384
	ds_read_b128 v[194:197], v191 offset:17408
	ds_read_b128 v[198:201], v191 offset:18432
	ds_read_b128 v[202:205], v191 offset:19456
	ds_read_b128 v[206:209], v191 offset:20480
	ds_read_b128 v[210:213], v191 offset:21504
	ds_read_b128 v[214:217], v191 offset:22528
	ds_read_b128 v[218:221], v191 offset:23552
	global_load_lds_dwordx4 v154, s[42:43]
	s_add_i32 m0, s73, 0x2000
	s_add_u32 s74, s42, 0x40000
	s_addc_u32 s75, s43, 0
	s_add_i32 s73, s67, s17
	global_load_lds_dwordx4 v158, s[42:43]
	s_mov_b32 m0, s73
	global_load_lds_dwordx4 v154, s[74:75]
	s_add_i32 m0, s73, 0x2000
	s_nop 0
	global_load_lds_dwordx4 v158, s[74:75]
	s_mov_b32 m0, s18
	s_nop 0
	global_load_lds_dwordx4 v152, s[62:63]
	s_mov_b32 m0, s19
	s_nop 0
	global_load_lds_dwordx4 v156, s[62:63]
	s_add_u32 s98, s42, s12
	s_addc_u32 s99, s43, s13
	s_add_u32 s100, s62, s12
	s_addc_u32 s101, s63, s13
	s_waitcnt vmcnt(8)
	s_waitcnt lgkmcnt(0)
	s_barrier
	s_waitcnt lgkmcnt(0)
	v_mfma_f32_16x16x32_bf16 v[60:63], v[128:131], v[180:183], 0
	v_mfma_f32_16x16x32_bf16 v[56:59], v[136:139], v[180:183], 0
	v_mfma_f32_16x16x32_bf16 v[44:47], v[128:131], v[198:201], 0
	v_mfma_f32_16x16x32_bf16 v[40:43], v[136:139], v[198:201], 0
	v_mfma_f32_16x16x32_bf16 v[28:31], v[128:131], v[206:209], 0
	v_mfma_f32_16x16x32_bf16 v[24:27], v[136:139], v[206:209], 0
	v_mfma_f32_16x16x32_bf16 v[12:15], v[128:131], v[214:217], 0
	v_mfma_f32_16x16x32_bf16 v[8:11], v[136:139], v[214:217], 0
	v_mfma_f32_16x16x32_bf16 v[60:63], v[132:135], v[194:197], v[60:63]
	v_mfma_f32_16x16x32_bf16 v[56:59], v[140:143], v[194:197], v[56:59]
	v_mfma_f32_16x16x32_bf16 v[44:47], v[132:135], v[202:205], v[44:47]
	v_mfma_f32_16x16x32_bf16 v[40:43], v[140:143], v[202:205], v[40:43]
	v_mfma_f32_16x16x32_bf16 v[28:31], v[132:135], v[210:213], v[28:31]
	v_mfma_f32_16x16x32_bf16 v[24:27], v[140:143], v[210:213], v[24:27]
	v_mfma_f32_16x16x32_bf16 v[12:15], v[132:135], v[218:221], v[12:15]
	v_mfma_f32_16x16x32_bf16 v[8:11], v[140:143], v[218:221], v[8:11]
	v_mfma_f32_16x16x32_bf16 v[52:55], v[144:147], v[180:183], 0
	v_mfma_f32_16x16x32_bf16 v[48:51], v[172:175], v[180:183], 0
	v_mfma_f32_16x16x32_bf16 v[36:39], v[144:147], v[198:201], 0
	v_mfma_f32_16x16x32_bf16 v[32:35], v[172:175], v[198:201], 0
	v_mfma_f32_16x16x32_bf16 v[20:23], v[144:147], v[206:209], 0
	v_mfma_f32_16x16x32_bf16 v[16:19], v[172:175], v[206:209], 0
	v_mfma_f32_16x16x32_bf16 v[4:7], v[144:147], v[214:217], 0
	v_mfma_f32_16x16x32_bf16 v[0:3], v[172:175], v[214:217], 0
	v_mfma_f32_16x16x32_bf16 v[52:55], v[148:151], v[194:197], v[52:55]
	v_mfma_f32_16x16x32_bf16 v[48:51], v[176:179], v[194:197], v[48:51]
	v_mfma_f32_16x16x32_bf16 v[36:39], v[148:151], v[202:205], v[36:39]
	v_mfma_f32_16x16x32_bf16 v[32:35], v[176:179], v[202:205], v[32:35]
	v_mfma_f32_16x16x32_bf16 v[20:23], v[148:151], v[210:213], v[20:23]
	v_mfma_f32_16x16x32_bf16 v[16:19], v[176:179], v[210:213], v[16:19]
	v_mfma_f32_16x16x32_bf16 v[4:7], v[148:151], v[218:221], v[4:7]
	v_mfma_f32_16x16x32_bf16 v[0:3], v[176:179], v[218:221], v[0:3]
	s_barrier
	s_add_i32 s73, 0, 0x18000
	s_add_i32 s74, 0, 0x1c000
	v_add_u32_e32 v140, s73, v186
	v_add_u32_e32 v176, s74, v186
	ds_read_b128 v[128:131], v140
	ds_read_b128 v[132:135], v140 offset:1024
	ds_read_b128 v[136:139], v140 offset:2048
	ds_read_b128 v[140:143], v140 offset:3072
	ds_read_b128 v[144:147], v176
	ds_read_b128 v[148:151], v176 offset:1024
	ds_read_b128 v[172:175], v176 offset:2048
	ds_read_b128 v[176:179], v176 offset:3072
	s_add_u32 s62, s62, 0x40000
	s_addc_u32 s63, s63, 0
	s_mov_b32 m0, s20
	ds_read_b128 v[180:183], v191 offset:32768
	ds_read_b128 v[194:197], v191 offset:33792
	ds_read_b128 v[198:201], v191 offset:34816
	ds_read_b128 v[202:205], v191 offset:35840
	ds_read_b128 v[206:209], v191 offset:36864
	ds_read_b128 v[210:213], v191 offset:37888
	ds_read_b128 v[214:217], v191 offset:38912
	ds_read_b128 v[218:221], v191 offset:39936
	global_load_lds_dwordx4 v152, s[62:63]
	s_mov_b32 m0, s21
	s_nop 0
	global_load_lds_dwordx4 v156, s[62:63]
	s_waitcnt vmcnt(8)
	s_waitcnt lgkmcnt(0)
	s_barrier
	s_waitcnt lgkmcnt(0)
	v_mfma_f32_16x16x32_bf16 v[124:127], v[128:131], v[180:183], v[124:127]
	v_mfma_f32_16x16x32_bf16 v[120:123], v[136:139], v[180:183], v[120:123]
	v_mfma_f32_16x16x32_bf16 v[108:111], v[128:131], v[198:201], v[108:111]
	v_mfma_f32_16x16x32_bf16 v[104:107], v[136:139], v[198:201], v[104:107]
	v_mfma_f32_16x16x32_bf16 v[92:95], v[128:131], v[206:209], v[92:95]
	v_mfma_f32_16x16x32_bf16 v[88:91], v[136:139], v[206:209], v[88:91]
	v_mfma_f32_16x16x32_bf16 v[76:79], v[128:131], v[214:217], v[76:79]
	v_mfma_f32_16x16x32_bf16 v[72:75], v[136:139], v[214:217], v[72:75]
	v_mfma_f32_16x16x32_bf16 v[124:127], v[132:135], v[194:197], v[124:127]
	v_mfma_f32_16x16x32_bf16 v[120:123], v[140:143], v[194:197], v[120:123]
	v_mfma_f32_16x16x32_bf16 v[108:111], v[132:135], v[202:205], v[108:111]
	v_mfma_f32_16x16x32_bf16 v[104:107], v[140:143], v[202:205], v[104:107]
	v_mfma_f32_16x16x32_bf16 v[92:95], v[132:135], v[210:213], v[92:95]
	v_mfma_f32_16x16x32_bf16 v[88:91], v[140:143], v[210:213], v[88:91]
	v_mfma_f32_16x16x32_bf16 v[76:79], v[132:135], v[218:221], v[76:79]
	v_mfma_f32_16x16x32_bf16 v[72:75], v[140:143], v[218:221], v[72:75]
	v_mfma_f32_16x16x32_bf16 v[116:119], v[144:147], v[180:183], v[116:119]
	v_mfma_f32_16x16x32_bf16 v[112:115], v[172:175], v[180:183], v[112:115]
	v_mfma_f32_16x16x32_bf16 v[100:103], v[144:147], v[198:201], v[100:103]
	v_mfma_f32_16x16x32_bf16 v[96:99], v[172:175], v[198:201], v[96:99]
	v_mfma_f32_16x16x32_bf16 v[84:87], v[144:147], v[206:209], v[84:87]
	v_mfma_f32_16x16x32_bf16 v[80:83], v[172:175], v[206:209], v[80:83]
	v_mfma_f32_16x16x32_bf16 v[68:71], v[144:147], v[214:217], v[68:71]
	v_mfma_f32_16x16x32_bf16 v[64:67], v[172:175], v[214:217], v[64:67]
	v_mfma_f32_16x16x32_bf16 v[116:119], v[148:151], v[194:197], v[116:119]
	v_mfma_f32_16x16x32_bf16 v[112:115], v[176:179], v[194:197], v[112:115]
	v_mfma_f32_16x16x32_bf16 v[100:103], v[148:151], v[202:205], v[100:103]
	v_mfma_f32_16x16x32_bf16 v[96:99], v[176:179], v[202:205], v[96:99]
	v_mfma_f32_16x16x32_bf16 v[84:87], v[148:151], v[210:213], v[84:87]
	v_mfma_f32_16x16x32_bf16 v[80:83], v[176:179], v[210:213], v[80:83]
	v_mfma_f32_16x16x32_bf16 v[68:71], v[148:151], v[218:221], v[68:71]
	v_mfma_f32_16x16x32_bf16 v[64:67], v[176:179], v[218:221], v[64:67]
	s_barrier
	s_add_i32 s62, s73, s17
	s_mov_b32 m0, s62
	ds_read_b128 v[180:183], v191 offset:49152
	ds_read_b128 v[194:197], v191 offset:50176
	ds_read_b128 v[198:201], v191 offset:51200
	ds_read_b128 v[202:205], v191 offset:52224
	ds_read_b128 v[206:209], v191 offset:53248
	ds_read_b128 v[210:213], v191 offset:54272
	ds_read_b128 v[214:217], v191 offset:55296
	ds_read_b128 v[218:221], v191 offset:56320
	global_load_lds_dwordx4 v154, s[98:99]
	s_add_i32 m0, s62, 0x2000
	s_add_u32 s42, s42, 0x40080
	s_addc_u32 s43, s43, 0
	s_add_i32 s62, s74, s17
	global_load_lds_dwordx4 v158, s[98:99]
	s_mov_b32 m0, s62
	s_nop 0
	global_load_lds_dwordx4 v154, s[42:43]
	s_add_i32 m0, s62, 0x2000
	s_nop 0
	global_load_lds_dwordx4 v158, s[42:43]
	s_mov_b32 m0, s23
	s_nop 0
	global_load_lds_dwordx4 v152, s[100:101]
	s_mov_b32 m0, s60
	s_nop 0
	global_load_lds_dwordx4 v156, s[100:101]
	s_waitcnt vmcnt(8)
	s_waitcnt lgkmcnt(0)
	s_barrier
	s_waitcnt lgkmcnt(0)
	v_mfma_f32_16x16x32_bf16 v[60:63], v[128:131], v[180:183], v[60:63]
	v_mfma_f32_16x16x32_bf16 v[56:59], v[136:139], v[180:183], v[56:59]
	v_mfma_f32_16x16x32_bf16 v[44:47], v[128:131], v[198:201], v[44:47]
	v_mfma_f32_16x16x32_bf16 v[40:43], v[136:139], v[198:201], v[40:43]
	v_mfma_f32_16x16x32_bf16 v[28:31], v[128:131], v[206:209], v[28:31]
	v_mfma_f32_16x16x32_bf16 v[24:27], v[136:139], v[206:209], v[24:27]
	v_mfma_f32_16x16x32_bf16 v[12:15], v[128:131], v[214:217], v[12:15]
	v_mfma_f32_16x16x32_bf16 v[8:11], v[136:139], v[214:217], v[8:11]
	v_mfma_f32_16x16x32_bf16 v[60:63], v[132:135], v[194:197], v[60:63]
	v_mfma_f32_16x16x32_bf16 v[56:59], v[140:143], v[194:197], v[56:59]
	v_mfma_f32_16x16x32_bf16 v[44:47], v[132:135], v[202:205], v[44:47]
	v_mfma_f32_16x16x32_bf16 v[40:43], v[140:143], v[202:205], v[40:43]
	v_mfma_f32_16x16x32_bf16 v[28:31], v[132:135], v[210:213], v[28:31]
	v_mfma_f32_16x16x32_bf16 v[24:27], v[140:143], v[210:213], v[24:27]
	v_mfma_f32_16x16x32_bf16 v[12:15], v[132:135], v[218:221], v[12:15]
	v_mfma_f32_16x16x32_bf16 v[8:11], v[140:143], v[218:221], v[8:11]
	v_mfma_f32_16x16x32_bf16 v[52:55], v[144:147], v[180:183], v[52:55]
	v_mfma_f32_16x16x32_bf16 v[48:51], v[172:175], v[180:183], v[48:51]
	v_mfma_f32_16x16x32_bf16 v[36:39], v[144:147], v[198:201], v[36:39]
	v_mfma_f32_16x16x32_bf16 v[32:35], v[172:175], v[198:201], v[32:35]
	v_mfma_f32_16x16x32_bf16 v[20:23], v[144:147], v[206:209], v[20:23]
	v_mfma_f32_16x16x32_bf16 v[16:19], v[172:175], v[206:209], v[16:19]
	v_mfma_f32_16x16x32_bf16 v[4:7], v[144:147], v[214:217], v[4:7]
	v_mfma_f32_16x16x32_bf16 v[0:3], v[172:175], v[214:217], v[0:3]
	v_mfma_f32_16x16x32_bf16 v[52:55], v[148:151], v[194:197], v[52:55]
	v_mfma_f32_16x16x32_bf16 v[48:51], v[176:179], v[194:197], v[48:51]
	v_mfma_f32_16x16x32_bf16 v[36:39], v[148:151], v[202:205], v[36:39]
	v_mfma_f32_16x16x32_bf16 v[32:35], v[176:179], v[202:205], v[32:35]
	v_mfma_f32_16x16x32_bf16 v[20:23], v[148:151], v[210:213], v[20:23]
	v_mfma_f32_16x16x32_bf16 v[16:19], v[176:179], v[210:213], v[16:19]
	v_mfma_f32_16x16x32_bf16 v[4:7], v[148:151], v[218:221], v[4:7]
	v_mfma_f32_16x16x32_bf16 v[0:3], v[176:179], v[218:221], v[0:3]
	s_barrier
	s_add_i32 s72, s72, 2
	s_add_u32 s40, s40, 0x100
	s_addc_u32 s41, s41, 0
	s_add_u32 s70, s70, 0x100
	s_addc_u32 s71, s71, 0
	s_cmp_gt_u32 s72, 13
	s_cbranch_scc1 .Lpeel_exit_1026

.Lpeel_exit_1026:
	s_and_b64 vcc, exec, s[24:25]
	s_cbranch_vccz .LBB0_1029
	s_barrier

.LBB0_1114:
	s_ashr_i32 s27, s26, 31
	s_lshl_b64 s[30:31], s[26:27], 19
	s_add_u32 s30, s82, s30
	s_addc_u32 s31, s83, s31
	s_and_b64 s[34:35], s[4:5], exec
	s_cselect_b32 s27, s31, s39
	s_cselect_b32 s64, s30, s38
	s_ashr_i32 s29, s28, 31
	s_lshl_b64 s[34:35], s[28:29], 19
	s_add_u32 s34, s6, s34
	s_addc_u32 s35, s7, s35
	s_and_b64 s[42:43], s[4:5], exec
	s_cselect_b32 s29, s35, s41
	s_cselect_b32 s65, s34, s40
	s_add_u32 s38, s38, 0x40080
	s_addc_u32 s39, s39, 0
	s_add_u32 s66, s40, 0x100
	s_addc_u32 s67, s41, 0
	s_mov_b32 s70, -2
	ds_read_b128 v[144:147], v155
	ds_read_b128 v[160:163], v155 offset:1024
	ds_read_b128 v[164:167], v155 offset:2048
	ds_read_b128 v[168:171], v155 offset:3072
	ds_read_b128 v[172:175], v157
	ds_read_b128 v[176:179], v157 offset:1024
	ds_read_b128 v[180:183], v157 offset:2048
	ds_read_b128 v[186:189], v157 offset:3072
	s_add_u32 s40, s38, 0xfffc0080
	s_addc_u32 s41, s39, -1
	s_cmp_eq_u32 s70, 12
	s_cselect_b32 s43, s27, s41
	s_cselect_b32 s42, s64, s40
	s_cselect_b32 s41, s29, s67
	s_cselect_b32 s40, s65, s66
	s_add_i32 m0, s16, 0xc000
	ds_read_b128 v[190:193], v158
	ds_read_b128 v[194:197], v158 offset:1024
	ds_read_b128 v[198:201], v158 offset:2048
	ds_read_b128 v[202:205], v158 offset:3072
	ds_read_b128 v[206:209], v158 offset:4096
	ds_read_b128 v[210:213], v158 offset:5120
	ds_read_b128 v[214:217], v158 offset:6144
	ds_read_b128 v[218:221], v158 offset:7168
	global_load_lds_dwordx4 v136, s[38:39]
	s_add_i32 m0, s16, 0xe000
	s_nop 0
	global_load_lds_dwordx4 v138, s[38:39]
	s_waitcnt vmcnt(8)
	s_waitcnt lgkmcnt(0)
	s_barrier
	s_waitcnt lgkmcnt(0)
	v_mfma_f32_16x16x32_bf16 v[124:127], v[144:147], v[190:193], 0
	v_mfma_f32_16x16x32_bf16 v[120:123], v[164:167], v[190:193], 0
	v_mfma_f32_16x16x32_bf16 v[116:119], v[144:147], v[198:201], 0
	v_mfma_f32_16x16x32_bf16 v[104:107], v[164:167], v[198:201], 0
	v_mfma_f32_16x16x32_bf16 v[92:95], v[144:147], v[206:209], 0
	v_mfma_f32_16x16x32_bf16 v[88:91], v[164:167], v[206:209], 0
	v_mfma_f32_16x16x32_bf16 v[76:79], v[144:147], v[214:217], 0
	v_mfma_f32_16x16x32_bf16 v[72:75], v[164:167], v[214:217], 0
	v_mfma_f32_16x16x32_bf16 v[124:127], v[160:163], v[194:197], v[124:127]
	v_mfma_f32_16x16x32_bf16 v[120:123], v[168:171], v[194:197], v[120:123]
	v_mfma_f32_16x16x32_bf16 v[116:119], v[160:163], v[202:205], v[116:119]
	v_mfma_f32_16x16x32_bf16 v[104:107], v[168:171], v[202:205], v[104:107]
	v_mfma_f32_16x16x32_bf16 v[92:95], v[160:163], v[210:213], v[92:95]
	v_mfma_f32_16x16x32_bf16 v[88:91], v[168:171], v[210:213], v[88:91]
	v_mfma_f32_16x16x32_bf16 v[76:79], v[160:163], v[218:221], v[76:79]
	v_mfma_f32_16x16x32_bf16 v[72:75], v[168:171], v[218:221], v[72:75]
	v_mfma_f32_16x16x32_bf16 v[112:115], v[172:175], v[190:193], 0
	v_mfma_f32_16x16x32_bf16 v[108:111], v[180:183], v[190:193], 0
	v_mfma_f32_16x16x32_bf16 v[100:103], v[172:175], v[198:201], 0
	v_mfma_f32_16x16x32_bf16 v[96:99], v[180:183], v[198:201], 0
	v_mfma_f32_16x16x32_bf16 v[84:87], v[172:175], v[206:209], 0
	v_mfma_f32_16x16x32_bf16 v[80:83], v[180:183], v[206:209], 0
	v_mfma_f32_16x16x32_bf16 v[68:71], v[172:175], v[214:217], 0
	v_mfma_f32_16x16x32_bf16 v[64:67], v[180:183], v[214:217], 0
	v_mfma_f32_16x16x32_bf16 v[112:115], v[176:179], v[194:197], v[112:115]
	v_mfma_f32_16x16x32_bf16 v[108:111], v[186:189], v[194:197], v[108:111]
	v_mfma_f32_16x16x32_bf16 v[100:103], v[176:179], v[202:205], v[100:103]
	v_mfma_f32_16x16x32_bf16 v[96:99], v[186:189], v[202:205], v[96:99]
	v_mfma_f32_16x16x32_bf16 v[84:87], v[176:179], v[210:213], v[84:87]
	v_mfma_f32_16x16x32_bf16 v[80:83], v[186:189], v[210:213], v[80:83]
	v_mfma_f32_16x16x32_bf16 v[68:71], v[176:179], v[218:221], v[68:71]
	v_mfma_f32_16x16x32_bf16 v[64:67], v[186:189], v[218:221], v[64:67]
	s_barrier
	s_add_i32 s71, s60, s3
	s_mov_b32 m0, s71
	ds_read_b128 v[190:193], v158 offset:16384
	ds_read_b128 v[194:197], v158 offset:17408
	ds_read_b128 v[198:201], v158 offset:18432
	ds_read_b128 v[202:205], v158 offset:19456
	ds_read_b128 v[206:209], v158 offset:20480
	ds_read_b128 v[210:213], v158 offset:21504
	ds_read_b128 v[214:217], v158 offset:22528
	ds_read_b128 v[218:221], v158 offset:23552
	global_load_lds_dwordx4 v132, s[40:41]
	s_add_i32 m0, s71, 0x2000
	s_add_u32 s72, s40, 0x40000
	s_addc_u32 s73, s41, 0
	s_add_i32 s71, s61, s3
	global_load_lds_dwordx4 v128, s[40:41]
	s_mov_b32 m0, s71
	global_load_lds_dwordx4 v132, s[72:73]
	s_add_i32 m0, s71, 0x2000
	s_nop 0
	global_load_lds_dwordx4 v128, s[72:73]
	s_mov_b32 m0, s16
	s_nop 0
	global_load_lds_dwordx4 v134, s[42:43]
	s_mov_b32 m0, s17
	s_nop 0
	global_load_lds_dwordx4 v130, s[42:43]
	s_add_u32 s98, s40, s12
	s_addc_u32 s99, s41, s13
	s_add_u32 s100, s42, s12
	s_addc_u32 s101, s43, s13
	s_waitcnt vmcnt(8)
	s_waitcnt lgkmcnt(0)
	s_barrier
	s_waitcnt lgkmcnt(0)
	v_mfma_f32_16x16x32_bf16 v[60:63], v[144:147], v[190:193], 0
	v_mfma_f32_16x16x32_bf16 v[56:59], v[164:167], v[190:193], 0
	v_mfma_f32_16x16x32_bf16 v[44:47], v[144:147], v[198:201], 0
	v_mfma_f32_16x16x32_bf16 v[40:43], v[164:167], v[198:201], 0
	v_mfma_f32_16x16x32_bf16 v[28:31], v[144:147], v[206:209], 0
	v_mfma_f32_16x16x32_bf16 v[24:27], v[164:167], v[206:209], 0
	v_mfma_f32_16x16x32_bf16 v[12:15], v[144:147], v[214:217], 0
	v_mfma_f32_16x16x32_bf16 v[8:11], v[164:167], v[214:217], 0
	v_mfma_f32_16x16x32_bf16 v[60:63], v[160:163], v[194:197], v[60:63]
	v_mfma_f32_16x16x32_bf16 v[56:59], v[168:171], v[194:197], v[56:59]
	v_mfma_f32_16x16x32_bf16 v[44:47], v[160:163], v[202:205], v[44:47]
	v_mfma_f32_16x16x32_bf16 v[40:43], v[168:171], v[202:205], v[40:43]
	v_mfma_f32_16x16x32_bf16 v[28:31], v[160:163], v[210:213], v[28:31]
	v_mfma_f32_16x16x32_bf16 v[24:27], v[168:171], v[210:213], v[24:27]
	v_mfma_f32_16x16x32_bf16 v[12:15], v[160:163], v[218:221], v[12:15]
	v_mfma_f32_16x16x32_bf16 v[8:11], v[168:171], v[218:221], v[8:11]
	v_mfma_f32_16x16x32_bf16 v[52:55], v[172:175], v[190:193], 0
	v_mfma_f32_16x16x32_bf16 v[48:51], v[180:183], v[190:193], 0
	v_mfma_f32_16x16x32_bf16 v[36:39], v[172:175], v[198:201], 0
	v_mfma_f32_16x16x32_bf16 v[32:35], v[180:183], v[198:201], 0
	v_mfma_f32_16x16x32_bf16 v[20:23], v[172:175], v[206:209], 0
	v_mfma_f32_16x16x32_bf16 v[16:19], v[180:183], v[206:209], 0
	v_mfma_f32_16x16x32_bf16 v[4:7], v[172:175], v[214:217], 0
	v_mfma_f32_16x16x32_bf16 v[0:3], v[180:183], v[214:217], 0
	v_mfma_f32_16x16x32_bf16 v[52:55], v[176:179], v[194:197], v[52:55]
	v_mfma_f32_16x16x32_bf16 v[48:51], v[186:189], v[194:197], v[48:51]
	v_mfma_f32_16x16x32_bf16 v[36:39], v[176:179], v[202:205], v[36:39]
	v_mfma_f32_16x16x32_bf16 v[32:35], v[186:189], v[202:205], v[32:35]
	v_mfma_f32_16x16x32_bf16 v[20:23], v[176:179], v[210:213], v[20:23]
	v_mfma_f32_16x16x32_bf16 v[16:19], v[186:189], v[210:213], v[16:19]
	v_mfma_f32_16x16x32_bf16 v[4:7], v[176:179], v[218:221], v[4:7]
	v_mfma_f32_16x16x32_bf16 v[0:3], v[186:189], v[218:221], v[0:3]
	s_barrier
	s_add_i32 s71, 0, 0x18000
	v_add_u32_e32 v148, s71, v151
	s_add_i32 s72, 0, 0x1c000
	ds_read_b128 v[144:147], v148
	ds_read_b128 v[160:163], v148 offset:1024
	ds_read_b128 v[164:167], v148 offset:2048
	ds_read_b128 v[168:171], v148 offset:3072
	v_add_u32_e32 v148, s72, v151
	ds_read_b128 v[172:175], v148
	ds_read_b128 v[176:179], v148 offset:1024
	ds_read_b128 v[180:183], v148 offset:2048
	ds_read_b128 v[186:189], v148 offset:3072
	s_add_u32 s42, s42, 0x40000
	s_addc_u32 s43, s43, 0
	s_mov_b32 m0, s18
	ds_read_b128 v[190:193], v158 offset:32768
	ds_read_b128 v[194:197], v158 offset:33792
	ds_read_b128 v[198:201], v158 offset:34816
	ds_read_b128 v[202:205], v158 offset:35840
	ds_read_b128 v[206:209], v158 offset:36864
	ds_read_b128 v[210:213], v158 offset:37888
	ds_read_b128 v[214:217], v158 offset:38912
	ds_read_b128 v[218:221], v158 offset:39936
	global_load_lds_dwordx4 v134, s[42:43]
	s_mov_b32 m0, s19
	s_nop 0
	global_load_lds_dwordx4 v130, s[42:43]
	s_waitcnt vmcnt(8)
	s_waitcnt lgkmcnt(0)
	s_barrier
	s_waitcnt lgkmcnt(0)
	v_mfma_f32_16x16x32_bf16 v[124:127], v[144:147], v[190:193], v[124:127]
	v_mfma_f32_16x16x32_bf16 v[120:123], v[164:167], v[190:193], v[120:123]
	v_mfma_f32_16x16x32_bf16 v[116:119], v[144:147], v[198:201], v[116:119]
	v_mfma_f32_16x16x32_bf16 v[104:107], v[164:167], v[198:201], v[104:107]
	v_mfma_f32_16x16x32_bf16 v[92:95], v[144:147], v[206:209], v[92:95]
	v_mfma_f32_16x16x32_bf16 v[88:91], v[164:167], v[206:209], v[88:91]
	v_mfma_f32_16x16x32_bf16 v[76:79], v[144:147], v[214:217], v[76:79]
	v_mfma_f32_16x16x32_bf16 v[72:75], v[164:167], v[214:217], v[72:75]
	v_mfma_f32_16x16x32_bf16 v[124:127], v[160:163], v[194:197], v[124:127]
	v_mfma_f32_16x16x32_bf16 v[120:123], v[168:171], v[194:197], v[120:123]
	v_mfma_f32_16x16x32_bf16 v[116:119], v[160:163], v[202:205], v[116:119]
	v_mfma_f32_16x16x32_bf16 v[104:107], v[168:171], v[202:205], v[104:107]
	v_mfma_f32_16x16x32_bf16 v[92:95], v[160:163], v[210:213], v[92:95]
	v_mfma_f32_16x16x32_bf16 v[88:91], v[168:171], v[210:213], v[88:91]
	v_mfma_f32_16x16x32_bf16 v[76:79], v[160:163], v[218:221], v[76:79]
	v_mfma_f32_16x16x32_bf16 v[72:75], v[168:171], v[218:221], v[72:75]
	v_mfma_f32_16x16x32_bf16 v[112:115], v[172:175], v[190:193], v[112:115]
	v_mfma_f32_16x16x32_bf16 v[108:111], v[180:183], v[190:193], v[108:111]
	v_mfma_f32_16x16x32_bf16 v[100:103], v[172:175], v[198:201], v[100:103]
	v_mfma_f32_16x16x32_bf16 v[96:99], v[180:183], v[198:201], v[96:99]
	v_mfma_f32_16x16x32_bf16 v[84:87], v[172:175], v[206:209], v[84:87]
	v_mfma_f32_16x16x32_bf16 v[80:83], v[180:183], v[206:209], v[80:83]
	v_mfma_f32_16x16x32_bf16 v[68:71], v[172:175], v[214:217], v[68:71]
	v_mfma_f32_16x16x32_bf16 v[64:67], v[180:183], v[214:217], v[64:67]
	v_mfma_f32_16x16x32_bf16 v[112:115], v[176:179], v[194:197], v[112:115]
	v_mfma_f32_16x16x32_bf16 v[108:111], v[186:189], v[194:197], v[108:111]
	v_mfma_f32_16x16x32_bf16 v[100:103], v[176:179], v[202:205], v[100:103]
	v_mfma_f32_16x16x32_bf16 v[96:99], v[186:189], v[202:205], v[96:99]
	v_mfma_f32_16x16x32_bf16 v[84:87], v[176:179], v[210:213], v[84:87]
	v_mfma_f32_16x16x32_bf16 v[80:83], v[186:189], v[210:213], v[80:83]
	v_mfma_f32_16x16x32_bf16 v[68:71], v[176:179], v[218:221], v[68:71]
	v_mfma_f32_16x16x32_bf16 v[64:67], v[186:189], v[218:221], v[64:67]
	s_barrier
	s_add_i32 s42, s71, s3
	s_mov_b32 m0, s42
	ds_read_b128 v[190:193], v158 offset:49152
	ds_read_b128 v[194:197], v158 offset:50176
	ds_read_b128 v[198:201], v158 offset:51200
	ds_read_b128 v[202:205], v158 offset:52224
	ds_read_b128 v[206:209], v158 offset:53248
	ds_read_b128 v[210:213], v158 offset:54272
	ds_read_b128 v[214:217], v158 offset:55296
	ds_read_b128 v[218:221], v158 offset:56320
	global_load_lds_dwordx4 v132, s[98:99]
	s_add_i32 m0, s42, 0x2000
	s_add_u32 s40, s40, 0x40080
	s_addc_u32 s41, s41, 0
	s_add_i32 s42, s72, s3
	global_load_lds_dwordx4 v128, s[98:99]
	s_mov_b32 m0, s42
	s_nop 0
	global_load_lds_dwordx4 v132, s[40:41]
	s_add_i32 m0, s42, 0x2000
	s_nop 0
	global_load_lds_dwordx4 v128, s[40:41]
	s_mov_b32 m0, s21
	s_nop 0
	global_load_lds_dwordx4 v134, s[100:101]
	s_mov_b32 m0, s22
	s_nop 0
	global_load_lds_dwordx4 v130, s[100:101]
	s_waitcnt vmcnt(8)
	s_waitcnt lgkmcnt(0)
	s_barrier
	s_waitcnt lgkmcnt(0)
	v_mfma_f32_16x16x32_bf16 v[60:63], v[144:147], v[190:193], v[60:63]
	v_mfma_f32_16x16x32_bf16 v[56:59], v[164:167], v[190:193], v[56:59]
	v_mfma_f32_16x16x32_bf16 v[44:47], v[144:147], v[198:201], v[44:47]
	v_mfma_f32_16x16x32_bf16 v[40:43], v[164:167], v[198:201], v[40:43]
	v_mfma_f32_16x16x32_bf16 v[28:31], v[144:147], v[206:209], v[28:31]
	v_mfma_f32_16x16x32_bf16 v[24:27], v[164:167], v[206:209], v[24:27]
	v_mfma_f32_16x16x32_bf16 v[12:15], v[144:147], v[214:217], v[12:15]
	v_mfma_f32_16x16x32_bf16 v[8:11], v[164:167], v[214:217], v[8:11]
	v_mfma_f32_16x16x32_bf16 v[60:63], v[160:163], v[194:197], v[60:63]
	v_mfma_f32_16x16x32_bf16 v[56:59], v[168:171], v[194:197], v[56:59]
	v_mfma_f32_16x16x32_bf16 v[44:47], v[160:163], v[202:205], v[44:47]
	v_mfma_f32_16x16x32_bf16 v[40:43], v[168:171], v[202:205], v[40:43]
	v_mfma_f32_16x16x32_bf16 v[28:31], v[160:163], v[210:213], v[28:31]
	v_mfma_f32_16x16x32_bf16 v[24:27], v[168:171], v[210:213], v[24:27]
	v_mfma_f32_16x16x32_bf16 v[12:15], v[160:163], v[218:221], v[12:15]
	v_mfma_f32_16x16x32_bf16 v[8:11], v[168:171], v[218:221], v[8:11]
	v_mfma_f32_16x16x32_bf16 v[52:55], v[172:175], v[190:193], v[52:55]
	v_mfma_f32_16x16x32_bf16 v[48:51], v[180:183], v[190:193], v[48:51]
	v_mfma_f32_16x16x32_bf16 v[36:39], v[172:175], v[198:201], v[36:39]
	v_mfma_f32_16x16x32_bf16 v[32:35], v[180:183], v[198:201], v[32:35]
	v_mfma_f32_16x16x32_bf16 v[20:23], v[172:175], v[206:209], v[20:23]
	v_mfma_f32_16x16x32_bf16 v[16:19], v[180:183], v[206:209], v[16:19]
	v_mfma_f32_16x16x32_bf16 v[4:7], v[172:175], v[214:217], v[4:7]
	v_mfma_f32_16x16x32_bf16 v[0:3], v[180:183], v[214:217], v[0:3]
	v_mfma_f32_16x16x32_bf16 v[52:55], v[176:179], v[194:197], v[52:55]
	v_mfma_f32_16x16x32_bf16 v[48:51], v[186:189], v[194:197], v[48:51]
	v_mfma_f32_16x16x32_bf16 v[36:39], v[176:179], v[202:205], v[36:39]
	v_mfma_f32_16x16x32_bf16 v[32:35], v[186:189], v[202:205], v[32:35]
	v_mfma_f32_16x16x32_bf16 v[20:23], v[176:179], v[210:213], v[20:23]
	v_mfma_f32_16x16x32_bf16 v[16:19], v[186:189], v[210:213], v[16:19]
	v_mfma_f32_16x16x32_bf16 v[4:7], v[176:179], v[218:221], v[4:7]
	v_mfma_f32_16x16x32_bf16 v[0:3], v[186:189], v[218:221], v[0:3]
	s_barrier
	s_add_i32 s70, s70, 2
	s_add_u32 s38, s38, 0x100
	s_addc_u32 s39, s39, 0
	s_add_u32 s66, s66, 0x100
	s_addc_u32 s67, s67, 0
	s_cmp_gt_u32 s70, 13
	s_cbranch_scc1 .Lpeel_exit_1115
.LBB0_1115:
	ds_read_b128 v[144:147], v155
	ds_read_b128 v[160:163], v155 offset:1024
	ds_read_b128 v[164:167], v155 offset:2048
	ds_read_b128 v[168:171], v155 offset:3072
	ds_read_b128 v[172:175], v157
	ds_read_b128 v[176:179], v157 offset:1024
	ds_read_b128 v[180:183], v157 offset:2048
	ds_read_b128 v[186:189], v157 offset:3072
	s_add_u32 s40, s38, 0xfffc0080
	s_addc_u32 s41, s39, -1
	s_cmp_eq_u32 s70, 12
	s_cselect_b32 s43, s27, s41
	s_cselect_b32 s42, s64, s40
	s_cselect_b32 s41, s29, s67
	s_cselect_b32 s40, s65, s66
	s_add_i32 m0, s16, 0xc000
	ds_read_b128 v[190:193], v158
	ds_read_b128 v[194:197], v158 offset:1024
	ds_read_b128 v[198:201], v158 offset:2048
	ds_read_b128 v[202:205], v158 offset:3072
	ds_read_b128 v[206:209], v158 offset:4096
	ds_read_b128 v[210:213], v158 offset:5120
	ds_read_b128 v[214:217], v158 offset:6144
	ds_read_b128 v[218:221], v158 offset:7168
	global_load_lds_dwordx4 v136, s[38:39]
	s_add_i32 m0, s16, 0xe000
	s_nop 0
	global_load_lds_dwordx4 v138, s[38:39]
	s_waitcnt vmcnt(8)
	s_waitcnt lgkmcnt(0)
	s_barrier
	s_waitcnt lgkmcnt(0)
	v_mfma_f32_16x16x32_bf16 v[124:127], v[144:147], v[190:193], v[124:127]
	v_mfma_f32_16x16x32_bf16 v[120:123], v[164:167], v[190:193], v[120:123]
	v_mfma_f32_16x16x32_bf16 v[116:119], v[144:147], v[198:201], v[116:119]
	v_mfma_f32_16x16x32_bf16 v[104:107], v[164:167], v[198:201], v[104:107]
	v_mfma_f32_16x16x32_bf16 v[92:95], v[144:147], v[206:209], v[92:95]
	v_mfma_f32_16x16x32_bf16 v[88:91], v[164:167], v[206:209], v[88:91]
	v_mfma_f32_16x16x32_bf16 v[76:79], v[144:147], v[214:217], v[76:79]
	v_mfma_f32_16x16x32_bf16 v[72:75], v[164:167], v[214:217], v[72:75]
	v_mfma_f32_16x16x32_bf16 v[124:127], v[160:163], v[194:197], v[124:127]
	v_mfma_f32_16x16x32_bf16 v[120:123], v[168:171], v[194:197], v[120:123]
	v_mfma_f32_16x16x32_bf16 v[116:119], v[160:163], v[202:205], v[116:119]
	v_mfma_f32_16x16x32_bf16 v[104:107], v[168:171], v[202:205], v[104:107]
	v_mfma_f32_16x16x32_bf16 v[92:95], v[160:163], v[210:213], v[92:95]
	v_mfma_f32_16x16x32_bf16 v[88:91], v[168:171], v[210:213], v[88:91]
	v_mfma_f32_16x16x32_bf16 v[76:79], v[160:163], v[218:221], v[76:79]
	v_mfma_f32_16x16x32_bf16 v[72:75], v[168:171], v[218:221], v[72:75]
	v_mfma_f32_16x16x32_bf16 v[112:115], v[172:175], v[190:193], v[112:115]
	v_mfma_f32_16x16x32_bf16 v[108:111], v[180:183], v[190:193], v[108:111]
	v_mfma_f32_16x16x32_bf16 v[100:103], v[172:175], v[198:201], v[100:103]
	v_mfma_f32_16x16x32_bf16 v[96:99], v[180:183], v[198:201], v[96:99]
	v_mfma_f32_16x16x32_bf16 v[84:87], v[172:175], v[206:209], v[84:87]
	v_mfma_f32_16x16x32_bf16 v[80:83], v[180:183], v[206:209], v[80:83]
	v_mfma_f32_16x16x32_bf16 v[68:71], v[172:175], v[214:217], v[68:71]
	v_mfma_f32_16x16x32_bf16 v[64:67], v[180:183], v[214:217], v[64:67]
	v_mfma_f32_16x16x32_bf16 v[112:115], v[176:179], v[194:197], v[112:115]
	v_mfma_f32_16x16x32_bf16 v[108:111], v[186:189], v[194:197], v[108:111]
	v_mfma_f32_16x16x32_bf16 v[100:103], v[176:179], v[202:205], v[100:103]
	v_mfma_f32_16x16x32_bf16 v[96:99], v[186:189], v[202:205], v[96:99]
	v_mfma_f32_16x16x32_bf16 v[84:87], v[176:179], v[210:213], v[84:87]
	v_mfma_f32_16x16x32_bf16 v[80:83], v[186:189], v[210:213], v[80:83]
	v_mfma_f32_16x16x32_bf16 v[68:71], v[176:179], v[218:221], v[68:71]
	v_mfma_f32_16x16x32_bf16 v[64:67], v[186:189], v[218:221], v[64:67]
	s_barrier
	s_add_i32 s71, s60, s3
	s_mov_b32 m0, s71
	ds_read_b128 v[190:193], v158 offset:16384
	ds_read_b128 v[194:197], v158 offset:17408
	ds_read_b128 v[198:201], v158 offset:18432
	ds_read_b128 v[202:205], v158 offset:19456
	ds_read_b128 v[206:209], v158 offset:20480
	ds_read_b128 v[210:213], v158 offset:21504
	ds_read_b128 v[214:217], v158 offset:22528
	ds_read_b128 v[218:221], v158 offset:23552
	global_load_lds_dwordx4 v132, s[40:41]
	s_add_i32 m0, s71, 0x2000
	s_add_u32 s72, s40, 0x40000
	s_addc_u32 s73, s41, 0
	s_add_i32 s71, s61, s3
	global_load_lds_dwordx4 v128, s[40:41]
	s_mov_b32 m0, s71
	global_load_lds_dwordx4 v132, s[72:73]
	s_add_i32 m0, s71, 0x2000
	s_nop 0
	global_load_lds_dwordx4 v128, s[72:73]
	s_mov_b32 m0, s16
	s_nop 0
	global_load_lds_dwordx4 v134, s[42:43]
	s_mov_b32 m0, s17
	s_nop 0
	global_load_lds_dwordx4 v130, s[42:43]
	s_add_u32 s98, s40, s12
	s_addc_u32 s99, s41, s13
	s_add_u32 s100, s42, s12
	s_addc_u32 s101, s43, s13
	s_waitcnt vmcnt(8)
	s_waitcnt lgkmcnt(0)
	s_barrier
	s_waitcnt lgkmcnt(0)
	v_mfma_f32_16x16x32_bf16 v[60:63], v[144:147], v[190:193], v[60:63]
	v_mfma_f32_16x16x32_bf16 v[56:59], v[164:167], v[190:193], v[56:59]
	v_mfma_f32_16x16x32_bf16 v[44:47], v[144:147], v[198:201], v[44:47]
	v_mfma_f32_16x16x32_bf16 v[40:43], v[164:167], v[198:201], v[40:43]
	v_mfma_f32_16x16x32_bf16 v[28:31], v[144:147], v[206:209], v[28:31]
	v_mfma_f32_16x16x32_bf16 v[24:27], v[164:167], v[206:209], v[24:27]
	v_mfma_f32_16x16x32_bf16 v[12:15], v[144:147], v[214:217], v[12:15]
	v_mfma_f32_16x16x32_bf16 v[8:11], v[164:167], v[214:217], v[8:11]
	v_mfma_f32_16x16x32_bf16 v[60:63], v[160:163], v[194:197], v[60:63]
	v_mfma_f32_16x16x32_bf16 v[56:59], v[168:171], v[194:197], v[56:59]
	v_mfma_f32_16x16x32_bf16 v[44:47], v[160:163], v[202:205], v[44:47]
	v_mfma_f32_16x16x32_bf16 v[40:43], v[168:171], v[202:205], v[40:43]
	v_mfma_f32_16x16x32_bf16 v[28:31], v[160:163], v[210:213], v[28:31]
	v_mfma_f32_16x16x32_bf16 v[24:27], v[168:171], v[210:213], v[24:27]
	v_mfma_f32_16x16x32_bf16 v[12:15], v[160:163], v[218:221], v[12:15]
	v_mfma_f32_16x16x32_bf16 v[8:11], v[168:171], v[218:221], v[8:11]
	v_mfma_f32_16x16x32_bf16 v[52:55], v[172:175], v[190:193], v[52:55]
	v_mfma_f32_16x16x32_bf16 v[48:51], v[180:183], v[190:193], v[48:51]
	v_mfma_f32_16x16x32_bf16 v[36:39], v[172:175], v[198:201], v[36:39]
	v_mfma_f32_16x16x32_bf16 v[32:35], v[180:183], v[198:201], v[32:35]
	v_mfma_f32_16x16x32_bf16 v[20:23], v[172:175], v[206:209], v[20:23]
	v_mfma_f32_16x16x32_bf16 v[16:19], v[180:183], v[206:209], v[16:19]
	v_mfma_f32_16x16x32_bf16 v[4:7], v[172:175], v[214:217], v[4:7]
	v_mfma_f32_16x16x32_bf16 v[0:3], v[180:183], v[214:217], v[0:3]
	v_mfma_f32_16x16x32_bf16 v[52:55], v[176:179], v[194:197], v[52:55]
	v_mfma_f32_16x16x32_bf16 v[48:51], v[186:189], v[194:197], v[48:51]
	v_mfma_f32_16x16x32_bf16 v[36:39], v[176:179], v[202:205], v[36:39]
	v_mfma_f32_16x16x32_bf16 v[32:35], v[186:189], v[202:205], v[32:35]
	v_mfma_f32_16x16x32_bf16 v[20:23], v[176:179], v[210:213], v[20:23]
	v_mfma_f32_16x16x32_bf16 v[16:19], v[186:189], v[210:213], v[16:19]
	v_mfma_f32_16x16x32_bf16 v[4:7], v[176:179], v[218:221], v[4:7]
	v_mfma_f32_16x16x32_bf16 v[0:3], v[186:189], v[218:221], v[0:3]
	s_barrier
	s_add_i32 s71, 0, 0x18000
	v_add_u32_e32 v148, s71, v151
	s_add_i32 s72, 0, 0x1c000
	ds_read_b128 v[144:147], v148
	ds_read_b128 v[160:163], v148 offset:1024
	ds_read_b128 v[164:167], v148 offset:2048
	ds_read_b128 v[168:171], v148 offset:3072
	v_add_u32_e32 v148, s72, v151
	ds_read_b128 v[172:175], v148
	ds_read_b128 v[176:179], v148 offset:1024
	ds_read_b128 v[180:183], v148 offset:2048
	ds_read_b128 v[186:189], v148 offset:3072
	s_add_u32 s42, s42, 0x40000
	s_addc_u32 s43, s43, 0
	s_mov_b32 m0, s18
	ds_read_b128 v[190:193], v158 offset:32768
	ds_read_b128 v[194:197], v158 offset:33792
	ds_read_b128 v[198:201], v158 offset:34816
	ds_read_b128 v[202:205], v158 offset:35840
	ds_read_b128 v[206:209], v158 offset:36864
	ds_read_b128 v[210:213], v158 offset:37888
	ds_read_b128 v[214:217], v158 offset:38912
	ds_read_b128 v[218:221], v158 offset:39936
	global_load_lds_dwordx4 v134, s[42:43]
	s_mov_b32 m0, s19
	s_nop 0
	global_load_lds_dwordx4 v130, s[42:43]
	s_waitcnt vmcnt(8)
	s_waitcnt lgkmcnt(0)
	s_barrier
	s_waitcnt lgkmcnt(0)
	v_mfma_f32_16x16x32_bf16 v[124:127], v[144:147], v[190:193], v[124:127]
	v_mfma_f32_16x16x32_bf16 v[120:123], v[164:167], v[190:193], v[120:123]
	v_mfma_f32_16x16x32_bf16 v[116:119], v[144:147], v[198:201], v[116:119]
	v_mfma_f32_16x16x32_bf16 v[104:107], v[164:167], v[198:201], v[104:107]
	v_mfma_f32_16x16x32_bf16 v[92:95], v[144:147], v[206:209], v[92:95]
	v_mfma_f32_16x16x32_bf16 v[88:91], v[164:167], v[206:209], v[88:91]
	v_mfma_f32_16x16x32_bf16 v[76:79], v[144:147], v[214:217], v[76:79]
	v_mfma_f32_16x16x32_bf16 v[72:75], v[164:167], v[214:217], v[72:75]
	v_mfma_f32_16x16x32_bf16 v[124:127], v[160:163], v[194:197], v[124:127]
	v_mfma_f32_16x16x32_bf16 v[120:123], v[168:171], v[194:197], v[120:123]
	v_mfma_f32_16x16x32_bf16 v[116:119], v[160:163], v[202:205], v[116:119]
	v_mfma_f32_16x16x32_bf16 v[104:107], v[168:171], v[202:205], v[104:107]
	v_mfma_f32_16x16x32_bf16 v[92:95], v[160:163], v[210:213], v[92:95]
	v_mfma_f32_16x16x32_bf16 v[88:91], v[168:171], v[210:213], v[88:91]
	v_mfma_f32_16x16x32_bf16 v[76:79], v[160:163], v[218:221], v[76:79]
	v_mfma_f32_16x16x32_bf16 v[72:75], v[168:171], v[218:221], v[72:75]
	v_mfma_f32_16x16x32_bf16 v[112:115], v[172:175], v[190:193], v[112:115]
	v_mfma_f32_16x16x32_bf16 v[108:111], v[180:183], v[190:193], v[108:111]
	v_mfma_f32_16x16x32_bf16 v[100:103], v[172:175], v[198:201], v[100:103]
	v_mfma_f32_16x16x32_bf16 v[96:99], v[180:183], v[198:201], v[96:99]
	v_mfma_f32_16x16x32_bf16 v[84:87], v[172:175], v[206:209], v[84:87]
	v_mfma_f32_16x16x32_bf16 v[80:83], v[180:183], v[206:209], v[80:83]
	v_mfma_f32_16x16x32_bf16 v[68:71], v[172:175], v[214:217], v[68:71]
	v_mfma_f32_16x16x32_bf16 v[64:67], v[180:183], v[214:217], v[64:67]
	v_mfma_f32_16x16x32_bf16 v[112:115], v[176:179], v[194:197], v[112:115]
	v_mfma_f32_16x16x32_bf16 v[108:111], v[186:189], v[194:197], v[108:111]
	v_mfma_f32_16x16x32_bf16 v[100:103], v[176:179], v[202:205], v[100:103]
	v_mfma_f32_16x16x32_bf16 v[96:99], v[186:189], v[202:205], v[96:99]
	v_mfma_f32_16x16x32_bf16 v[84:87], v[176:179], v[210:213], v[84:87]
	v_mfma_f32_16x16x32_bf16 v[80:83], v[186:189], v[210:213], v[80:83]
	v_mfma_f32_16x16x32_bf16 v[68:71], v[176:179], v[218:221], v[68:71]
	v_mfma_f32_16x16x32_bf16 v[64:67], v[186:189], v[218:221], v[64:67]
	s_barrier
	s_add_i32 s42, s71, s3
	s_mov_b32 m0, s42
	ds_read_b128 v[190:193], v158 offset:49152
	ds_read_b128 v[194:197], v158 offset:50176
	ds_read_b128 v[198:201], v158 offset:51200
	ds_read_b128 v[202:205], v158 offset:52224
	ds_read_b128 v[206:209], v158 offset:53248
	ds_read_b128 v[210:213], v158 offset:54272
	ds_read_b128 v[214:217], v158 offset:55296
	ds_read_b128 v[218:221], v158 offset:56320
	global_load_lds_dwordx4 v132, s[98:99]
	s_add_i32 m0, s42, 0x2000
	s_add_u32 s40, s40, 0x40080
	s_addc_u32 s41, s41, 0
	s_add_i32 s42, s72, s3
	global_load_lds_dwordx4 v128, s[98:99]
	s_mov_b32 m0, s42
	s_nop 0
	global_load_lds_dwordx4 v132, s[40:41]
	s_add_i32 m0, s42, 0x2000
	s_nop 0
	global_load_lds_dwordx4 v128, s[40:41]
	s_mov_b32 m0, s21
	s_nop 0
	global_load_lds_dwordx4 v134, s[100:101]
	s_mov_b32 m0, s22
	s_nop 0
	global_load_lds_dwordx4 v130, s[100:101]
	s_waitcnt vmcnt(8)
	s_waitcnt lgkmcnt(0)
	s_barrier
	s_waitcnt lgkmcnt(0)
	v_mfma_f32_16x16x32_bf16 v[60:63], v[144:147], v[190:193], v[60:63]
	v_mfma_f32_16x16x32_bf16 v[56:59], v[164:167], v[190:193], v[56:59]
	v_mfma_f32_16x16x32_bf16 v[44:47], v[144:147], v[198:201], v[44:47]
	v_mfma_f32_16x16x32_bf16 v[40:43], v[164:167], v[198:201], v[40:43]
	v_mfma_f32_16x16x32_bf16 v[28:31], v[144:147], v[206:209], v[28:31]
	v_mfma_f32_16x16x32_bf16 v[24:27], v[164:167], v[206:209], v[24:27]
	v_mfma_f32_16x16x32_bf16 v[12:15], v[144:147], v[214:217], v[12:15]
	v_mfma_f32_16x16x32_bf16 v[8:11], v[164:167], v[214:217], v[8:11]
	v_mfma_f32_16x16x32_bf16 v[60:63], v[160:163], v[194:197], v[60:63]
	v_mfma_f32_16x16x32_bf16 v[56:59], v[168:171], v[194:197], v[56:59]
	v_mfma_f32_16x16x32_bf16 v[44:47], v[160:163], v[202:205], v[44:47]
	v_mfma_f32_16x16x32_bf16 v[40:43], v[168:171], v[202:205], v[40:43]
	v_mfma_f32_16x16x32_bf16 v[28:31], v[160:163], v[210:213], v[28:31]
	v_mfma_f32_16x16x32_bf16 v[24:27], v[168:171], v[210:213], v[24:27]
	v_mfma_f32_16x16x32_bf16 v[12:15], v[160:163], v[218:221], v[12:15]
	v_mfma_f32_16x16x32_bf16 v[8:11], v[168:171], v[218:221], v[8:11]
	v_mfma_f32_16x16x32_bf16 v[52:55], v[172:175], v[190:193], v[52:55]
	v_mfma_f32_16x16x32_bf16 v[48:51], v[180:183], v[190:193], v[48:51]
	v_mfma_f32_16x16x32_bf16 v[36:39], v[172:175], v[198:201], v[36:39]
	v_mfma_f32_16x16x32_bf16 v[32:35], v[180:183], v[198:201], v[32:35]
	v_mfma_f32_16x16x32_bf16 v[20:23], v[172:175], v[206:209], v[20:23]
	v_mfma_f32_16x16x32_bf16 v[16:19], v[180:183], v[206:209], v[16:19]
	v_mfma_f32_16x16x32_bf16 v[4:7], v[172:175], v[214:217], v[4:7]
	v_mfma_f32_16x16x32_bf16 v[0:3], v[180:183], v[214:217], v[0:3]
	v_mfma_f32_16x16x32_bf16 v[52:55], v[176:179], v[194:197], v[52:55]
	v_mfma_f32_16x16x32_bf16 v[48:51], v[186:189], v[194:197], v[48:51]
	v_mfma_f32_16x16x32_bf16 v[36:39], v[176:179], v[202:205], v[36:39]
	v_mfma_f32_16x16x32_bf16 v[32:35], v[186:189], v[202:205], v[32:35]
	v_mfma_f32_16x16x32_bf16 v[20:23], v[176:179], v[210:213], v[20:23]
	v_mfma_f32_16x16x32_bf16 v[16:19], v[186:189], v[210:213], v[16:19]
	v_mfma_f32_16x16x32_bf16 v[4:7], v[176:179], v[218:221], v[4:7]
	v_mfma_f32_16x16x32_bf16 v[0:3], v[186:189], v[218:221], v[0:3]
	s_barrier
	s_add_i32 s70, s70, 2
	s_add_u32 s38, s38, 0x100
	s_addc_u32 s39, s39, 0
	s_add_u32 s66, s66, 0x100
	s_addc_u32 s67, s67, 0
	s_cmp_gt_u32 s70, 13
	s_cbranch_scc0 .LBB0_1115

.LBB0_1323:
	s_add_u32 s34, s34, 0xb0080
	s_addc_u32 s35, s35, 0
	s_add_u32 s31, s36, 0x100
	s_addc_u32 s63, s37, 0
	s_mov_b32 s64, -2
	s_waitcnt lgkmcnt(0)
	ds_read_b128 v[128:131], v189
	ds_read_b128 v[132:135], v189 offset:1024
	ds_read_b128 v[136:139], v189 offset:2048
	ds_read_b128 v[140:143], v189 offset:3072
	ds_read_b128 v[144:147], v190
	ds_read_b128 v[148:151], v190 offset:1024
	ds_read_b128 v[172:175], v190 offset:2048
	ds_read_b128 v[176:179], v190 offset:3072
	s_add_u32 s36, s34, 0xfff50080
	s_addc_u32 s37, s35, -1
	s_cmp_eq_u32 s64, 40
	s_cselect_b32 s39, s1, s37
	s_cselect_b32 s38, s0, s36
	s_cselect_b32 s37, s29, s63
	s_cselect_b32 s36, s28, s31
	s_add_i32 m0, s16, 0xc000
	ds_read_b128 v[180:183], v191
	ds_read_b128 v[194:197], v191 offset:1024
	ds_read_b128 v[198:201], v191 offset:2048
	ds_read_b128 v[202:205], v191 offset:3072
	ds_read_b128 v[206:209], v191 offset:4096
	ds_read_b128 v[210:213], v191 offset:5120
	ds_read_b128 v[214:217], v191 offset:6144
	ds_read_b128 v[218:221], v191 offset:7168
	global_load_lds_dwordx4 v164, s[34:35]
	s_add_i32 m0, s16, 0xe000
	s_nop 0
	global_load_lds_dwordx4 v166, s[34:35]
	s_waitcnt vmcnt(8)
	s_waitcnt lgkmcnt(0)
	s_barrier
	s_waitcnt lgkmcnt(0)
	v_mfma_f32_16x16x32_bf16 v[124:127], v[128:131], v[180:183], 0
	v_mfma_f32_16x16x32_bf16 v[120:123], v[136:139], v[180:183], 0
	v_mfma_f32_16x16x32_bf16 v[108:111], v[128:131], v[198:201], 0
	v_mfma_f32_16x16x32_bf16 v[104:107], v[136:139], v[198:201], 0
	v_mfma_f32_16x16x32_bf16 v[92:95], v[128:131], v[206:209], 0
	v_mfma_f32_16x16x32_bf16 v[88:91], v[136:139], v[206:209], 0
	v_mfma_f32_16x16x32_bf16 v[76:79], v[128:131], v[214:217], 0
	v_mfma_f32_16x16x32_bf16 v[72:75], v[136:139], v[214:217], 0
	v_mfma_f32_16x16x32_bf16 v[124:127], v[132:135], v[194:197], v[124:127]
	v_mfma_f32_16x16x32_bf16 v[120:123], v[140:143], v[194:197], v[120:123]
	v_mfma_f32_16x16x32_bf16 v[108:111], v[132:135], v[202:205], v[108:111]
	v_mfma_f32_16x16x32_bf16 v[104:107], v[140:143], v[202:205], v[104:107]
	v_mfma_f32_16x16x32_bf16 v[92:95], v[132:135], v[210:213], v[92:95]
	v_mfma_f32_16x16x32_bf16 v[88:91], v[140:143], v[210:213], v[88:91]
	v_mfma_f32_16x16x32_bf16 v[76:79], v[132:135], v[218:221], v[76:79]
	v_mfma_f32_16x16x32_bf16 v[72:75], v[140:143], v[218:221], v[72:75]
	v_mfma_f32_16x16x32_bf16 v[116:119], v[144:147], v[180:183], 0
	v_mfma_f32_16x16x32_bf16 v[112:115], v[172:175], v[180:183], 0
	v_mfma_f32_16x16x32_bf16 v[100:103], v[144:147], v[198:201], 0
	v_mfma_f32_16x16x32_bf16 v[96:99], v[172:175], v[198:201], 0
	v_mfma_f32_16x16x32_bf16 v[84:87], v[144:147], v[206:209], 0
	v_mfma_f32_16x16x32_bf16 v[80:83], v[172:175], v[206:209], 0
	v_mfma_f32_16x16x32_bf16 v[68:71], v[144:147], v[214:217], 0
	v_mfma_f32_16x16x32_bf16 v[64:67], v[172:175], v[214:217], 0
	v_mfma_f32_16x16x32_bf16 v[116:119], v[148:151], v[194:197], v[116:119]
	v_mfma_f32_16x16x32_bf16 v[112:115], v[176:179], v[194:197], v[112:115]
	v_mfma_f32_16x16x32_bf16 v[100:103], v[148:151], v[202:205], v[100:103]
	v_mfma_f32_16x16x32_bf16 v[96:99], v[176:179], v[202:205], v[96:99]
	v_mfma_f32_16x16x32_bf16 v[84:87], v[148:151], v[210:213], v[84:87]
	v_mfma_f32_16x16x32_bf16 v[80:83], v[176:179], v[210:213], v[80:83]
	v_mfma_f32_16x16x32_bf16 v[68:71], v[148:151], v[218:221], v[68:71]
	v_mfma_f32_16x16x32_bf16 v[64:67], v[176:179], v[218:221], v[64:67]
	s_barrier
	s_add_i32 s65, s42, s15
	s_mov_b32 m0, s65
	ds_read_b128 v[180:183], v191 offset:16384
	ds_read_b128 v[194:197], v191 offset:17408
	ds_read_b128 v[198:201], v191 offset:18432
	ds_read_b128 v[202:205], v191 offset:19456
	ds_read_b128 v[206:209], v191 offset:20480
	ds_read_b128 v[210:213], v191 offset:21504
	ds_read_b128 v[214:217], v191 offset:22528
	ds_read_b128 v[218:221], v191 offset:23552
	global_load_lds_dwordx4 v154, s[36:37]
	s_add_i32 m0, s65, 0x2000
	s_add_u32 s66, s36, 0xb0000
	s_addc_u32 s67, s37, 0
	s_add_i32 s65, s43, s15
	global_load_lds_dwordx4 v158, s[36:37]
	s_mov_b32 m0, s65
	global_load_lds_dwordx4 v154, s[66:67]
	s_add_i32 m0, s65, 0x2000
	s_nop 0
	global_load_lds_dwordx4 v158, s[66:67]
	s_mov_b32 m0, s16
	s_nop 0
	global_load_lds_dwordx4 v152, s[38:39]
	s_mov_b32 m0, s17
	s_nop 0
	global_load_lds_dwordx4 v156, s[38:39]
	s_add_u32 s98, s36, s24
	s_addc_u32 s99, s37, s25
	s_add_u32 s100, s38, s24
	s_addc_u32 s101, s39, s25
	s_waitcnt vmcnt(8)
	s_waitcnt lgkmcnt(0)
	s_barrier
	s_waitcnt lgkmcnt(0)
	v_mfma_f32_16x16x32_bf16 v[60:63], v[128:131], v[180:183], 0
	v_mfma_f32_16x16x32_bf16 v[56:59], v[136:139], v[180:183], 0
	v_mfma_f32_16x16x32_bf16 v[44:47], v[128:131], v[198:201], 0
	v_mfma_f32_16x16x32_bf16 v[40:43], v[136:139], v[198:201], 0
	v_mfma_f32_16x16x32_bf16 v[28:31], v[128:131], v[206:209], 0
	v_mfma_f32_16x16x32_bf16 v[24:27], v[136:139], v[206:209], 0
	v_mfma_f32_16x16x32_bf16 v[12:15], v[128:131], v[214:217], 0
	v_mfma_f32_16x16x32_bf16 v[8:11], v[136:139], v[214:217], 0
	v_mfma_f32_16x16x32_bf16 v[60:63], v[132:135], v[194:197], v[60:63]
	v_mfma_f32_16x16x32_bf16 v[56:59], v[140:143], v[194:197], v[56:59]
	v_mfma_f32_16x16x32_bf16 v[44:47], v[132:135], v[202:205], v[44:47]
	v_mfma_f32_16x16x32_bf16 v[40:43], v[140:143], v[202:205], v[40:43]
	v_mfma_f32_16x16x32_bf16 v[28:31], v[132:135], v[210:213], v[28:31]
	v_mfma_f32_16x16x32_bf16 v[24:27], v[140:143], v[210:213], v[24:27]
	v_mfma_f32_16x16x32_bf16 v[12:15], v[132:135], v[218:221], v[12:15]
	v_mfma_f32_16x16x32_bf16 v[8:11], v[140:143], v[218:221], v[8:11]
	v_mfma_f32_16x16x32_bf16 v[52:55], v[144:147], v[180:183], 0
	v_mfma_f32_16x16x32_bf16 v[48:51], v[172:175], v[180:183], 0
	v_mfma_f32_16x16x32_bf16 v[36:39], v[144:147], v[198:201], 0
	v_mfma_f32_16x16x32_bf16 v[32:35], v[172:175], v[198:201], 0
	v_mfma_f32_16x16x32_bf16 v[20:23], v[144:147], v[206:209], 0
	v_mfma_f32_16x16x32_bf16 v[16:19], v[172:175], v[206:209], 0
	v_mfma_f32_16x16x32_bf16 v[4:7], v[144:147], v[214:217], 0
	v_mfma_f32_16x16x32_bf16 v[0:3], v[172:175], v[214:217], 0
	v_mfma_f32_16x16x32_bf16 v[52:55], v[148:151], v[194:197], v[52:55]
	v_mfma_f32_16x16x32_bf16 v[48:51], v[176:179], v[194:197], v[48:51]
	v_mfma_f32_16x16x32_bf16 v[36:39], v[148:151], v[202:205], v[36:39]
	v_mfma_f32_16x16x32_bf16 v[32:35], v[176:179], v[202:205], v[32:35]
	v_mfma_f32_16x16x32_bf16 v[20:23], v[148:151], v[210:213], v[20:23]
	v_mfma_f32_16x16x32_bf16 v[16:19], v[176:179], v[210:213], v[16:19]
	v_mfma_f32_16x16x32_bf16 v[4:7], v[148:151], v[218:221], v[4:7]
	v_mfma_f32_16x16x32_bf16 v[0:3], v[176:179], v[218:221], v[0:3]
	s_barrier
	s_add_i32 s65, 0, 0x18000
	s_add_i32 s66, 0, 0x1c000
	v_add_u32_e32 v140, s65, v186
	v_add_u32_e32 v176, s66, v186
	ds_read_b128 v[128:131], v140
	ds_read_b128 v[132:135], v140 offset:1024
	ds_read_b128 v[136:139], v140 offset:2048
	ds_read_b128 v[140:143], v140 offset:3072
	ds_read_b128 v[144:147], v176
	ds_read_b128 v[148:151], v176 offset:1024
	ds_read_b128 v[172:175], v176 offset:2048
	ds_read_b128 v[176:179], v176 offset:3072
	s_add_u32 s38, s38, 0xb0000
	s_addc_u32 s39, s39, 0
	s_mov_b32 m0, s18
	ds_read_b128 v[180:183], v191 offset:32768
	ds_read_b128 v[194:197], v191 offset:33792
	ds_read_b128 v[198:201], v191 offset:34816
	ds_read_b128 v[202:205], v191 offset:35840
	ds_read_b128 v[206:209], v191 offset:36864
	ds_read_b128 v[210:213], v191 offset:37888
	ds_read_b128 v[214:217], v191 offset:38912
	ds_read_b128 v[218:221], v191 offset:39936
	global_load_lds_dwordx4 v152, s[38:39]
	s_mov_b32 m0, s19
	s_nop 0
	global_load_lds_dwordx4 v156, s[38:39]
	s_waitcnt vmcnt(8)
	s_waitcnt lgkmcnt(0)
	s_barrier
	s_waitcnt lgkmcnt(0)
	v_mfma_f32_16x16x32_bf16 v[124:127], v[128:131], v[180:183], v[124:127]
	v_mfma_f32_16x16x32_bf16 v[120:123], v[136:139], v[180:183], v[120:123]
	v_mfma_f32_16x16x32_bf16 v[108:111], v[128:131], v[198:201], v[108:111]
	v_mfma_f32_16x16x32_bf16 v[104:107], v[136:139], v[198:201], v[104:107]
	v_mfma_f32_16x16x32_bf16 v[92:95], v[128:131], v[206:209], v[92:95]
	v_mfma_f32_16x16x32_bf16 v[88:91], v[136:139], v[206:209], v[88:91]
	v_mfma_f32_16x16x32_bf16 v[76:79], v[128:131], v[214:217], v[76:79]
	v_mfma_f32_16x16x32_bf16 v[72:75], v[136:139], v[214:217], v[72:75]
	v_mfma_f32_16x16x32_bf16 v[124:127], v[132:135], v[194:197], v[124:127]
	v_mfma_f32_16x16x32_bf16 v[120:123], v[140:143], v[194:197], v[120:123]
	v_mfma_f32_16x16x32_bf16 v[108:111], v[132:135], v[202:205], v[108:111]
	v_mfma_f32_16x16x32_bf16 v[104:107], v[140:143], v[202:205], v[104:107]
	v_mfma_f32_16x16x32_bf16 v[92:95], v[132:135], v[210:213], v[92:95]
	v_mfma_f32_16x16x32_bf16 v[88:91], v[140:143], v[210:213], v[88:91]
	v_mfma_f32_16x16x32_bf16 v[76:79], v[132:135], v[218:221], v[76:79]
	v_mfma_f32_16x16x32_bf16 v[72:75], v[140:143], v[218:221], v[72:75]
	v_mfma_f32_16x16x32_bf16 v[116:119], v[144:147], v[180:183], v[116:119]
	v_mfma_f32_16x16x32_bf16 v[112:115], v[172:175], v[180:183], v[112:115]
	v_mfma_f32_16x16x32_bf16 v[100:103], v[144:147], v[198:201], v[100:103]
	v_mfma_f32_16x16x32_bf16 v[96:99], v[172:175], v[198:201], v[96:99]
	v_mfma_f32_16x16x32_bf16 v[84:87], v[144:147], v[206:209], v[84:87]
	v_mfma_f32_16x16x32_bf16 v[80:83], v[172:175], v[206:209], v[80:83]
	v_mfma_f32_16x16x32_bf16 v[68:71], v[144:147], v[214:217], v[68:71]
	v_mfma_f32_16x16x32_bf16 v[64:67], v[172:175], v[214:217], v[64:67]
	v_mfma_f32_16x16x32_bf16 v[116:119], v[148:151], v[194:197], v[116:119]
	v_mfma_f32_16x16x32_bf16 v[112:115], v[176:179], v[194:197], v[112:115]
	v_mfma_f32_16x16x32_bf16 v[100:103], v[148:151], v[202:205], v[100:103]
	v_mfma_f32_16x16x32_bf16 v[96:99], v[176:179], v[202:205], v[96:99]
	v_mfma_f32_16x16x32_bf16 v[84:87], v[148:151], v[210:213], v[84:87]
	v_mfma_f32_16x16x32_bf16 v[80:83], v[176:179], v[210:213], v[80:83]
	v_mfma_f32_16x16x32_bf16 v[68:71], v[148:151], v[218:221], v[68:71]
	v_mfma_f32_16x16x32_bf16 v[64:67], v[176:179], v[218:221], v[64:67]
	s_barrier
	s_add_i32 s38, s65, s15
	s_mov_b32 m0, s38
	ds_read_b128 v[180:183], v191 offset:49152
	ds_read_b128 v[194:197], v191 offset:50176
	ds_read_b128 v[198:201], v191 offset:51200
	ds_read_b128 v[202:205], v191 offset:52224
	ds_read_b128 v[206:209], v191 offset:53248
	ds_read_b128 v[210:213], v191 offset:54272
	ds_read_b128 v[214:217], v191 offset:55296
	ds_read_b128 v[218:221], v191 offset:56320
	global_load_lds_dwordx4 v154, s[98:99]
	s_add_i32 m0, s38, 0x2000
	s_add_u32 s36, s36, 0xb0080
	s_addc_u32 s37, s37, 0
	s_add_i32 s38, s66, s15
	global_load_lds_dwordx4 v158, s[98:99]
	s_mov_b32 m0, s38
	s_nop 0
	global_load_lds_dwordx4 v154, s[36:37]
	s_add_i32 m0, s38, 0x2000
	s_nop 0
	global_load_lds_dwordx4 v158, s[36:37]
	s_mov_b32 m0, s21
	s_nop 0
	global_load_lds_dwordx4 v152, s[100:101]
	s_mov_b32 m0, s22
	s_nop 0
	global_load_lds_dwordx4 v156, s[100:101]
	s_waitcnt vmcnt(8)
	s_waitcnt lgkmcnt(0)
	s_barrier
	s_waitcnt lgkmcnt(0)
	v_mfma_f32_16x16x32_bf16 v[60:63], v[128:131], v[180:183], v[60:63]
	v_mfma_f32_16x16x32_bf16 v[56:59], v[136:139], v[180:183], v[56:59]
	v_mfma_f32_16x16x32_bf16 v[44:47], v[128:131], v[198:201], v[44:47]
	v_mfma_f32_16x16x32_bf16 v[40:43], v[136:139], v[198:201], v[40:43]
	v_mfma_f32_16x16x32_bf16 v[28:31], v[128:131], v[206:209], v[28:31]
	v_mfma_f32_16x16x32_bf16 v[24:27], v[136:139], v[206:209], v[24:27]
	v_mfma_f32_16x16x32_bf16 v[12:15], v[128:131], v[214:217], v[12:15]
	v_mfma_f32_16x16x32_bf16 v[8:11], v[136:139], v[214:217], v[8:11]
	v_mfma_f32_16x16x32_bf16 v[60:63], v[132:135], v[194:197], v[60:63]
	v_mfma_f32_16x16x32_bf16 v[56:59], v[140:143], v[194:197], v[56:59]
	v_mfma_f32_16x16x32_bf16 v[44:47], v[132:135], v[202:205], v[44:47]
	v_mfma_f32_16x16x32_bf16 v[40:43], v[140:143], v[202:205], v[40:43]
	v_mfma_f32_16x16x32_bf16 v[28:31], v[132:135], v[210:213], v[28:31]
	v_mfma_f32_16x16x32_bf16 v[24:27], v[140:143], v[210:213], v[24:27]
	v_mfma_f32_16x16x32_bf16 v[12:15], v[132:135], v[218:221], v[12:15]
	v_mfma_f32_16x16x32_bf16 v[8:11], v[140:143], v[218:221], v[8:11]
	v_mfma_f32_16x16x32_bf16 v[52:55], v[144:147], v[180:183], v[52:55]
	v_mfma_f32_16x16x32_bf16 v[48:51], v[172:175], v[180:183], v[48:51]
	v_mfma_f32_16x16x32_bf16 v[36:39], v[144:147], v[198:201], v[36:39]
	v_mfma_f32_16x16x32_bf16 v[32:35], v[172:175], v[198:201], v[32:35]
	v_mfma_f32_16x16x32_bf16 v[20:23], v[144:147], v[206:209], v[20:23]
	v_mfma_f32_16x16x32_bf16 v[16:19], v[172:175], v[206:209], v[16:19]
	v_mfma_f32_16x16x32_bf16 v[4:7], v[144:147], v[214:217], v[4:7]
	v_mfma_f32_16x16x32_bf16 v[0:3], v[172:175], v[214:217], v[0:3]
	v_mfma_f32_16x16x32_bf16 v[52:55], v[148:151], v[194:197], v[52:55]
	v_mfma_f32_16x16x32_bf16 v[48:51], v[176:179], v[194:197], v[48:51]
	v_mfma_f32_16x16x32_bf16 v[36:39], v[148:151], v[202:205], v[36:39]
	v_mfma_f32_16x16x32_bf16 v[32:35], v[176:179], v[202:205], v[32:35]
	v_mfma_f32_16x16x32_bf16 v[20:23], v[148:151], v[210:213], v[20:23]
	v_mfma_f32_16x16x32_bf16 v[16:19], v[176:179], v[210:213], v[16:19]
	v_mfma_f32_16x16x32_bf16 v[4:7], v[148:151], v[218:221], v[4:7]
	v_mfma_f32_16x16x32_bf16 v[0:3], v[176:179], v[218:221], v[0:3]
	s_barrier
	s_add_i32 s64, s64, 2
	s_add_u32 s34, s34, 0x100
	s_addc_u32 s35, s35, 0
	s_add_u32 s31, s31, 0x100
	s_addc_u32 s63, s63, 0
	s_cmp_gt_u32 s64, 41
	s_cbranch_scc1 .Lpeel_exit_1324

.Lpeel_exit_1324:
	s_and_b64 vcc, exec, s[26:27]
	s_cbranch_vccz .LBB0_1327
	s_barrier

.LBB0_1412:
	s_ashr_i32 s27, s26, 31
	s_lshl_b64 s[14:15], s[26:27], 19
	s_add_u32 s30, s82, s14
	s_addc_u32 s31, s83, s15
	s_and_b64 s[14:15], s[4:5], exec
	s_cselect_b32 s14, s31, s39
	s_cselect_b32 s15, s30, s38
	s_ashr_i32 s29, s28, 31
	s_lshl_b64 s[16:17], s[28:29], 19
	s_add_u32 s34, s6, s16
	s_addc_u32 s35, s7, s17
	s_and_b64 s[16:17], s[4:5], exec
	s_cselect_b32 s16, s35, s41
	s_cselect_b32 s17, s34, s40
	s_add_u32 s38, s38, 0x40080
	s_addc_u32 s39, s39, 0
	s_add_u32 s18, s40, 0x100
	s_addc_u32 s19, s41, 0
	s_mov_b32 s20, -2
	ds_read_b128 v[128:131], v171
	ds_read_b128 v[132:135], v171 offset:1024
	ds_read_b128 v[178:181], v171 offset:2048
	ds_read_b128 v[186:189], v171 offset:3072
	ds_read_b128 v[190:193], v173
	ds_read_b128 v[194:197], v173 offset:1024
	ds_read_b128 v[198:201], v173 offset:2048
	ds_read_b128 v[202:205], v173 offset:3072
	s_add_u32 s21, s38, 0xfffc0080
	s_addc_u32 s22, s39, -1
	s_cmp_eq_u32 s20, 12
	s_cselect_b32 s43, s14, s22
	s_cselect_b32 s42, s15, s21
	s_cselect_b32 s41, s16, s19
	s_cselect_b32 s40, s17, s18
	s_add_i32 m0, s37, 0xc000
	ds_read_b128 v[206:209], v175
	ds_read_b128 v[210:213], v175 offset:1024
	ds_read_b128 v[214:217], v175 offset:2048
	ds_read_b128 v[218:221], v175 offset:3072
	ds_read_b128 v[222:225], v175 offset:4096
	ds_read_b128 v[226:229], v175 offset:5120
	ds_read_b128 v[230:233], v175 offset:6144
	ds_read_b128 v[234:237], v175 offset:7168
	global_load_lds_dwordx4 v152, s[38:39]
	s_add_i32 m0, s37, 0xe000
	s_nop 0
	global_load_lds_dwordx4 v154, s[38:39]
	s_waitcnt vmcnt(8)
	s_waitcnt lgkmcnt(0)
	s_barrier
	s_waitcnt lgkmcnt(0)
	v_mfma_f32_16x16x32_bf16 v[124:127], v[128:131], v[206:209], 0
	v_mfma_f32_16x16x32_bf16 v[120:123], v[178:181], v[206:209], 0
	v_mfma_f32_16x16x32_bf16 v[108:111], v[128:131], v[214:217], 0
	v_mfma_f32_16x16x32_bf16 v[100:103], v[178:181], v[214:217], 0
	v_mfma_f32_16x16x32_bf16 v[92:95], v[128:131], v[222:225], 0
	v_mfma_f32_16x16x32_bf16 v[84:87], v[178:181], v[222:225], 0
	v_mfma_f32_16x16x32_bf16 v[76:79], v[128:131], v[230:233], 0
	v_mfma_f32_16x16x32_bf16 v[68:71], v[178:181], v[230:233], 0
	v_mfma_f32_16x16x32_bf16 v[124:127], v[132:135], v[210:213], v[124:127]
	v_mfma_f32_16x16x32_bf16 v[120:123], v[186:189], v[210:213], v[120:123]
	v_mfma_f32_16x16x32_bf16 v[108:111], v[132:135], v[218:221], v[108:111]
	v_mfma_f32_16x16x32_bf16 v[100:103], v[186:189], v[218:221], v[100:103]
	v_mfma_f32_16x16x32_bf16 v[92:95], v[132:135], v[226:229], v[92:95]
	v_mfma_f32_16x16x32_bf16 v[84:87], v[186:189], v[226:229], v[84:87]
	v_mfma_f32_16x16x32_bf16 v[76:79], v[132:135], v[234:237], v[76:79]
	v_mfma_f32_16x16x32_bf16 v[68:71], v[186:189], v[234:237], v[68:71]
	v_mfma_f32_16x16x32_bf16 v[116:119], v[190:193], v[206:209], 0
	v_mfma_f32_16x16x32_bf16 v[112:115], v[198:201], v[206:209], 0
	v_mfma_f32_16x16x32_bf16 v[104:107], v[190:193], v[214:217], 0
	v_mfma_f32_16x16x32_bf16 v[96:99], v[198:201], v[214:217], 0
	v_mfma_f32_16x16x32_bf16 v[88:91], v[190:193], v[222:225], 0
	v_mfma_f32_16x16x32_bf16 v[80:83], v[198:201], v[222:225], 0
	v_mfma_f32_16x16x32_bf16 v[72:75], v[190:193], v[230:233], 0
	v_mfma_f32_16x16x32_bf16 v[64:67], v[198:201], v[230:233], 0
	v_mfma_f32_16x16x32_bf16 v[116:119], v[194:197], v[210:213], v[116:119]
	v_mfma_f32_16x16x32_bf16 v[112:115], v[202:205], v[210:213], v[112:115]
	v_mfma_f32_16x16x32_bf16 v[104:107], v[194:197], v[218:221], v[104:107]
	v_mfma_f32_16x16x32_bf16 v[96:99], v[202:205], v[218:221], v[96:99]
	v_mfma_f32_16x16x32_bf16 v[88:91], v[194:197], v[226:229], v[88:91]
	v_mfma_f32_16x16x32_bf16 v[80:83], v[202:205], v[226:229], v[80:83]
	v_mfma_f32_16x16x32_bf16 v[72:75], v[194:197], v[234:237], v[72:75]
	v_mfma_f32_16x16x32_bf16 v[64:67], v[202:205], v[234:237], v[64:67]
	s_barrier
	s_add_i32 s21, s44, s60
	s_mov_b32 m0, s21
	ds_read_b128 v[206:209], v175 offset:16384
	ds_read_b128 v[210:213], v175 offset:17408
	ds_read_b128 v[214:217], v175 offset:18432
	ds_read_b128 v[218:221], v175 offset:19456
	ds_read_b128 v[222:225], v175 offset:20480
	ds_read_b128 v[226:229], v175 offset:21504
	ds_read_b128 v[230:233], v175 offset:22528
	ds_read_b128 v[234:237], v175 offset:23552
	global_load_lds_dwordx4 v140, s[40:41]
	s_add_i32 m0, s21, 0x2000
	s_add_u32 s22, s40, 0x40000
	s_addc_u32 s23, s41, 0
	s_add_i32 s21, s45, s60
	global_load_lds_dwordx4 v136, s[40:41]
	s_mov_b32 m0, s21
	global_load_lds_dwordx4 v140, s[22:23]
	s_add_i32 m0, s21, 0x2000
	s_nop 0
	global_load_lds_dwordx4 v136, s[22:23]
	s_mov_b32 m0, s37
	s_nop 0
	global_load_lds_dwordx4 v142, s[42:43]
	s_mov_b32 m0, s63
	s_nop 0
	global_load_lds_dwordx4 v138, s[42:43]
	s_add_u32 s98, s40, s12
	s_addc_u32 s99, s41, s13
	s_add_u32 s100, s42, s12
	s_addc_u32 s101, s43, s13
	s_waitcnt vmcnt(8)
	s_waitcnt lgkmcnt(0)
	s_barrier
	s_waitcnt lgkmcnt(0)
	v_mfma_f32_16x16x32_bf16 v[60:63], v[128:131], v[206:209], 0
	v_mfma_f32_16x16x32_bf16 v[52:55], v[178:181], v[206:209], 0
	v_mfma_f32_16x16x32_bf16 v[44:47], v[128:131], v[214:217], 0
	v_mfma_f32_16x16x32_bf16 v[36:39], v[178:181], v[214:217], 0
	v_mfma_f32_16x16x32_bf16 v[28:31], v[128:131], v[222:225], 0
	v_mfma_f32_16x16x32_bf16 v[20:23], v[178:181], v[222:225], 0
	v_mfma_f32_16x16x32_bf16 v[12:15], v[128:131], v[230:233], 0
	v_mfma_f32_16x16x32_bf16 v[4:7], v[178:181], v[230:233], 0
	v_mfma_f32_16x16x32_bf16 v[60:63], v[132:135], v[210:213], v[60:63]
	v_mfma_f32_16x16x32_bf16 v[52:55], v[186:189], v[210:213], v[52:55]
	v_mfma_f32_16x16x32_bf16 v[44:47], v[132:135], v[218:221], v[44:47]
	v_mfma_f32_16x16x32_bf16 v[36:39], v[186:189], v[218:221], v[36:39]
	v_mfma_f32_16x16x32_bf16 v[28:31], v[132:135], v[226:229], v[28:31]
	v_mfma_f32_16x16x32_bf16 v[20:23], v[186:189], v[226:229], v[20:23]
	v_mfma_f32_16x16x32_bf16 v[12:15], v[132:135], v[234:237], v[12:15]
	v_mfma_f32_16x16x32_bf16 v[4:7], v[186:189], v[234:237], v[4:7]
	v_mfma_f32_16x16x32_bf16 v[56:59], v[190:193], v[206:209], 0
	v_mfma_f32_16x16x32_bf16 v[48:51], v[198:201], v[206:209], 0
	v_mfma_f32_16x16x32_bf16 v[40:43], v[190:193], v[214:217], 0
	v_mfma_f32_16x16x32_bf16 v[32:35], v[198:201], v[214:217], 0
	v_mfma_f32_16x16x32_bf16 v[24:27], v[190:193], v[222:225], 0
	v_mfma_f32_16x16x32_bf16 v[16:19], v[198:201], v[222:225], 0
	v_mfma_f32_16x16x32_bf16 v[8:11], v[190:193], v[230:233], 0
	v_mfma_f32_16x16x32_bf16 v[0:3], v[198:201], v[230:233], 0
	v_mfma_f32_16x16x32_bf16 v[56:59], v[194:197], v[210:213], v[56:59]
	v_mfma_f32_16x16x32_bf16 v[48:51], v[202:205], v[210:213], v[48:51]
	v_mfma_f32_16x16x32_bf16 v[40:43], v[194:197], v[218:221], v[40:43]
	v_mfma_f32_16x16x32_bf16 v[32:35], v[202:205], v[218:221], v[32:35]
	v_mfma_f32_16x16x32_bf16 v[24:27], v[194:197], v[226:229], v[24:27]
	v_mfma_f32_16x16x32_bf16 v[16:19], v[202:205], v[226:229], v[16:19]
	v_mfma_f32_16x16x32_bf16 v[8:11], v[194:197], v[234:237], v[8:11]
	v_mfma_f32_16x16x32_bf16 v[0:3], v[202:205], v[234:237], v[0:3]
	s_barrier
	s_add_i32 s21, 0, 0x18000
	v_add_u32_e32 v144, s21, v165
	s_add_i32 s27, 0, 0x1c000
	ds_read_b128 v[128:131], v144
	ds_read_b128 v[132:135], v144 offset:1024
	ds_read_b128 v[178:181], v144 offset:2048
	ds_read_b128 v[186:189], v144 offset:3072
	v_add_u32_e32 v144, s27, v165
	ds_read_b128 v[190:193], v144
	ds_read_b128 v[194:197], v144 offset:1024
	ds_read_b128 v[198:201], v144 offset:2048
	ds_read_b128 v[202:205], v144 offset:3072
	s_add_u32 s22, s42, 0x40000
	s_addc_u32 s23, s43, 0
	s_mov_b32 m0, s64
	ds_read_b128 v[206:209], v175 offset:32768
	ds_read_b128 v[210:213], v175 offset:33792
	ds_read_b128 v[214:217], v175 offset:34816
	ds_read_b128 v[218:221], v175 offset:35840
	ds_read_b128 v[222:225], v175 offset:36864
	ds_read_b128 v[226:229], v175 offset:37888
	ds_read_b128 v[230:233], v175 offset:38912
	ds_read_b128 v[234:237], v175 offset:39936
	global_load_lds_dwordx4 v142, s[22:23]
	s_mov_b32 m0, s65
	s_nop 0
	global_load_lds_dwordx4 v138, s[22:23]
	s_waitcnt vmcnt(8)
	s_waitcnt lgkmcnt(0)
	s_barrier
	s_waitcnt lgkmcnt(0)
	v_mfma_f32_16x16x32_bf16 v[124:127], v[128:131], v[206:209], v[124:127]
	v_mfma_f32_16x16x32_bf16 v[120:123], v[178:181], v[206:209], v[120:123]
	v_mfma_f32_16x16x32_bf16 v[108:111], v[128:131], v[214:217], v[108:111]
	v_mfma_f32_16x16x32_bf16 v[100:103], v[178:181], v[214:217], v[100:103]
	v_mfma_f32_16x16x32_bf16 v[92:95], v[128:131], v[222:225], v[92:95]
	v_mfma_f32_16x16x32_bf16 v[84:87], v[178:181], v[222:225], v[84:87]
	v_mfma_f32_16x16x32_bf16 v[76:79], v[128:131], v[230:233], v[76:79]
	v_mfma_f32_16x16x32_bf16 v[68:71], v[178:181], v[230:233], v[68:71]
	v_mfma_f32_16x16x32_bf16 v[124:127], v[132:135], v[210:213], v[124:127]
	v_mfma_f32_16x16x32_bf16 v[120:123], v[186:189], v[210:213], v[120:123]
	v_mfma_f32_16x16x32_bf16 v[108:111], v[132:135], v[218:221], v[108:111]
	v_mfma_f32_16x16x32_bf16 v[100:103], v[186:189], v[218:221], v[100:103]
	v_mfma_f32_16x16x32_bf16 v[92:95], v[132:135], v[226:229], v[92:95]
	v_mfma_f32_16x16x32_bf16 v[84:87], v[186:189], v[226:229], v[84:87]
	v_mfma_f32_16x16x32_bf16 v[76:79], v[132:135], v[234:237], v[76:79]
	v_mfma_f32_16x16x32_bf16 v[68:71], v[186:189], v[234:237], v[68:71]
	v_mfma_f32_16x16x32_bf16 v[116:119], v[190:193], v[206:209], v[116:119]
	v_mfma_f32_16x16x32_bf16 v[112:115], v[198:201], v[206:209], v[112:115]
	v_mfma_f32_16x16x32_bf16 v[104:107], v[190:193], v[214:217], v[104:107]
	v_mfma_f32_16x16x32_bf16 v[96:99], v[198:201], v[214:217], v[96:99]
	v_mfma_f32_16x16x32_bf16 v[88:91], v[190:193], v[222:225], v[88:91]
	v_mfma_f32_16x16x32_bf16 v[80:83], v[198:201], v[222:225], v[80:83]
	v_mfma_f32_16x16x32_bf16 v[72:75], v[190:193], v[230:233], v[72:75]
	v_mfma_f32_16x16x32_bf16 v[64:67], v[198:201], v[230:233], v[64:67]
	v_mfma_f32_16x16x32_bf16 v[116:119], v[194:197], v[210:213], v[116:119]
	v_mfma_f32_16x16x32_bf16 v[112:115], v[202:205], v[210:213], v[112:115]
	v_mfma_f32_16x16x32_bf16 v[104:107], v[194:197], v[218:221], v[104:107]
	v_mfma_f32_16x16x32_bf16 v[96:99], v[202:205], v[218:221], v[96:99]
	v_mfma_f32_16x16x32_bf16 v[88:91], v[194:197], v[226:229], v[88:91]
	v_mfma_f32_16x16x32_bf16 v[80:83], v[202:205], v[226:229], v[80:83]
	v_mfma_f32_16x16x32_bf16 v[72:75], v[194:197], v[234:237], v[72:75]
	v_mfma_f32_16x16x32_bf16 v[64:67], v[202:205], v[234:237], v[64:67]
	s_barrier
	s_add_i32 s21, s21, s60
	s_mov_b32 m0, s21
	ds_read_b128 v[206:209], v175 offset:49152
	ds_read_b128 v[210:213], v175 offset:50176
	ds_read_b128 v[214:217], v175 offset:51200
	ds_read_b128 v[218:221], v175 offset:52224
	ds_read_b128 v[222:225], v175 offset:53248
	ds_read_b128 v[226:229], v175 offset:54272
	ds_read_b128 v[230:233], v175 offset:55296
	ds_read_b128 v[234:237], v175 offset:56320
	global_load_lds_dwordx4 v140, s[98:99]
	s_add_i32 m0, s21, 0x2000
	s_add_u32 s22, s40, 0x40080
	s_addc_u32 s23, s41, 0
	s_add_i32 s21, s27, s60
	global_load_lds_dwordx4 v136, s[98:99]
	s_mov_b32 m0, s21
	s_nop 0
	global_load_lds_dwordx4 v140, s[22:23]
	s_add_i32 m0, s21, 0x2000
	s_nop 0
	global_load_lds_dwordx4 v136, s[22:23]
	s_mov_b32 m0, s67
	s_nop 0
	global_load_lds_dwordx4 v142, s[100:101]
	s_mov_b32 m0, s70
	s_nop 0
	global_load_lds_dwordx4 v138, s[100:101]
	s_waitcnt vmcnt(8)
	s_waitcnt lgkmcnt(0)
	s_barrier
	s_waitcnt lgkmcnt(0)
	v_mfma_f32_16x16x32_bf16 v[60:63], v[128:131], v[206:209], v[60:63]
	v_mfma_f32_16x16x32_bf16 v[52:55], v[178:181], v[206:209], v[52:55]
	v_mfma_f32_16x16x32_bf16 v[44:47], v[128:131], v[214:217], v[44:47]
	v_mfma_f32_16x16x32_bf16 v[36:39], v[178:181], v[214:217], v[36:39]
	v_mfma_f32_16x16x32_bf16 v[28:31], v[128:131], v[222:225], v[28:31]
	v_mfma_f32_16x16x32_bf16 v[20:23], v[178:181], v[222:225], v[20:23]
	v_mfma_f32_16x16x32_bf16 v[12:15], v[128:131], v[230:233], v[12:15]
	v_mfma_f32_16x16x32_bf16 v[4:7], v[178:181], v[230:233], v[4:7]
	v_mfma_f32_16x16x32_bf16 v[60:63], v[132:135], v[210:213], v[60:63]
	v_mfma_f32_16x16x32_bf16 v[52:55], v[186:189], v[210:213], v[52:55]
	v_mfma_f32_16x16x32_bf16 v[44:47], v[132:135], v[218:221], v[44:47]
	v_mfma_f32_16x16x32_bf16 v[36:39], v[186:189], v[218:221], v[36:39]
	v_mfma_f32_16x16x32_bf16 v[28:31], v[132:135], v[226:229], v[28:31]
	v_mfma_f32_16x16x32_bf16 v[20:23], v[186:189], v[226:229], v[20:23]
	v_mfma_f32_16x16x32_bf16 v[12:15], v[132:135], v[234:237], v[12:15]
	v_mfma_f32_16x16x32_bf16 v[4:7], v[186:189], v[234:237], v[4:7]
	v_mfma_f32_16x16x32_bf16 v[56:59], v[190:193], v[206:209], v[56:59]
	v_mfma_f32_16x16x32_bf16 v[48:51], v[198:201], v[206:209], v[48:51]
	v_mfma_f32_16x16x32_bf16 v[40:43], v[190:193], v[214:217], v[40:43]
	v_mfma_f32_16x16x32_bf16 v[32:35], v[198:201], v[214:217], v[32:35]
	v_mfma_f32_16x16x32_bf16 v[24:27], v[190:193], v[222:225], v[24:27]
	v_mfma_f32_16x16x32_bf16 v[16:19], v[198:201], v[222:225], v[16:19]
	v_mfma_f32_16x16x32_bf16 v[8:11], v[190:193], v[230:233], v[8:11]
	v_mfma_f32_16x16x32_bf16 v[0:3], v[198:201], v[230:233], v[0:3]
	v_mfma_f32_16x16x32_bf16 v[56:59], v[194:197], v[210:213], v[56:59]
	v_mfma_f32_16x16x32_bf16 v[48:51], v[202:205], v[210:213], v[48:51]
	v_mfma_f32_16x16x32_bf16 v[40:43], v[194:197], v[218:221], v[40:43]
	v_mfma_f32_16x16x32_bf16 v[32:35], v[202:205], v[218:221], v[32:35]
	v_mfma_f32_16x16x32_bf16 v[24:27], v[194:197], v[226:229], v[24:27]
	v_mfma_f32_16x16x32_bf16 v[16:19], v[202:205], v[226:229], v[16:19]
	v_mfma_f32_16x16x32_bf16 v[8:11], v[194:197], v[234:237], v[8:11]
	v_mfma_f32_16x16x32_bf16 v[0:3], v[202:205], v[234:237], v[0:3]
	s_barrier
	s_add_i32 s20, s20, 2
	s_add_u32 s38, s38, 0x100
	s_addc_u32 s39, s39, 0
	s_add_u32 s18, s18, 0x100
	s_addc_u32 s19, s19, 0
	s_cmp_gt_u32 s20, 13
	s_cbranch_scc1 .Lpeel_exit_1413
.LBB0_1413:
	ds_read_b128 v[128:131], v171
	ds_read_b128 v[132:135], v171 offset:1024
	ds_read_b128 v[178:181], v171 offset:2048
	ds_read_b128 v[186:189], v171 offset:3072
	ds_read_b128 v[190:193], v173
	ds_read_b128 v[194:197], v173 offset:1024
	ds_read_b128 v[198:201], v173 offset:2048
	ds_read_b128 v[202:205], v173 offset:3072
	s_add_u32 s21, s38, 0xfffc0080
	s_addc_u32 s22, s39, -1
	s_cmp_eq_u32 s20, 12
	s_cselect_b32 s43, s14, s22
	s_cselect_b32 s42, s15, s21
	s_cselect_b32 s41, s16, s19
	s_cselect_b32 s40, s17, s18
	s_add_i32 m0, s37, 0xc000
	ds_read_b128 v[206:209], v175
	ds_read_b128 v[210:213], v175 offset:1024
	ds_read_b128 v[214:217], v175 offset:2048
	ds_read_b128 v[218:221], v175 offset:3072
	ds_read_b128 v[222:225], v175 offset:4096
	ds_read_b128 v[226:229], v175 offset:5120
	ds_read_b128 v[230:233], v175 offset:6144
	ds_read_b128 v[234:237], v175 offset:7168
	global_load_lds_dwordx4 v152, s[38:39]
	s_add_i32 m0, s37, 0xe000
	s_nop 0
	global_load_lds_dwordx4 v154, s[38:39]
	s_waitcnt vmcnt(8)
	s_waitcnt lgkmcnt(0)
	s_barrier
	s_waitcnt lgkmcnt(0)
	v_mfma_f32_16x16x32_bf16 v[124:127], v[128:131], v[206:209], v[124:127]
	v_mfma_f32_16x16x32_bf16 v[120:123], v[178:181], v[206:209], v[120:123]
	v_mfma_f32_16x16x32_bf16 v[108:111], v[128:131], v[214:217], v[108:111]
	v_mfma_f32_16x16x32_bf16 v[100:103], v[178:181], v[214:217], v[100:103]
	v_mfma_f32_16x16x32_bf16 v[92:95], v[128:131], v[222:225], v[92:95]
	v_mfma_f32_16x16x32_bf16 v[84:87], v[178:181], v[222:225], v[84:87]
	v_mfma_f32_16x16x32_bf16 v[76:79], v[128:131], v[230:233], v[76:79]
	v_mfma_f32_16x16x32_bf16 v[68:71], v[178:181], v[230:233], v[68:71]
	v_mfma_f32_16x16x32_bf16 v[124:127], v[132:135], v[210:213], v[124:127]
	v_mfma_f32_16x16x32_bf16 v[120:123], v[186:189], v[210:213], v[120:123]
	v_mfma_f32_16x16x32_bf16 v[108:111], v[132:135], v[218:221], v[108:111]
	v_mfma_f32_16x16x32_bf16 v[100:103], v[186:189], v[218:221], v[100:103]
	v_mfma_f32_16x16x32_bf16 v[92:95], v[132:135], v[226:229], v[92:95]
	v_mfma_f32_16x16x32_bf16 v[84:87], v[186:189], v[226:229], v[84:87]
	v_mfma_f32_16x16x32_bf16 v[76:79], v[132:135], v[234:237], v[76:79]
	v_mfma_f32_16x16x32_bf16 v[68:71], v[186:189], v[234:237], v[68:71]
	v_mfma_f32_16x16x32_bf16 v[116:119], v[190:193], v[206:209], v[116:119]
	v_mfma_f32_16x16x32_bf16 v[112:115], v[198:201], v[206:209], v[112:115]
	v_mfma_f32_16x16x32_bf16 v[104:107], v[190:193], v[214:217], v[104:107]
	v_mfma_f32_16x16x32_bf16 v[96:99], v[198:201], v[214:217], v[96:99]
	v_mfma_f32_16x16x32_bf16 v[88:91], v[190:193], v[222:225], v[88:91]
	v_mfma_f32_16x16x32_bf16 v[80:83], v[198:201], v[222:225], v[80:83]
	v_mfma_f32_16x16x32_bf16 v[72:75], v[190:193], v[230:233], v[72:75]
	v_mfma_f32_16x16x32_bf16 v[64:67], v[198:201], v[230:233], v[64:67]
	v_mfma_f32_16x16x32_bf16 v[116:119], v[194:197], v[210:213], v[116:119]
	v_mfma_f32_16x16x32_bf16 v[112:115], v[202:205], v[210:213], v[112:115]
	v_mfma_f32_16x16x32_bf16 v[104:107], v[194:197], v[218:221], v[104:107]
	v_mfma_f32_16x16x32_bf16 v[96:99], v[202:205], v[218:221], v[96:99]
	v_mfma_f32_16x16x32_bf16 v[88:91], v[194:197], v[226:229], v[88:91]
	v_mfma_f32_16x16x32_bf16 v[80:83], v[202:205], v[226:229], v[80:83]
	v_mfma_f32_16x16x32_bf16 v[72:75], v[194:197], v[234:237], v[72:75]
	v_mfma_f32_16x16x32_bf16 v[64:67], v[202:205], v[234:237], v[64:67]
	s_barrier
	s_add_i32 s21, s44, s60
	s_mov_b32 m0, s21
	ds_read_b128 v[206:209], v175 offset:16384
	ds_read_b128 v[210:213], v175 offset:17408
	ds_read_b128 v[214:217], v175 offset:18432
	ds_read_b128 v[218:221], v175 offset:19456
	ds_read_b128 v[222:225], v175 offset:20480
	ds_read_b128 v[226:229], v175 offset:21504
	ds_read_b128 v[230:233], v175 offset:22528
	ds_read_b128 v[234:237], v175 offset:23552
	global_load_lds_dwordx4 v140, s[40:41]
	s_add_i32 m0, s21, 0x2000
	s_add_u32 s22, s40, 0x40000
	s_addc_u32 s23, s41, 0
	s_add_i32 s21, s45, s60
	global_load_lds_dwordx4 v136, s[40:41]
	s_mov_b32 m0, s21
	global_load_lds_dwordx4 v140, s[22:23]
	s_add_i32 m0, s21, 0x2000
	s_nop 0
	global_load_lds_dwordx4 v136, s[22:23]
	s_mov_b32 m0, s37
	s_nop 0
	global_load_lds_dwordx4 v142, s[42:43]
	s_mov_b32 m0, s63
	s_nop 0
	global_load_lds_dwordx4 v138, s[42:43]
	s_add_u32 s98, s40, s12
	s_addc_u32 s99, s41, s13
	s_add_u32 s100, s42, s12
	s_addc_u32 s101, s43, s13
	s_waitcnt vmcnt(8)
	s_waitcnt lgkmcnt(0)
	s_barrier
	s_waitcnt lgkmcnt(0)
	v_mfma_f32_16x16x32_bf16 v[60:63], v[128:131], v[206:209], v[60:63]
	v_mfma_f32_16x16x32_bf16 v[52:55], v[178:181], v[206:209], v[52:55]
	v_mfma_f32_16x16x32_bf16 v[44:47], v[128:131], v[214:217], v[44:47]
	v_mfma_f32_16x16x32_bf16 v[36:39], v[178:181], v[214:217], v[36:39]
	v_mfma_f32_16x16x32_bf16 v[28:31], v[128:131], v[222:225], v[28:31]
	v_mfma_f32_16x16x32_bf16 v[20:23], v[178:181], v[222:225], v[20:23]
	v_mfma_f32_16x16x32_bf16 v[12:15], v[128:131], v[230:233], v[12:15]
	v_mfma_f32_16x16x32_bf16 v[4:7], v[178:181], v[230:233], v[4:7]
	v_mfma_f32_16x16x32_bf16 v[60:63], v[132:135], v[210:213], v[60:63]
	v_mfma_f32_16x16x32_bf16 v[52:55], v[186:189], v[210:213], v[52:55]
	v_mfma_f32_16x16x32_bf16 v[44:47], v[132:135], v[218:221], v[44:47]
	v_mfma_f32_16x16x32_bf16 v[36:39], v[186:189], v[218:221], v[36:39]
	v_mfma_f32_16x16x32_bf16 v[28:31], v[132:135], v[226:229], v[28:31]
	v_mfma_f32_16x16x32_bf16 v[20:23], v[186:189], v[226:229], v[20:23]
	v_mfma_f32_16x16x32_bf16 v[12:15], v[132:135], v[234:237], v[12:15]
	v_mfma_f32_16x16x32_bf16 v[4:7], v[186:189], v[234:237], v[4:7]
	v_mfma_f32_16x16x32_bf16 v[56:59], v[190:193], v[206:209], v[56:59]
	v_mfma_f32_16x16x32_bf16 v[48:51], v[198:201], v[206:209], v[48:51]
	v_mfma_f32_16x16x32_bf16 v[40:43], v[190:193], v[214:217], v[40:43]
	v_mfma_f32_16x16x32_bf16 v[32:35], v[198:201], v[214:217], v[32:35]
	v_mfma_f32_16x16x32_bf16 v[24:27], v[190:193], v[222:225], v[24:27]
	v_mfma_f32_16x16x32_bf16 v[16:19], v[198:201], v[222:225], v[16:19]
	v_mfma_f32_16x16x32_bf16 v[8:11], v[190:193], v[230:233], v[8:11]
	v_mfma_f32_16x16x32_bf16 v[0:3], v[198:201], v[230:233], v[0:3]
	v_mfma_f32_16x16x32_bf16 v[56:59], v[194:197], v[210:213], v[56:59]
	v_mfma_f32_16x16x32_bf16 v[48:51], v[202:205], v[210:213], v[48:51]
	v_mfma_f32_16x16x32_bf16 v[40:43], v[194:197], v[218:221], v[40:43]
	v_mfma_f32_16x16x32_bf16 v[32:35], v[202:205], v[218:221], v[32:35]
	v_mfma_f32_16x16x32_bf16 v[24:27], v[194:197], v[226:229], v[24:27]
	v_mfma_f32_16x16x32_bf16 v[16:19], v[202:205], v[226:229], v[16:19]
	v_mfma_f32_16x16x32_bf16 v[8:11], v[194:197], v[234:237], v[8:11]
	v_mfma_f32_16x16x32_bf16 v[0:3], v[202:205], v[234:237], v[0:3]
	s_barrier
	s_add_i32 s21, 0, 0x18000
	v_add_u32_e32 v144, s21, v165
	s_add_i32 s27, 0, 0x1c000
	ds_read_b128 v[128:131], v144
	ds_read_b128 v[132:135], v144 offset:1024
	ds_read_b128 v[178:181], v144 offset:2048
	ds_read_b128 v[186:189], v144 offset:3072
	v_add_u32_e32 v144, s27, v165
	ds_read_b128 v[190:193], v144
	ds_read_b128 v[194:197], v144 offset:1024
	ds_read_b128 v[198:201], v144 offset:2048
	ds_read_b128 v[202:205], v144 offset:3072
	s_add_u32 s22, s42, 0x40000
	s_addc_u32 s23, s43, 0
	s_mov_b32 m0, s64
	ds_read_b128 v[206:209], v175 offset:32768
	ds_read_b128 v[210:213], v175 offset:33792
	ds_read_b128 v[214:217], v175 offset:34816
	ds_read_b128 v[218:221], v175 offset:35840
	ds_read_b128 v[222:225], v175 offset:36864
	ds_read_b128 v[226:229], v175 offset:37888
	ds_read_b128 v[230:233], v175 offset:38912
	ds_read_b128 v[234:237], v175 offset:39936
	global_load_lds_dwordx4 v142, s[22:23]
	s_mov_b32 m0, s65
	s_nop 0
	global_load_lds_dwordx4 v138, s[22:23]
	s_waitcnt vmcnt(8)
	s_waitcnt lgkmcnt(0)
	s_barrier
	s_waitcnt lgkmcnt(0)
	v_mfma_f32_16x16x32_bf16 v[124:127], v[128:131], v[206:209], v[124:127]
	v_mfma_f32_16x16x32_bf16 v[120:123], v[178:181], v[206:209], v[120:123]
	v_mfma_f32_16x16x32_bf16 v[108:111], v[128:131], v[214:217], v[108:111]
	v_mfma_f32_16x16x32_bf16 v[100:103], v[178:181], v[214:217], v[100:103]
	v_mfma_f32_16x16x32_bf16 v[92:95], v[128:131], v[222:225], v[92:95]
	v_mfma_f32_16x16x32_bf16 v[84:87], v[178:181], v[222:225], v[84:87]
	v_mfma_f32_16x16x32_bf16 v[76:79], v[128:131], v[230:233], v[76:79]
	v_mfma_f32_16x16x32_bf16 v[68:71], v[178:181], v[230:233], v[68:71]
	v_mfma_f32_16x16x32_bf16 v[124:127], v[132:135], v[210:213], v[124:127]
	v_mfma_f32_16x16x32_bf16 v[120:123], v[186:189], v[210:213], v[120:123]
	v_mfma_f32_16x16x32_bf16 v[108:111], v[132:135], v[218:221], v[108:111]
	v_mfma_f32_16x16x32_bf16 v[100:103], v[186:189], v[218:221], v[100:103]
	v_mfma_f32_16x16x32_bf16 v[92:95], v[132:135], v[226:229], v[92:95]
	v_mfma_f32_16x16x32_bf16 v[84:87], v[186:189], v[226:229], v[84:87]
	v_mfma_f32_16x16x32_bf16 v[76:79], v[132:135], v[234:237], v[76:79]
	v_mfma_f32_16x16x32_bf16 v[68:71], v[186:189], v[234:237], v[68:71]
	v_mfma_f32_16x16x32_bf16 v[116:119], v[190:193], v[206:209], v[116:119]
	v_mfma_f32_16x16x32_bf16 v[112:115], v[198:201], v[206:209], v[112:115]
	v_mfma_f32_16x16x32_bf16 v[104:107], v[190:193], v[214:217], v[104:107]
	v_mfma_f32_16x16x32_bf16 v[96:99], v[198:201], v[214:217], v[96:99]
	v_mfma_f32_16x16x32_bf16 v[88:91], v[190:193], v[222:225], v[88:91]
	v_mfma_f32_16x16x32_bf16 v[80:83], v[198:201], v[222:225], v[80:83]
	v_mfma_f32_16x16x32_bf16 v[72:75], v[190:193], v[230:233], v[72:75]
	v_mfma_f32_16x16x32_bf16 v[64:67], v[198:201], v[230:233], v[64:67]
	v_mfma_f32_16x16x32_bf16 v[116:119], v[194:197], v[210:213], v[116:119]
	v_mfma_f32_16x16x32_bf16 v[112:115], v[202:205], v[210:213], v[112:115]
	v_mfma_f32_16x16x32_bf16 v[104:107], v[194:197], v[218:221], v[104:107]
	v_mfma_f32_16x16x32_bf16 v[96:99], v[202:205], v[218:221], v[96:99]
	v_mfma_f32_16x16x32_bf16 v[88:91], v[194:197], v[226:229], v[88:91]
	v_mfma_f32_16x16x32_bf16 v[80:83], v[202:205], v[226:229], v[80:83]
	v_mfma_f32_16x16x32_bf16 v[72:75], v[194:197], v[234:237], v[72:75]
	v_mfma_f32_16x16x32_bf16 v[64:67], v[202:205], v[234:237], v[64:67]
	s_barrier
	s_add_i32 s21, s21, s60
	s_mov_b32 m0, s21
	ds_read_b128 v[206:209], v175 offset:49152
	ds_read_b128 v[210:213], v175 offset:50176
	ds_read_b128 v[214:217], v175 offset:51200
	ds_read_b128 v[218:221], v175 offset:52224
	ds_read_b128 v[222:225], v175 offset:53248
	ds_read_b128 v[226:229], v175 offset:54272
	ds_read_b128 v[230:233], v175 offset:55296
	ds_read_b128 v[234:237], v175 offset:56320
	global_load_lds_dwordx4 v140, s[98:99]
	s_add_i32 m0, s21, 0x2000
	s_add_u32 s22, s40, 0x40080
	s_addc_u32 s23, s41, 0
	s_add_i32 s21, s27, s60
	global_load_lds_dwordx4 v136, s[98:99]
	s_mov_b32 m0, s21
	s_nop 0
	global_load_lds_dwordx4 v140, s[22:23]
	s_add_i32 m0, s21, 0x2000
	s_nop 0
	global_load_lds_dwordx4 v136, s[22:23]
	s_mov_b32 m0, s67
	s_nop 0
	global_load_lds_dwordx4 v142, s[100:101]
	s_mov_b32 m0, s70
	s_nop 0
	global_load_lds_dwordx4 v138, s[100:101]
	s_waitcnt vmcnt(8)
	s_waitcnt lgkmcnt(0)
	s_barrier
	s_waitcnt lgkmcnt(0)
	v_mfma_f32_16x16x32_bf16 v[60:63], v[128:131], v[206:209], v[60:63]
	v_mfma_f32_16x16x32_bf16 v[52:55], v[178:181], v[206:209], v[52:55]
	v_mfma_f32_16x16x32_bf16 v[44:47], v[128:131], v[214:217], v[44:47]
	v_mfma_f32_16x16x32_bf16 v[36:39], v[178:181], v[214:217], v[36:39]
	v_mfma_f32_16x16x32_bf16 v[28:31], v[128:131], v[222:225], v[28:31]
	v_mfma_f32_16x16x32_bf16 v[20:23], v[178:181], v[222:225], v[20:23]
	v_mfma_f32_16x16x32_bf16 v[12:15], v[128:131], v[230:233], v[12:15]
	v_mfma_f32_16x16x32_bf16 v[4:7], v[178:181], v[230:233], v[4:7]
	v_mfma_f32_16x16x32_bf16 v[60:63], v[132:135], v[210:213], v[60:63]
	v_mfma_f32_16x16x32_bf16 v[52:55], v[186:189], v[210:213], v[52:55]
	v_mfma_f32_16x16x32_bf16 v[44:47], v[132:135], v[218:221], v[44:47]
	v_mfma_f32_16x16x32_bf16 v[36:39], v[186:189], v[218:221], v[36:39]
	v_mfma_f32_16x16x32_bf16 v[28:31], v[132:135], v[226:229], v[28:31]
	v_mfma_f32_16x16x32_bf16 v[20:23], v[186:189], v[226:229], v[20:23]
	v_mfma_f32_16x16x32_bf16 v[12:15], v[132:135], v[234:237], v[12:15]
	v_mfma_f32_16x16x32_bf16 v[4:7], v[186:189], v[234:237], v[4:7]
	v_mfma_f32_16x16x32_bf16 v[56:59], v[190:193], v[206:209], v[56:59]
	v_mfma_f32_16x16x32_bf16 v[48:51], v[198:201], v[206:209], v[48:51]
	v_mfma_f32_16x16x32_bf16 v[40:43], v[190:193], v[214:217], v[40:43]
	v_mfma_f32_16x16x32_bf16 v[32:35], v[198:201], v[214:217], v[32:35]
	v_mfma_f32_16x16x32_bf16 v[24:27], v[190:193], v[222:225], v[24:27]
	v_mfma_f32_16x16x32_bf16 v[16:19], v[198:201], v[222:225], v[16:19]
	v_mfma_f32_16x16x32_bf16 v[8:11], v[190:193], v[230:233], v[8:11]
	v_mfma_f32_16x16x32_bf16 v[0:3], v[198:201], v[230:233], v[0:3]
	v_mfma_f32_16x16x32_bf16 v[56:59], v[194:197], v[210:213], v[56:59]
	v_mfma_f32_16x16x32_bf16 v[48:51], v[202:205], v[210:213], v[48:51]
	v_mfma_f32_16x16x32_bf16 v[40:43], v[194:197], v[218:221], v[40:43]
	v_mfma_f32_16x16x32_bf16 v[32:35], v[202:205], v[218:221], v[32:35]
	v_mfma_f32_16x16x32_bf16 v[24:27], v[194:197], v[226:229], v[24:27]
	v_mfma_f32_16x16x32_bf16 v[16:19], v[202:205], v[226:229], v[16:19]
	v_mfma_f32_16x16x32_bf16 v[8:11], v[194:197], v[234:237], v[8:11]
	v_mfma_f32_16x16x32_bf16 v[0:3], v[202:205], v[234:237], v[0:3]
	s_barrier
	s_add_i32 s20, s20, 2
	s_add_u32 s38, s38, 0x100
	s_addc_u32 s39, s39, 0
	s_add_u32 s18, s18, 0x100
	s_addc_u32 s19, s19, 0
	s_cmp_gt_u32 s20, 13
	s_cbranch_scc0 .LBB0_1413
.Lpeel_exit_1413:
	s_and_b64 vcc, exec, s[24:25]
	s_cbranch_vccz .LBB0_1418
	s_barrier
	s_cmp_lt_i32 s80, 8
	s_mov_b64 s[38:39], -1
	s_cbranch_scc1 .LBB0_1419

.LBB0_1629:
	s_add_u32 s22, s22, 0xb0080
	s_addc_u32 s23, s23, 0
	s_add_u32 s21, s24, 0x100
	s_addc_u32 s47, s25, 0
	s_mov_b32 s50, -2
	s_waitcnt lgkmcnt(0)
	ds_read_b128 v[128:131], v189
	ds_read_b128 v[132:135], v189 offset:1024
	ds_read_b128 v[136:139], v189 offset:2048
	ds_read_b128 v[140:143], v189 offset:3072
	ds_read_b128 v[144:147], v190
	ds_read_b128 v[148:151], v190 offset:1024
	ds_read_b128 v[172:175], v190 offset:2048
	ds_read_b128 v[176:179], v190 offset:3072
	s_add_u32 s24, s22, 0xfff50080
	s_addc_u32 s25, s23, -1
	s_cmp_eq_u32 s50, 40
	s_cselect_b32 s27, s1, s25
	s_cselect_b32 s26, s0, s24
	s_cselect_b32 s25, s19, s47
	s_cselect_b32 s24, s18, s21
	s_add_i32 m0, s30, 0xc000
	ds_read_b128 v[180:183], v191
	ds_read_b128 v[194:197], v191 offset:1024
	ds_read_b128 v[198:201], v191 offset:2048
	ds_read_b128 v[202:205], v191 offset:3072
	ds_read_b128 v[206:209], v191 offset:4096
	ds_read_b128 v[210:213], v191 offset:5120
	ds_read_b128 v[214:217], v191 offset:6144
	ds_read_b128 v[218:221], v191 offset:7168
	global_load_lds_dwordx4 v164, s[22:23]
	s_add_i32 m0, s30, 0xe000
	s_nop 0
	global_load_lds_dwordx4 v166, s[22:23]
	s_waitcnt vmcnt(8)
	s_waitcnt lgkmcnt(0)
	s_barrier
	s_waitcnt lgkmcnt(0)
	v_mfma_f32_16x16x32_bf16 v[124:127], v[128:131], v[180:183], 0
	v_mfma_f32_16x16x32_bf16 v[120:123], v[136:139], v[180:183], 0
	v_mfma_f32_16x16x32_bf16 v[108:111], v[128:131], v[198:201], 0
	v_mfma_f32_16x16x32_bf16 v[104:107], v[136:139], v[198:201], 0
	v_mfma_f32_16x16x32_bf16 v[92:95], v[128:131], v[206:209], 0
	v_mfma_f32_16x16x32_bf16 v[88:91], v[136:139], v[206:209], 0
	v_mfma_f32_16x16x32_bf16 v[76:79], v[128:131], v[214:217], 0
	v_mfma_f32_16x16x32_bf16 v[72:75], v[136:139], v[214:217], 0
	v_mfma_f32_16x16x32_bf16 v[124:127], v[132:135], v[194:197], v[124:127]
	v_mfma_f32_16x16x32_bf16 v[120:123], v[140:143], v[194:197], v[120:123]
	v_mfma_f32_16x16x32_bf16 v[108:111], v[132:135], v[202:205], v[108:111]
	v_mfma_f32_16x16x32_bf16 v[104:107], v[140:143], v[202:205], v[104:107]
	v_mfma_f32_16x16x32_bf16 v[92:95], v[132:135], v[210:213], v[92:95]
	v_mfma_f32_16x16x32_bf16 v[88:91], v[140:143], v[210:213], v[88:91]
	v_mfma_f32_16x16x32_bf16 v[76:79], v[132:135], v[218:221], v[76:79]
	v_mfma_f32_16x16x32_bf16 v[72:75], v[140:143], v[218:221], v[72:75]
	v_mfma_f32_16x16x32_bf16 v[116:119], v[144:147], v[180:183], 0
	v_mfma_f32_16x16x32_bf16 v[112:115], v[172:175], v[180:183], 0
	v_mfma_f32_16x16x32_bf16 v[100:103], v[144:147], v[198:201], 0
	v_mfma_f32_16x16x32_bf16 v[96:99], v[172:175], v[198:201], 0
	v_mfma_f32_16x16x32_bf16 v[84:87], v[144:147], v[206:209], 0
	v_mfma_f32_16x16x32_bf16 v[80:83], v[172:175], v[206:209], 0
	v_mfma_f32_16x16x32_bf16 v[68:71], v[144:147], v[214:217], 0
	v_mfma_f32_16x16x32_bf16 v[64:67], v[172:175], v[214:217], 0
	v_mfma_f32_16x16x32_bf16 v[116:119], v[148:151], v[194:197], v[116:119]
	v_mfma_f32_16x16x32_bf16 v[112:115], v[176:179], v[194:197], v[112:115]
	v_mfma_f32_16x16x32_bf16 v[100:103], v[148:151], v[202:205], v[100:103]
	v_mfma_f32_16x16x32_bf16 v[96:99], v[176:179], v[202:205], v[96:99]
	v_mfma_f32_16x16x32_bf16 v[84:87], v[148:151], v[210:213], v[84:87]
	v_mfma_f32_16x16x32_bf16 v[80:83], v[176:179], v[210:213], v[80:83]
	v_mfma_f32_16x16x32_bf16 v[68:71], v[148:151], v[218:221], v[68:71]
	v_mfma_f32_16x16x32_bf16 v[64:67], v[176:179], v[218:221], v[64:67]
	s_barrier
	s_add_i32 s51, s42, s29
	s_mov_b32 m0, s51
	ds_read_b128 v[180:183], v191 offset:16384
	ds_read_b128 v[194:197], v191 offset:17408
	ds_read_b128 v[198:201], v191 offset:18432
	ds_read_b128 v[202:205], v191 offset:19456
	ds_read_b128 v[206:209], v191 offset:20480
	ds_read_b128 v[210:213], v191 offset:21504
	ds_read_b128 v[214:217], v191 offset:22528
	ds_read_b128 v[218:221], v191 offset:23552
	global_load_lds_dwordx4 v154, s[24:25]
	s_add_i32 m0, s51, 0x2000
	s_add_u32 s52, s24, 0xb0000
	s_addc_u32 s53, s25, 0
	s_add_i32 s51, s43, s29
	global_load_lds_dwordx4 v158, s[24:25]
	s_mov_b32 m0, s51
	global_load_lds_dwordx4 v154, s[52:53]
	s_add_i32 m0, s51, 0x2000
	s_nop 0
	global_load_lds_dwordx4 v158, s[52:53]
	s_mov_b32 m0, s30
	s_nop 0
	global_load_lds_dwordx4 v152, s[26:27]
	s_mov_b32 m0, s31
	s_nop 0
	global_load_lds_dwordx4 v156, s[26:27]
	s_add_u32 s98, s24, s14
	s_addc_u32 s99, s25, s15
	s_add_u32 s100, s26, s14
	s_addc_u32 s101, s27, s15
	s_waitcnt vmcnt(8)
	s_waitcnt lgkmcnt(0)
	s_barrier
	s_waitcnt lgkmcnt(0)
	v_mfma_f32_16x16x32_bf16 v[60:63], v[128:131], v[180:183], 0
	v_mfma_f32_16x16x32_bf16 v[56:59], v[136:139], v[180:183], 0
	v_mfma_f32_16x16x32_bf16 v[44:47], v[128:131], v[198:201], 0
	v_mfma_f32_16x16x32_bf16 v[40:43], v[136:139], v[198:201], 0
	v_mfma_f32_16x16x32_bf16 v[28:31], v[128:131], v[206:209], 0
	v_mfma_f32_16x16x32_bf16 v[24:27], v[136:139], v[206:209], 0
	v_mfma_f32_16x16x32_bf16 v[12:15], v[128:131], v[214:217], 0
	v_mfma_f32_16x16x32_bf16 v[8:11], v[136:139], v[214:217], 0
	v_mfma_f32_16x16x32_bf16 v[60:63], v[132:135], v[194:197], v[60:63]
	v_mfma_f32_16x16x32_bf16 v[56:59], v[140:143], v[194:197], v[56:59]
	v_mfma_f32_16x16x32_bf16 v[44:47], v[132:135], v[202:205], v[44:47]
	v_mfma_f32_16x16x32_bf16 v[40:43], v[140:143], v[202:205], v[40:43]
	v_mfma_f32_16x16x32_bf16 v[28:31], v[132:135], v[210:213], v[28:31]
	v_mfma_f32_16x16x32_bf16 v[24:27], v[140:143], v[210:213], v[24:27]
	v_mfma_f32_16x16x32_bf16 v[12:15], v[132:135], v[218:221], v[12:15]
	v_mfma_f32_16x16x32_bf16 v[8:11], v[140:143], v[218:221], v[8:11]
	v_mfma_f32_16x16x32_bf16 v[52:55], v[144:147], v[180:183], 0
	v_mfma_f32_16x16x32_bf16 v[48:51], v[172:175], v[180:183], 0
	v_mfma_f32_16x16x32_bf16 v[36:39], v[144:147], v[198:201], 0
	v_mfma_f32_16x16x32_bf16 v[32:35], v[172:175], v[198:201], 0
	v_mfma_f32_16x16x32_bf16 v[20:23], v[144:147], v[206:209], 0
	v_mfma_f32_16x16x32_bf16 v[16:19], v[172:175], v[206:209], 0
	v_mfma_f32_16x16x32_bf16 v[4:7], v[144:147], v[214:217], 0
	v_mfma_f32_16x16x32_bf16 v[0:3], v[172:175], v[214:217], 0
	v_mfma_f32_16x16x32_bf16 v[52:55], v[148:151], v[194:197], v[52:55]
	v_mfma_f32_16x16x32_bf16 v[48:51], v[176:179], v[194:197], v[48:51]
	v_mfma_f32_16x16x32_bf16 v[36:39], v[148:151], v[202:205], v[36:39]
	v_mfma_f32_16x16x32_bf16 v[32:35], v[176:179], v[202:205], v[32:35]
	v_mfma_f32_16x16x32_bf16 v[20:23], v[148:151], v[210:213], v[20:23]
	v_mfma_f32_16x16x32_bf16 v[16:19], v[176:179], v[210:213], v[16:19]
	v_mfma_f32_16x16x32_bf16 v[4:7], v[148:151], v[218:221], v[4:7]
	v_mfma_f32_16x16x32_bf16 v[0:3], v[176:179], v[218:221], v[0:3]
	s_barrier
	s_add_i32 s51, 0, 0x18000
	s_add_i32 s52, 0, 0x1c000
	v_add_u32_e32 v140, s51, v186
	v_add_u32_e32 v176, s52, v186
	ds_read_b128 v[128:131], v140
	ds_read_b128 v[132:135], v140 offset:1024
	ds_read_b128 v[136:139], v140 offset:2048
	ds_read_b128 v[140:143], v140 offset:3072
	ds_read_b128 v[144:147], v176
	ds_read_b128 v[148:151], v176 offset:1024
	ds_read_b128 v[172:175], v176 offset:2048
	ds_read_b128 v[176:179], v176 offset:3072
	s_add_u32 s26, s26, 0xb0000
	s_addc_u32 s27, s27, 0
	s_mov_b32 m0, s34
	ds_read_b128 v[180:183], v191 offset:32768
	ds_read_b128 v[194:197], v191 offset:33792
	ds_read_b128 v[198:201], v191 offset:34816
	ds_read_b128 v[202:205], v191 offset:35840
	ds_read_b128 v[206:209], v191 offset:36864
	ds_read_b128 v[210:213], v191 offset:37888
	ds_read_b128 v[214:217], v191 offset:38912
	ds_read_b128 v[218:221], v191 offset:39936
	global_load_lds_dwordx4 v152, s[26:27]
	s_mov_b32 m0, s35
	s_nop 0
	global_load_lds_dwordx4 v156, s[26:27]
	s_waitcnt vmcnt(8)
	s_waitcnt lgkmcnt(0)
	s_barrier
	s_waitcnt lgkmcnt(0)
	v_mfma_f32_16x16x32_bf16 v[124:127], v[128:131], v[180:183], v[124:127]
	v_mfma_f32_16x16x32_bf16 v[120:123], v[136:139], v[180:183], v[120:123]
	v_mfma_f32_16x16x32_bf16 v[108:111], v[128:131], v[198:201], v[108:111]
	v_mfma_f32_16x16x32_bf16 v[104:107], v[136:139], v[198:201], v[104:107]
	v_mfma_f32_16x16x32_bf16 v[92:95], v[128:131], v[206:209], v[92:95]
	v_mfma_f32_16x16x32_bf16 v[88:91], v[136:139], v[206:209], v[88:91]
	v_mfma_f32_16x16x32_bf16 v[76:79], v[128:131], v[214:217], v[76:79]
	v_mfma_f32_16x16x32_bf16 v[72:75], v[136:139], v[214:217], v[72:75]
	v_mfma_f32_16x16x32_bf16 v[124:127], v[132:135], v[194:197], v[124:127]
	v_mfma_f32_16x16x32_bf16 v[120:123], v[140:143], v[194:197], v[120:123]
	v_mfma_f32_16x16x32_bf16 v[108:111], v[132:135], v[202:205], v[108:111]
	v_mfma_f32_16x16x32_bf16 v[104:107], v[140:143], v[202:205], v[104:107]
	v_mfma_f32_16x16x32_bf16 v[92:95], v[132:135], v[210:213], v[92:95]
	v_mfma_f32_16x16x32_bf16 v[88:91], v[140:143], v[210:213], v[88:91]
	v_mfma_f32_16x16x32_bf16 v[76:79], v[132:135], v[218:221], v[76:79]
	v_mfma_f32_16x16x32_bf16 v[72:75], v[140:143], v[218:221], v[72:75]
	v_mfma_f32_16x16x32_bf16 v[116:119], v[144:147], v[180:183], v[116:119]
	v_mfma_f32_16x16x32_bf16 v[112:115], v[172:175], v[180:183], v[112:115]
	v_mfma_f32_16x16x32_bf16 v[100:103], v[144:147], v[198:201], v[100:103]
	v_mfma_f32_16x16x32_bf16 v[96:99], v[172:175], v[198:201], v[96:99]
	v_mfma_f32_16x16x32_bf16 v[84:87], v[144:147], v[206:209], v[84:87]
	v_mfma_f32_16x16x32_bf16 v[80:83], v[172:175], v[206:209], v[80:83]
	v_mfma_f32_16x16x32_bf16 v[68:71], v[144:147], v[214:217], v[68:71]
	v_mfma_f32_16x16x32_bf16 v[64:67], v[172:175], v[214:217], v[64:67]
	v_mfma_f32_16x16x32_bf16 v[116:119], v[148:151], v[194:197], v[116:119]
	v_mfma_f32_16x16x32_bf16 v[112:115], v[176:179], v[194:197], v[112:115]
	v_mfma_f32_16x16x32_bf16 v[100:103], v[148:151], v[202:205], v[100:103]
	v_mfma_f32_16x16x32_bf16 v[96:99], v[176:179], v[202:205], v[96:99]
	v_mfma_f32_16x16x32_bf16 v[84:87], v[148:151], v[210:213], v[84:87]
	v_mfma_f32_16x16x32_bf16 v[80:83], v[176:179], v[210:213], v[80:83]
	v_mfma_f32_16x16x32_bf16 v[68:71], v[148:151], v[218:221], v[68:71]
	v_mfma_f32_16x16x32_bf16 v[64:67], v[176:179], v[218:221], v[64:67]
	s_barrier
	s_add_i32 s26, s51, s29
	s_mov_b32 m0, s26
	ds_read_b128 v[180:183], v191 offset:49152
	ds_read_b128 v[194:197], v191 offset:50176
	ds_read_b128 v[198:201], v191 offset:51200
	ds_read_b128 v[202:205], v191 offset:52224
	ds_read_b128 v[206:209], v191 offset:53248
	ds_read_b128 v[210:213], v191 offset:54272
	ds_read_b128 v[214:217], v191 offset:55296
	ds_read_b128 v[218:221], v191 offset:56320
	global_load_lds_dwordx4 v154, s[98:99]
	s_add_i32 m0, s26, 0x2000
	s_add_u32 s24, s24, 0xb0080
	s_addc_u32 s25, s25, 0
	s_add_i32 s26, s52, s29
	global_load_lds_dwordx4 v158, s[98:99]
	s_mov_b32 m0, s26
	s_nop 0
	global_load_lds_dwordx4 v154, s[24:25]
	s_add_i32 m0, s26, 0x2000
	s_nop 0
	global_load_lds_dwordx4 v158, s[24:25]
	s_mov_b32 m0, s37
	s_nop 0
	global_load_lds_dwordx4 v152, s[100:101]
	s_mov_b32 m0, s38
	s_nop 0
	global_load_lds_dwordx4 v156, s[100:101]
	s_waitcnt vmcnt(8)
	s_waitcnt lgkmcnt(0)
	s_barrier
	s_waitcnt lgkmcnt(0)
	v_mfma_f32_16x16x32_bf16 v[60:63], v[128:131], v[180:183], v[60:63]
	v_mfma_f32_16x16x32_bf16 v[56:59], v[136:139], v[180:183], v[56:59]
	v_mfma_f32_16x16x32_bf16 v[44:47], v[128:131], v[198:201], v[44:47]
	v_mfma_f32_16x16x32_bf16 v[40:43], v[136:139], v[198:201], v[40:43]
	v_mfma_f32_16x16x32_bf16 v[28:31], v[128:131], v[206:209], v[28:31]
	v_mfma_f32_16x16x32_bf16 v[24:27], v[136:139], v[206:209], v[24:27]
	v_mfma_f32_16x16x32_bf16 v[12:15], v[128:131], v[214:217], v[12:15]
	v_mfma_f32_16x16x32_bf16 v[8:11], v[136:139], v[214:217], v[8:11]
	v_mfma_f32_16x16x32_bf16 v[60:63], v[132:135], v[194:197], v[60:63]
	v_mfma_f32_16x16x32_bf16 v[56:59], v[140:143], v[194:197], v[56:59]
	v_mfma_f32_16x16x32_bf16 v[44:47], v[132:135], v[202:205], v[44:47]
	v_mfma_f32_16x16x32_bf16 v[40:43], v[140:143], v[202:205], v[40:43]
	v_mfma_f32_16x16x32_bf16 v[28:31], v[132:135], v[210:213], v[28:31]
	v_mfma_f32_16x16x32_bf16 v[24:27], v[140:143], v[210:213], v[24:27]
	v_mfma_f32_16x16x32_bf16 v[12:15], v[132:135], v[218:221], v[12:15]
	v_mfma_f32_16x16x32_bf16 v[8:11], v[140:143], v[218:221], v[8:11]
	v_mfma_f32_16x16x32_bf16 v[52:55], v[144:147], v[180:183], v[52:55]
	v_mfma_f32_16x16x32_bf16 v[48:51], v[172:175], v[180:183], v[48:51]
	v_mfma_f32_16x16x32_bf16 v[36:39], v[144:147], v[198:201], v[36:39]
	v_mfma_f32_16x16x32_bf16 v[32:35], v[172:175], v[198:201], v[32:35]
	v_mfma_f32_16x16x32_bf16 v[20:23], v[144:147], v[206:209], v[20:23]
	v_mfma_f32_16x16x32_bf16 v[16:19], v[172:175], v[206:209], v[16:19]
	v_mfma_f32_16x16x32_bf16 v[4:7], v[144:147], v[214:217], v[4:7]
	v_mfma_f32_16x16x32_bf16 v[0:3], v[172:175], v[214:217], v[0:3]
	v_mfma_f32_16x16x32_bf16 v[52:55], v[148:151], v[194:197], v[52:55]
	v_mfma_f32_16x16x32_bf16 v[48:51], v[176:179], v[194:197], v[48:51]
	v_mfma_f32_16x16x32_bf16 v[36:39], v[148:151], v[202:205], v[36:39]
	v_mfma_f32_16x16x32_bf16 v[32:35], v[176:179], v[202:205], v[32:35]
	v_mfma_f32_16x16x32_bf16 v[20:23], v[148:151], v[210:213], v[20:23]
	v_mfma_f32_16x16x32_bf16 v[16:19], v[176:179], v[210:213], v[16:19]
	v_mfma_f32_16x16x32_bf16 v[4:7], v[148:151], v[218:221], v[4:7]
	v_mfma_f32_16x16x32_bf16 v[0:3], v[176:179], v[218:221], v[0:3]
	s_barrier
	s_add_i32 s50, s50, 2
	s_add_u32 s22, s22, 0x100
	s_addc_u32 s23, s23, 0
	s_add_u32 s21, s21, 0x100
	s_addc_u32 s47, s47, 0
	s_cmp_gt_u32 s50, 41
	s_cbranch_scc1 .Lpeel_exit_1630

.Lpeel_exit_1630:
	s_and_b64 vcc, exec, s[16:17]
	s_cbranch_vccz .LBB0_1633
	s_barrier

.LBB0_1726:
	s_ashr_i32 s15, s14, 31
	s_lshl_b64 s[18:19], s[14:15], 19
	s_add_u32 s18, s82, s18
	s_addc_u32 s19, s83, s19
	s_and_b64 s[20:21], s[4:5], exec
	s_cselect_b32 s15, s19, s25
	s_cselect_b32 s47, s18, s24
	s_ashr_i32 s17, s16, 31
	s_lshl_b64 s[20:21], s[16:17], 19
	s_add_u32 s20, s30, s20
	s_addc_u32 s21, s31, s21
	s_and_b64 s[28:29], s[4:5], exec
	s_cselect_b32 s17, s21, s27
	s_cselect_b32 s48, s20, s26
	s_add_u32 s24, s24, 0x40080
	s_addc_u32 s25, s25, 0
	s_add_u32 s49, s26, 0x100
	s_addc_u32 s50, s27, 0
	s_mov_b32 s51, -2
	ds_read_b128 v[128:131], v163
	ds_read_b128 v[132:135], v163 offset:1024
	ds_read_b128 v[172:175], v163 offset:2048
	ds_read_b128 v[176:179], v163 offset:3072
	ds_read_b128 v[180:183], v165
	ds_read_b128 v[186:189], v165 offset:1024
	ds_read_b128 v[190:193], v165 offset:2048
	ds_read_b128 v[194:197], v165 offset:3072
	s_add_u32 s26, s24, 0xfffc0080
	s_addc_u32 s27, s25, -1
	s_cmp_eq_u32 s51, 12
	s_cselect_b32 s29, s15, s27
	s_cselect_b32 s28, s47, s26
	s_cselect_b32 s27, s17, s50
	s_cselect_b32 s26, s48, s49
	s_add_i32 m0, s23, 0xc000
	ds_read_b128 v[198:201], v167
	ds_read_b128 v[202:205], v167 offset:1024
	ds_read_b128 v[206:209], v167 offset:2048
	ds_read_b128 v[210:213], v167 offset:3072
	ds_read_b128 v[214:217], v167 offset:4096
	ds_read_b128 v[218:221], v167 offset:5120
	ds_read_b128 v[222:225], v167 offset:6144
	ds_read_b128 v[226:229], v167 offset:7168
	global_load_lds_dwordx4 v148, s[24:25]
	s_add_i32 m0, s23, 0xe000
	s_nop 0
	global_load_lds_dwordx4 v150, s[24:25]
	s_waitcnt vmcnt(8)
	s_waitcnt lgkmcnt(0)
	s_barrier
	s_waitcnt lgkmcnt(0)
	v_mfma_f32_16x16x32_bf16 v[124:127], v[128:131], v[198:201], 0
	v_mfma_f32_16x16x32_bf16 v[120:123], v[172:175], v[198:201], 0
	v_mfma_f32_16x16x32_bf16 v[116:119], v[128:131], v[206:209], 0
	v_mfma_f32_16x16x32_bf16 v[112:115], v[172:175], v[206:209], 0
	v_mfma_f32_16x16x32_bf16 v[108:111], v[128:131], v[214:217], 0
	v_mfma_f32_16x16x32_bf16 v[104:107], v[172:175], v[214:217], 0
	v_mfma_f32_16x16x32_bf16 v[100:103], v[128:131], v[222:225], 0
	v_mfma_f32_16x16x32_bf16 v[96:99], v[172:175], v[222:225], 0
	v_mfma_f32_16x16x32_bf16 v[124:127], v[132:135], v[202:205], v[124:127]
	v_mfma_f32_16x16x32_bf16 v[120:123], v[176:179], v[202:205], v[120:123]
	v_mfma_f32_16x16x32_bf16 v[116:119], v[132:135], v[210:213], v[116:119]
	v_mfma_f32_16x16x32_bf16 v[112:115], v[176:179], v[210:213], v[112:115]
	v_mfma_f32_16x16x32_bf16 v[108:111], v[132:135], v[218:221], v[108:111]
	v_mfma_f32_16x16x32_bf16 v[104:107], v[176:179], v[218:221], v[104:107]
	v_mfma_f32_16x16x32_bf16 v[100:103], v[132:135], v[226:229], v[100:103]
	v_mfma_f32_16x16x32_bf16 v[96:99], v[176:179], v[226:229], v[96:99]
	v_mfma_f32_16x16x32_bf16 v[72:75], v[180:183], v[198:201], 0
	v_mfma_f32_16x16x32_bf16 v[64:67], v[190:193], v[198:201], 0
	v_mfma_f32_16x16x32_bf16 v[56:59], v[180:183], v[206:209], 0
	v_mfma_f32_16x16x32_bf16 v[48:51], v[190:193], v[206:209], 0
	v_mfma_f32_16x16x32_bf16 v[44:47], v[180:183], v[214:217], 0
	v_mfma_f32_16x16x32_bf16 v[40:43], v[190:193], v[214:217], 0
	v_mfma_f32_16x16x32_bf16 v[36:39], v[180:183], v[222:225], 0
	v_mfma_f32_16x16x32_bf16 v[32:35], v[190:193], v[222:225], 0
	v_mfma_f32_16x16x32_bf16 v[72:75], v[186:189], v[202:205], v[72:75]
	v_mfma_f32_16x16x32_bf16 v[64:67], v[194:197], v[202:205], v[64:67]
	v_mfma_f32_16x16x32_bf16 v[56:59], v[186:189], v[210:213], v[56:59]
	v_mfma_f32_16x16x32_bf16 v[48:51], v[194:197], v[210:213], v[48:51]
	v_mfma_f32_16x16x32_bf16 v[44:47], v[186:189], v[218:221], v[44:47]
	v_mfma_f32_16x16x32_bf16 v[40:43], v[194:197], v[218:221], v[40:43]
	v_mfma_f32_16x16x32_bf16 v[36:39], v[186:189], v[226:229], v[36:39]
	v_mfma_f32_16x16x32_bf16 v[32:35], v[194:197], v[226:229], v[32:35]
	s_barrier
	s_add_i32 s52, s44, s34
	s_mov_b32 m0, s52
	ds_read_b128 v[198:201], v167 offset:16384
	ds_read_b128 v[202:205], v167 offset:17408
	ds_read_b128 v[206:209], v167 offset:18432
	ds_read_b128 v[210:213], v167 offset:19456
	ds_read_b128 v[214:217], v167 offset:20480
	ds_read_b128 v[218:221], v167 offset:21504
	ds_read_b128 v[222:225], v167 offset:22528
	ds_read_b128 v[226:229], v167 offset:23552
	global_load_lds_dwordx4 v138, s[26:27]
	s_add_i32 m0, s52, 0x2000
	s_add_u32 s52, s26, 0x40000
	s_addc_u32 s53, s27, 0
	s_add_i32 s54, s45, s34
	global_load_lds_dwordx4 v142, s[26:27]
	s_mov_b32 m0, s54
	global_load_lds_dwordx4 v138, s[52:53]
	s_add_i32 m0, s54, 0x2000
	s_nop 0
	global_load_lds_dwordx4 v142, s[52:53]
	s_mov_b32 m0, s23
	s_nop 0
	global_load_lds_dwordx4 v136, s[28:29]
	s_mov_b32 m0, s35
	s_nop 0
	global_load_lds_dwordx4 v140, s[28:29]
	s_add_u32 s98, s26, s10
	s_addc_u32 s99, s27, s11
	s_add_u32 s100, s28, s10
	s_addc_u32 s101, s29, s11
	s_waitcnt vmcnt(8)
	s_waitcnt lgkmcnt(0)
	s_barrier
	s_waitcnt lgkmcnt(0)
	v_mfma_f32_16x16x32_bf16 v[92:95], v[128:131], v[198:201], 0
	v_mfma_f32_16x16x32_bf16 v[88:91], v[172:175], v[198:201], 0
	v_mfma_f32_16x16x32_bf16 v[84:87], v[128:131], v[206:209], 0
	v_mfma_f32_16x16x32_bf16 v[80:83], v[172:175], v[206:209], 0
	v_mfma_f32_16x16x32_bf16 v[76:79], v[128:131], v[214:217], 0
	v_mfma_f32_16x16x32_bf16 v[68:71], v[172:175], v[214:217], 0
	v_mfma_f32_16x16x32_bf16 v[60:63], v[128:131], v[222:225], 0
	v_mfma_f32_16x16x32_bf16 v[52:55], v[172:175], v[222:225], 0
	v_mfma_f32_16x16x32_bf16 v[92:95], v[132:135], v[202:205], v[92:95]
	v_mfma_f32_16x16x32_bf16 v[88:91], v[176:179], v[202:205], v[88:91]
	v_mfma_f32_16x16x32_bf16 v[84:87], v[132:135], v[210:213], v[84:87]
	v_mfma_f32_16x16x32_bf16 v[80:83], v[176:179], v[210:213], v[80:83]
	v_mfma_f32_16x16x32_bf16 v[76:79], v[132:135], v[218:221], v[76:79]
	v_mfma_f32_16x16x32_bf16 v[68:71], v[176:179], v[218:221], v[68:71]
	v_mfma_f32_16x16x32_bf16 v[60:63], v[132:135], v[226:229], v[60:63]
	v_mfma_f32_16x16x32_bf16 v[52:55], v[176:179], v[226:229], v[52:55]
	v_mfma_f32_16x16x32_bf16 v[28:31], v[180:183], v[198:201], 0
	v_mfma_f32_16x16x32_bf16 v[24:27], v[190:193], v[198:201], 0
	v_mfma_f32_16x16x32_bf16 v[20:23], v[180:183], v[206:209], 0
	v_mfma_f32_16x16x32_bf16 v[16:19], v[190:193], v[206:209], 0
	v_mfma_f32_16x16x32_bf16 v[12:15], v[180:183], v[214:217], 0
	v_mfma_f32_16x16x32_bf16 v[8:11], v[190:193], v[214:217], 0
	v_mfma_f32_16x16x32_bf16 v[4:7], v[180:183], v[222:225], 0
	v_mfma_f32_16x16x32_bf16 v[0:3], v[190:193], v[222:225], 0
	v_mfma_f32_16x16x32_bf16 v[28:31], v[186:189], v[202:205], v[28:31]
	v_mfma_f32_16x16x32_bf16 v[24:27], v[194:197], v[202:205], v[24:27]
	v_mfma_f32_16x16x32_bf16 v[20:23], v[186:189], v[210:213], v[20:23]
	v_mfma_f32_16x16x32_bf16 v[16:19], v[194:197], v[210:213], v[16:19]
	v_mfma_f32_16x16x32_bf16 v[12:15], v[186:189], v[218:221], v[12:15]
	v_mfma_f32_16x16x32_bf16 v[8:11], v[194:197], v[218:221], v[8:11]
	v_mfma_f32_16x16x32_bf16 v[4:7], v[186:189], v[226:229], v[4:7]
	v_mfma_f32_16x16x32_bf16 v[0:3], v[194:197], v[226:229], v[0:3]
	s_barrier
	s_add_i32 s52, 0, 0x18000
	v_add_u32_e32 v158, s52, v161
	s_add_i32 s53, 0, 0x1c000
	ds_read_b128 v[128:131], v158
	ds_read_b128 v[132:135], v158 offset:1024
	ds_read_b128 v[172:175], v158 offset:2048
	ds_read_b128 v[176:179], v158 offset:3072
	v_add_u32_e32 v158, s53, v161
	ds_read_b128 v[180:183], v158
	ds_read_b128 v[186:189], v158 offset:1024
	ds_read_b128 v[190:193], v158 offset:2048
	ds_read_b128 v[194:197], v158 offset:3072
	s_add_u32 s28, s28, 0x40000
	s_addc_u32 s29, s29, 0
	s_mov_b32 m0, s36
	ds_read_b128 v[198:201], v167 offset:32768
	ds_read_b128 v[202:205], v167 offset:33792
	ds_read_b128 v[206:209], v167 offset:34816
	ds_read_b128 v[210:213], v167 offset:35840
	ds_read_b128 v[214:217], v167 offset:36864
	ds_read_b128 v[218:221], v167 offset:37888
	ds_read_b128 v[222:225], v167 offset:38912
	ds_read_b128 v[226:229], v167 offset:39936
	global_load_lds_dwordx4 v136, s[28:29]
	s_mov_b32 m0, s37
	s_nop 0
	global_load_lds_dwordx4 v140, s[28:29]
	s_waitcnt vmcnt(8)
	s_waitcnt lgkmcnt(0)
	s_barrier
	s_waitcnt lgkmcnt(0)
	v_mfma_f32_16x16x32_bf16 v[124:127], v[128:131], v[198:201], v[124:127]
	v_mfma_f32_16x16x32_bf16 v[120:123], v[172:175], v[198:201], v[120:123]
	v_mfma_f32_16x16x32_bf16 v[116:119], v[128:131], v[206:209], v[116:119]
	v_mfma_f32_16x16x32_bf16 v[112:115], v[172:175], v[206:209], v[112:115]
	v_mfma_f32_16x16x32_bf16 v[108:111], v[128:131], v[214:217], v[108:111]
	v_mfma_f32_16x16x32_bf16 v[104:107], v[172:175], v[214:217], v[104:107]
	v_mfma_f32_16x16x32_bf16 v[100:103], v[128:131], v[222:225], v[100:103]
	v_mfma_f32_16x16x32_bf16 v[96:99], v[172:175], v[222:225], v[96:99]
	v_mfma_f32_16x16x32_bf16 v[124:127], v[132:135], v[202:205], v[124:127]
	v_mfma_f32_16x16x32_bf16 v[120:123], v[176:179], v[202:205], v[120:123]
	v_mfma_f32_16x16x32_bf16 v[116:119], v[132:135], v[210:213], v[116:119]
	v_mfma_f32_16x16x32_bf16 v[112:115], v[176:179], v[210:213], v[112:115]
	v_mfma_f32_16x16x32_bf16 v[108:111], v[132:135], v[218:221], v[108:111]
	v_mfma_f32_16x16x32_bf16 v[104:107], v[176:179], v[218:221], v[104:107]
	v_mfma_f32_16x16x32_bf16 v[100:103], v[132:135], v[226:229], v[100:103]
	v_mfma_f32_16x16x32_bf16 v[96:99], v[176:179], v[226:229], v[96:99]
	v_mfma_f32_16x16x32_bf16 v[72:75], v[180:183], v[198:201], v[72:75]
	v_mfma_f32_16x16x32_bf16 v[64:67], v[190:193], v[198:201], v[64:67]
	v_mfma_f32_16x16x32_bf16 v[56:59], v[180:183], v[206:209], v[56:59]
	v_mfma_f32_16x16x32_bf16 v[48:51], v[190:193], v[206:209], v[48:51]
	v_mfma_f32_16x16x32_bf16 v[44:47], v[180:183], v[214:217], v[44:47]
	v_mfma_f32_16x16x32_bf16 v[40:43], v[190:193], v[214:217], v[40:43]
	v_mfma_f32_16x16x32_bf16 v[36:39], v[180:183], v[222:225], v[36:39]
	v_mfma_f32_16x16x32_bf16 v[32:35], v[190:193], v[222:225], v[32:35]
	v_mfma_f32_16x16x32_bf16 v[72:75], v[186:189], v[202:205], v[72:75]
	v_mfma_f32_16x16x32_bf16 v[64:67], v[194:197], v[202:205], v[64:67]
	v_mfma_f32_16x16x32_bf16 v[56:59], v[186:189], v[210:213], v[56:59]
	v_mfma_f32_16x16x32_bf16 v[48:51], v[194:197], v[210:213], v[48:51]
	v_mfma_f32_16x16x32_bf16 v[44:47], v[186:189], v[218:221], v[44:47]
	v_mfma_f32_16x16x32_bf16 v[40:43], v[194:197], v[218:221], v[40:43]
	v_mfma_f32_16x16x32_bf16 v[36:39], v[186:189], v[226:229], v[36:39]
	v_mfma_f32_16x16x32_bf16 v[32:35], v[194:197], v[226:229], v[32:35]
	s_barrier
	s_add_i32 s28, s52, s34
	s_mov_b32 m0, s28
	ds_read_b128 v[198:201], v167 offset:49152
	ds_read_b128 v[202:205], v167 offset:50176
	ds_read_b128 v[206:209], v167 offset:51200
	ds_read_b128 v[210:213], v167 offset:52224
	ds_read_b128 v[214:217], v167 offset:53248
	ds_read_b128 v[218:221], v167 offset:54272
	ds_read_b128 v[222:225], v167 offset:55296
	ds_read_b128 v[226:229], v167 offset:56320
	global_load_lds_dwordx4 v138, s[98:99]
	s_add_i32 m0, s28, 0x2000
	s_add_u32 s26, s26, 0x40080
	s_addc_u32 s27, s27, 0
	s_add_i32 s28, s53, s34
	global_load_lds_dwordx4 v142, s[98:99]
	s_mov_b32 m0, s28
	s_nop 0
	global_load_lds_dwordx4 v138, s[26:27]
	s_add_i32 m0, s28, 0x2000
	s_nop 0
	global_load_lds_dwordx4 v142, s[26:27]
	s_mov_b32 m0, s39
	s_nop 0
	global_load_lds_dwordx4 v136, s[100:101]
	s_mov_b32 m0, s40
	s_nop 0
	global_load_lds_dwordx4 v140, s[100:101]
	s_waitcnt vmcnt(8)
	s_waitcnt lgkmcnt(0)
	s_barrier
	s_waitcnt lgkmcnt(0)
	v_mfma_f32_16x16x32_bf16 v[92:95], v[128:131], v[198:201], v[92:95]
	v_mfma_f32_16x16x32_bf16 v[88:91], v[172:175], v[198:201], v[88:91]
	v_mfma_f32_16x16x32_bf16 v[84:87], v[128:131], v[206:209], v[84:87]
	v_mfma_f32_16x16x32_bf16 v[80:83], v[172:175], v[206:209], v[80:83]
	v_mfma_f32_16x16x32_bf16 v[76:79], v[128:131], v[214:217], v[76:79]
	v_mfma_f32_16x16x32_bf16 v[68:71], v[172:175], v[214:217], v[68:71]
	v_mfma_f32_16x16x32_bf16 v[60:63], v[128:131], v[222:225], v[60:63]
	v_mfma_f32_16x16x32_bf16 v[52:55], v[172:175], v[222:225], v[52:55]
	v_mfma_f32_16x16x32_bf16 v[92:95], v[132:135], v[202:205], v[92:95]
	v_mfma_f32_16x16x32_bf16 v[88:91], v[176:179], v[202:205], v[88:91]
	v_mfma_f32_16x16x32_bf16 v[84:87], v[132:135], v[210:213], v[84:87]
	v_mfma_f32_16x16x32_bf16 v[80:83], v[176:179], v[210:213], v[80:83]
	v_mfma_f32_16x16x32_bf16 v[76:79], v[132:135], v[218:221], v[76:79]
	v_mfma_f32_16x16x32_bf16 v[68:71], v[176:179], v[218:221], v[68:71]
	v_mfma_f32_16x16x32_bf16 v[60:63], v[132:135], v[226:229], v[60:63]
	v_mfma_f32_16x16x32_bf16 v[52:55], v[176:179], v[226:229], v[52:55]
	v_mfma_f32_16x16x32_bf16 v[28:31], v[180:183], v[198:201], v[28:31]
	v_mfma_f32_16x16x32_bf16 v[24:27], v[190:193], v[198:201], v[24:27]
	v_mfma_f32_16x16x32_bf16 v[20:23], v[180:183], v[206:209], v[20:23]
	v_mfma_f32_16x16x32_bf16 v[16:19], v[190:193], v[206:209], v[16:19]
	v_mfma_f32_16x16x32_bf16 v[12:15], v[180:183], v[214:217], v[12:15]
	v_mfma_f32_16x16x32_bf16 v[8:11], v[190:193], v[214:217], v[8:11]
	v_mfma_f32_16x16x32_bf16 v[4:7], v[180:183], v[222:225], v[4:7]
	v_mfma_f32_16x16x32_bf16 v[0:3], v[190:193], v[222:225], v[0:3]
	v_mfma_f32_16x16x32_bf16 v[28:31], v[186:189], v[202:205], v[28:31]
	v_mfma_f32_16x16x32_bf16 v[24:27], v[194:197], v[202:205], v[24:27]
	v_mfma_f32_16x16x32_bf16 v[20:23], v[186:189], v[210:213], v[20:23]
	v_mfma_f32_16x16x32_bf16 v[16:19], v[194:197], v[210:213], v[16:19]
	v_mfma_f32_16x16x32_bf16 v[12:15], v[186:189], v[218:221], v[12:15]
	v_mfma_f32_16x16x32_bf16 v[8:11], v[194:197], v[218:221], v[8:11]
	v_mfma_f32_16x16x32_bf16 v[4:7], v[186:189], v[226:229], v[4:7]
	v_mfma_f32_16x16x32_bf16 v[0:3], v[194:197], v[226:229], v[0:3]
	s_barrier
	s_add_i32 s51, s51, 2
	s_add_u32 s24, s24, 0x100
	s_addc_u32 s25, s25, 0
	s_add_u32 s49, s49, 0x100
	s_addc_u32 s50, s50, 0
	s_cmp_gt_u32 s51, 13
	s_cbranch_scc1 .Lpeel_exit_1727
.LBB0_1727:
	ds_read_b128 v[128:131], v163
	ds_read_b128 v[132:135], v163 offset:1024
	ds_read_b128 v[172:175], v163 offset:2048
	ds_read_b128 v[176:179], v163 offset:3072
	ds_read_b128 v[180:183], v165
	ds_read_b128 v[186:189], v165 offset:1024
	ds_read_b128 v[190:193], v165 offset:2048
	ds_read_b128 v[194:197], v165 offset:3072
	s_add_u32 s26, s24, 0xfffc0080
	s_addc_u32 s27, s25, -1
	s_cmp_eq_u32 s51, 12
	s_cselect_b32 s29, s15, s27
	s_cselect_b32 s28, s47, s26
	s_cselect_b32 s27, s17, s50
	s_cselect_b32 s26, s48, s49
	s_add_i32 m0, s23, 0xc000
	ds_read_b128 v[198:201], v167
	ds_read_b128 v[202:205], v167 offset:1024
	ds_read_b128 v[206:209], v167 offset:2048
	ds_read_b128 v[210:213], v167 offset:3072
	ds_read_b128 v[214:217], v167 offset:4096
	ds_read_b128 v[218:221], v167 offset:5120
	ds_read_b128 v[222:225], v167 offset:6144
	ds_read_b128 v[226:229], v167 offset:7168
	global_load_lds_dwordx4 v148, s[24:25]
	s_add_i32 m0, s23, 0xe000
	s_nop 0
	global_load_lds_dwordx4 v150, s[24:25]
	s_waitcnt vmcnt(8)
	s_waitcnt lgkmcnt(0)
	s_barrier
	s_waitcnt lgkmcnt(0)
	v_mfma_f32_16x16x32_bf16 v[124:127], v[128:131], v[198:201], v[124:127]
	v_mfma_f32_16x16x32_bf16 v[120:123], v[172:175], v[198:201], v[120:123]
	v_mfma_f32_16x16x32_bf16 v[116:119], v[128:131], v[206:209], v[116:119]
	v_mfma_f32_16x16x32_bf16 v[112:115], v[172:175], v[206:209], v[112:115]
	v_mfma_f32_16x16x32_bf16 v[108:111], v[128:131], v[214:217], v[108:111]
	v_mfma_f32_16x16x32_bf16 v[104:107], v[172:175], v[214:217], v[104:107]
	v_mfma_f32_16x16x32_bf16 v[100:103], v[128:131], v[222:225], v[100:103]
	v_mfma_f32_16x16x32_bf16 v[96:99], v[172:175], v[222:225], v[96:99]
	v_mfma_f32_16x16x32_bf16 v[124:127], v[132:135], v[202:205], v[124:127]
	v_mfma_f32_16x16x32_bf16 v[120:123], v[176:179], v[202:205], v[120:123]
	v_mfma_f32_16x16x32_bf16 v[116:119], v[132:135], v[210:213], v[116:119]
	v_mfma_f32_16x16x32_bf16 v[112:115], v[176:179], v[210:213], v[112:115]
	v_mfma_f32_16x16x32_bf16 v[108:111], v[132:135], v[218:221], v[108:111]
	v_mfma_f32_16x16x32_bf16 v[104:107], v[176:179], v[218:221], v[104:107]
	v_mfma_f32_16x16x32_bf16 v[100:103], v[132:135], v[226:229], v[100:103]
	v_mfma_f32_16x16x32_bf16 v[96:99], v[176:179], v[226:229], v[96:99]
	v_mfma_f32_16x16x32_bf16 v[72:75], v[180:183], v[198:201], v[72:75]
	v_mfma_f32_16x16x32_bf16 v[64:67], v[190:193], v[198:201], v[64:67]
	v_mfma_f32_16x16x32_bf16 v[56:59], v[180:183], v[206:209], v[56:59]
	v_mfma_f32_16x16x32_bf16 v[48:51], v[190:193], v[206:209], v[48:51]
	v_mfma_f32_16x16x32_bf16 v[44:47], v[180:183], v[214:217], v[44:47]
	v_mfma_f32_16x16x32_bf16 v[40:43], v[190:193], v[214:217], v[40:43]
	v_mfma_f32_16x16x32_bf16 v[36:39], v[180:183], v[222:225], v[36:39]
	v_mfma_f32_16x16x32_bf16 v[32:35], v[190:193], v[222:225], v[32:35]
	v_mfma_f32_16x16x32_bf16 v[72:75], v[186:189], v[202:205], v[72:75]
	v_mfma_f32_16x16x32_bf16 v[64:67], v[194:197], v[202:205], v[64:67]
	v_mfma_f32_16x16x32_bf16 v[56:59], v[186:189], v[210:213], v[56:59]
	v_mfma_f32_16x16x32_bf16 v[48:51], v[194:197], v[210:213], v[48:51]
	v_mfma_f32_16x16x32_bf16 v[44:47], v[186:189], v[218:221], v[44:47]
	v_mfma_f32_16x16x32_bf16 v[40:43], v[194:197], v[218:221], v[40:43]
	v_mfma_f32_16x16x32_bf16 v[36:39], v[186:189], v[226:229], v[36:39]
	v_mfma_f32_16x16x32_bf16 v[32:35], v[194:197], v[226:229], v[32:35]
	s_barrier
	s_add_i32 s52, s44, s34
	s_mov_b32 m0, s52
	ds_read_b128 v[198:201], v167 offset:16384
	ds_read_b128 v[202:205], v167 offset:17408
	ds_read_b128 v[206:209], v167 offset:18432
	ds_read_b128 v[210:213], v167 offset:19456
	ds_read_b128 v[214:217], v167 offset:20480
	ds_read_b128 v[218:221], v167 offset:21504
	ds_read_b128 v[222:225], v167 offset:22528
	ds_read_b128 v[226:229], v167 offset:23552
	global_load_lds_dwordx4 v138, s[26:27]
	s_add_i32 m0, s52, 0x2000
	s_add_u32 s52, s26, 0x40000
	s_addc_u32 s53, s27, 0
	s_add_i32 s54, s45, s34
	global_load_lds_dwordx4 v142, s[26:27]
	s_mov_b32 m0, s54
	global_load_lds_dwordx4 v138, s[52:53]
	s_add_i32 m0, s54, 0x2000
	s_nop 0
	global_load_lds_dwordx4 v142, s[52:53]
	s_mov_b32 m0, s23
	s_nop 0
	global_load_lds_dwordx4 v136, s[28:29]
	s_mov_b32 m0, s35
	s_nop 0
	global_load_lds_dwordx4 v140, s[28:29]
	s_add_u32 s98, s26, s10
	s_addc_u32 s99, s27, s11
	s_add_u32 s100, s28, s10
	s_addc_u32 s101, s29, s11
	s_waitcnt vmcnt(8)
	s_waitcnt lgkmcnt(0)
	s_barrier
	s_waitcnt lgkmcnt(0)
	v_mfma_f32_16x16x32_bf16 v[92:95], v[128:131], v[198:201], v[92:95]
	v_mfma_f32_16x16x32_bf16 v[88:91], v[172:175], v[198:201], v[88:91]
	v_mfma_f32_16x16x32_bf16 v[84:87], v[128:131], v[206:209], v[84:87]
	v_mfma_f32_16x16x32_bf16 v[80:83], v[172:175], v[206:209], v[80:83]
	v_mfma_f32_16x16x32_bf16 v[76:79], v[128:131], v[214:217], v[76:79]
	v_mfma_f32_16x16x32_bf16 v[68:71], v[172:175], v[214:217], v[68:71]
	v_mfma_f32_16x16x32_bf16 v[60:63], v[128:131], v[222:225], v[60:63]
	v_mfma_f32_16x16x32_bf16 v[52:55], v[172:175], v[222:225], v[52:55]
	v_mfma_f32_16x16x32_bf16 v[92:95], v[132:135], v[202:205], v[92:95]
	v_mfma_f32_16x16x32_bf16 v[88:91], v[176:179], v[202:205], v[88:91]
	v_mfma_f32_16x16x32_bf16 v[84:87], v[132:135], v[210:213], v[84:87]
	v_mfma_f32_16x16x32_bf16 v[80:83], v[176:179], v[210:213], v[80:83]
	v_mfma_f32_16x16x32_bf16 v[76:79], v[132:135], v[218:221], v[76:79]
	v_mfma_f32_16x16x32_bf16 v[68:71], v[176:179], v[218:221], v[68:71]
	v_mfma_f32_16x16x32_bf16 v[60:63], v[132:135], v[226:229], v[60:63]
	v_mfma_f32_16x16x32_bf16 v[52:55], v[176:179], v[226:229], v[52:55]
	v_mfma_f32_16x16x32_bf16 v[28:31], v[180:183], v[198:201], v[28:31]
	v_mfma_f32_16x16x32_bf16 v[24:27], v[190:193], v[198:201], v[24:27]
	v_mfma_f32_16x16x32_bf16 v[20:23], v[180:183], v[206:209], v[20:23]
	v_mfma_f32_16x16x32_bf16 v[16:19], v[190:193], v[206:209], v[16:19]
	v_mfma_f32_16x16x32_bf16 v[12:15], v[180:183], v[214:217], v[12:15]
	v_mfma_f32_16x16x32_bf16 v[8:11], v[190:193], v[214:217], v[8:11]
	v_mfma_f32_16x16x32_bf16 v[4:7], v[180:183], v[222:225], v[4:7]
	v_mfma_f32_16x16x32_bf16 v[0:3], v[190:193], v[222:225], v[0:3]
	v_mfma_f32_16x16x32_bf16 v[28:31], v[186:189], v[202:205], v[28:31]
	v_mfma_f32_16x16x32_bf16 v[24:27], v[194:197], v[202:205], v[24:27]
	v_mfma_f32_16x16x32_bf16 v[20:23], v[186:189], v[210:213], v[20:23]
	v_mfma_f32_16x16x32_bf16 v[16:19], v[194:197], v[210:213], v[16:19]
	v_mfma_f32_16x16x32_bf16 v[12:15], v[186:189], v[218:221], v[12:15]
	v_mfma_f32_16x16x32_bf16 v[8:11], v[194:197], v[218:221], v[8:11]
	v_mfma_f32_16x16x32_bf16 v[4:7], v[186:189], v[226:229], v[4:7]
	v_mfma_f32_16x16x32_bf16 v[0:3], v[194:197], v[226:229], v[0:3]
	s_barrier
	s_add_i32 s52, 0, 0x18000
	v_add_u32_e32 v158, s52, v161
	s_add_i32 s53, 0, 0x1c000
	ds_read_b128 v[128:131], v158
	ds_read_b128 v[132:135], v158 offset:1024
	ds_read_b128 v[172:175], v158 offset:2048
	ds_read_b128 v[176:179], v158 offset:3072
	v_add_u32_e32 v158, s53, v161
	ds_read_b128 v[180:183], v158
	ds_read_b128 v[186:189], v158 offset:1024
	ds_read_b128 v[190:193], v158 offset:2048
	ds_read_b128 v[194:197], v158 offset:3072
	s_add_u32 s28, s28, 0x40000
	s_addc_u32 s29, s29, 0
	s_mov_b32 m0, s36
	ds_read_b128 v[198:201], v167 offset:32768
	ds_read_b128 v[202:205], v167 offset:33792
	ds_read_b128 v[206:209], v167 offset:34816
	ds_read_b128 v[210:213], v167 offset:35840
	ds_read_b128 v[214:217], v167 offset:36864
	ds_read_b128 v[218:221], v167 offset:37888
	ds_read_b128 v[222:225], v167 offset:38912
	ds_read_b128 v[226:229], v167 offset:39936
	global_load_lds_dwordx4 v136, s[28:29]
	s_mov_b32 m0, s37
	s_nop 0
	global_load_lds_dwordx4 v140, s[28:29]
	s_waitcnt vmcnt(8)
	s_waitcnt lgkmcnt(0)
	s_barrier
	s_waitcnt lgkmcnt(0)
	v_mfma_f32_16x16x32_bf16 v[124:127], v[128:131], v[198:201], v[124:127]
	v_mfma_f32_16x16x32_bf16 v[120:123], v[172:175], v[198:201], v[120:123]
	v_mfma_f32_16x16x32_bf16 v[116:119], v[128:131], v[206:209], v[116:119]
	v_mfma_f32_16x16x32_bf16 v[112:115], v[172:175], v[206:209], v[112:115]
	v_mfma_f32_16x16x32_bf16 v[108:111], v[128:131], v[214:217], v[108:111]
	v_mfma_f32_16x16x32_bf16 v[104:107], v[172:175], v[214:217], v[104:107]
	v_mfma_f32_16x16x32_bf16 v[100:103], v[128:131], v[222:225], v[100:103]
	v_mfma_f32_16x16x32_bf16 v[96:99], v[172:175], v[222:225], v[96:99]
	v_mfma_f32_16x16x32_bf16 v[124:127], v[132:135], v[202:205], v[124:127]
	v_mfma_f32_16x16x32_bf16 v[120:123], v[176:179], v[202:205], v[120:123]
	v_mfma_f32_16x16x32_bf16 v[116:119], v[132:135], v[210:213], v[116:119]
	v_mfma_f32_16x16x32_bf16 v[112:115], v[176:179], v[210:213], v[112:115]
	v_mfma_f32_16x16x32_bf16 v[108:111], v[132:135], v[218:221], v[108:111]
	v_mfma_f32_16x16x32_bf16 v[104:107], v[176:179], v[218:221], v[104:107]
	v_mfma_f32_16x16x32_bf16 v[100:103], v[132:135], v[226:229], v[100:103]
	v_mfma_f32_16x16x32_bf16 v[96:99], v[176:179], v[226:229], v[96:99]
	v_mfma_f32_16x16x32_bf16 v[72:75], v[180:183], v[198:201], v[72:75]
	v_mfma_f32_16x16x32_bf16 v[64:67], v[190:193], v[198:201], v[64:67]
	v_mfma_f32_16x16x32_bf16 v[56:59], v[180:183], v[206:209], v[56:59]
	v_mfma_f32_16x16x32_bf16 v[48:51], v[190:193], v[206:209], v[48:51]
	v_mfma_f32_16x16x32_bf16 v[44:47], v[180:183], v[214:217], v[44:47]
	v_mfma_f32_16x16x32_bf16 v[40:43], v[190:193], v[214:217], v[40:43]
	v_mfma_f32_16x16x32_bf16 v[36:39], v[180:183], v[222:225], v[36:39]
	v_mfma_f32_16x16x32_bf16 v[32:35], v[190:193], v[222:225], v[32:35]
	v_mfma_f32_16x16x32_bf16 v[72:75], v[186:189], v[202:205], v[72:75]
	v_mfma_f32_16x16x32_bf16 v[64:67], v[194:197], v[202:205], v[64:67]
	v_mfma_f32_16x16x32_bf16 v[56:59], v[186:189], v[210:213], v[56:59]
	v_mfma_f32_16x16x32_bf16 v[48:51], v[194:197], v[210:213], v[48:51]
	v_mfma_f32_16x16x32_bf16 v[44:47], v[186:189], v[218:221], v[44:47]
	v_mfma_f32_16x16x32_bf16 v[40:43], v[194:197], v[218:221], v[40:43]
	v_mfma_f32_16x16x32_bf16 v[36:39], v[186:189], v[226:229], v[36:39]
	v_mfma_f32_16x16x32_bf16 v[32:35], v[194:197], v[226:229], v[32:35]
	s_barrier
	s_add_i32 s28, s52, s34
	s_mov_b32 m0, s28
	ds_read_b128 v[198:201], v167 offset:49152
	ds_read_b128 v[202:205], v167 offset:50176
	ds_read_b128 v[206:209], v167 offset:51200
	ds_read_b128 v[210:213], v167 offset:52224
	ds_read_b128 v[214:217], v167 offset:53248
	ds_read_b128 v[218:221], v167 offset:54272
	ds_read_b128 v[222:225], v167 offset:55296
	ds_read_b128 v[226:229], v167 offset:56320
	global_load_lds_dwordx4 v138, s[98:99]
	s_add_i32 m0, s28, 0x2000
	s_add_u32 s26, s26, 0x40080
	s_addc_u32 s27, s27, 0
	s_add_i32 s28, s53, s34
	global_load_lds_dwordx4 v142, s[98:99]
	s_mov_b32 m0, s28
	s_nop 0
	global_load_lds_dwordx4 v138, s[26:27]
	s_add_i32 m0, s28, 0x2000
	s_nop 0
	global_load_lds_dwordx4 v142, s[26:27]
	s_mov_b32 m0, s39
	s_nop 0
	global_load_lds_dwordx4 v136, s[100:101]
	s_mov_b32 m0, s40
	s_nop 0
	global_load_lds_dwordx4 v140, s[100:101]
	s_waitcnt vmcnt(8)
	s_waitcnt lgkmcnt(0)
	s_barrier
	s_waitcnt lgkmcnt(0)
	v_mfma_f32_16x16x32_bf16 v[92:95], v[128:131], v[198:201], v[92:95]
	v_mfma_f32_16x16x32_bf16 v[88:91], v[172:175], v[198:201], v[88:91]
	v_mfma_f32_16x16x32_bf16 v[84:87], v[128:131], v[206:209], v[84:87]
	v_mfma_f32_16x16x32_bf16 v[80:83], v[172:175], v[206:209], v[80:83]
	v_mfma_f32_16x16x32_bf16 v[76:79], v[128:131], v[214:217], v[76:79]
	v_mfma_f32_16x16x32_bf16 v[68:71], v[172:175], v[214:217], v[68:71]
	v_mfma_f32_16x16x32_bf16 v[60:63], v[128:131], v[222:225], v[60:63]
	v_mfma_f32_16x16x32_bf16 v[52:55], v[172:175], v[222:225], v[52:55]
	v_mfma_f32_16x16x32_bf16 v[92:95], v[132:135], v[202:205], v[92:95]
	v_mfma_f32_16x16x32_bf16 v[88:91], v[176:179], v[202:205], v[88:91]
	v_mfma_f32_16x16x32_bf16 v[84:87], v[132:135], v[210:213], v[84:87]
	v_mfma_f32_16x16x32_bf16 v[80:83], v[176:179], v[210:213], v[80:83]
	v_mfma_f32_16x16x32_bf16 v[76:79], v[132:135], v[218:221], v[76:79]
	v_mfma_f32_16x16x32_bf16 v[68:71], v[176:179], v[218:221], v[68:71]
	v_mfma_f32_16x16x32_bf16 v[60:63], v[132:135], v[226:229], v[60:63]
	v_mfma_f32_16x16x32_bf16 v[52:55], v[176:179], v[226:229], v[52:55]
	v_mfma_f32_16x16x32_bf16 v[28:31], v[180:183], v[198:201], v[28:31]
	v_mfma_f32_16x16x32_bf16 v[24:27], v[190:193], v[198:201], v[24:27]
	v_mfma_f32_16x16x32_bf16 v[20:23], v[180:183], v[206:209], v[20:23]
	v_mfma_f32_16x16x32_bf16 v[16:19], v[190:193], v[206:209], v[16:19]
	v_mfma_f32_16x16x32_bf16 v[12:15], v[180:183], v[214:217], v[12:15]
	v_mfma_f32_16x16x32_bf16 v[8:11], v[190:193], v[214:217], v[8:11]
	v_mfma_f32_16x16x32_bf16 v[4:7], v[180:183], v[222:225], v[4:7]
	v_mfma_f32_16x16x32_bf16 v[0:3], v[190:193], v[222:225], v[0:3]
	v_mfma_f32_16x16x32_bf16 v[28:31], v[186:189], v[202:205], v[28:31]
	v_mfma_f32_16x16x32_bf16 v[24:27], v[194:197], v[202:205], v[24:27]
	v_mfma_f32_16x16x32_bf16 v[20:23], v[186:189], v[210:213], v[20:23]
	v_mfma_f32_16x16x32_bf16 v[16:19], v[194:197], v[210:213], v[16:19]
	v_mfma_f32_16x16x32_bf16 v[12:15], v[186:189], v[218:221], v[12:15]
	v_mfma_f32_16x16x32_bf16 v[8:11], v[194:197], v[218:221], v[8:11]
	v_mfma_f32_16x16x32_bf16 v[4:7], v[186:189], v[226:229], v[4:7]
	v_mfma_f32_16x16x32_bf16 v[0:3], v[194:197], v[226:229], v[0:3]
	s_barrier
	s_add_i32 s51, s51, 2
	s_add_u32 s24, s24, 0x100
	s_addc_u32 s25, s25, 0
	s_add_u32 s49, s49, 0x100
	s_addc_u32 s50, s50, 0
	s_cmp_gt_u32 s51, 13
	s_cbranch_scc0 .LBB0_1727
.Lpeel_exit_1727:
	s_and_b64 vcc, exec, s[12:13]
	s_cbranch_vccz .LBB0_1730
	s_barrier

.LBB0_1885:
	s_ashr_i32 s17, s16, 31
	s_lshl_b64 s[20:21], s[16:17], 19
	s_add_u32 s20, s3, s20
	s_addc_u32 s21, s33, s21
	s_and_b64 s[22:23], s[8:9], exec
	s_cselect_b32 s17, s21, s29
	s_cselect_b32 s25, s20, s28
	s_ashr_i32 s19, s18, 31
	s_lshl_b64 s[22:23], s[18:19], 19
	s_add_u32 s22, s36, s22
	s_addc_u32 s23, s37, s23
	s_and_b64 s[34:35], s[8:9], exec
	s_cselect_b32 s19, s23, s31
	s_cselect_b32 s27, s22, s30
	s_add_u32 s28, s28, 0x40080
	s_addc_u32 s29, s29, 0
	s_add_u32 s51, s30, 0x100
	s_addc_u32 s52, s31, 0
	s_mov_b32 s53, -2
	s_waitcnt lgkmcnt(0)
	ds_read_b128 v[128:131], v188
	ds_read_b128 v[132:135], v188 offset:1024
	ds_read_b128 v[136:139], v188 offset:2048
	ds_read_b128 v[140:143], v188 offset:3072
	ds_read_b128 v[144:147], v189
	ds_read_b128 v[148:151], v189 offset:1024
	ds_read_b128 v[172:175], v189 offset:2048
	ds_read_b128 v[176:179], v189 offset:3072
	s_add_u32 s30, s28, 0xfffc0080
	s_addc_u32 s31, s29, -1
	s_cmp_eq_u32 s53, 12
	s_cselect_b32 s35, s17, s31
	s_cselect_b32 s34, s25, s30
	s_cselect_b32 s31, s19, s52
	s_cselect_b32 s30, s27, s51
	s_add_i32 m0, s39, 0xc000
	ds_read_b128 v[180:183], v190
	ds_read_b128 v[192:195], v190 offset:1024
	ds_read_b128 v[196:199], v190 offset:2048
	ds_read_b128 v[200:203], v190 offset:3072
	ds_read_b128 v[204:207], v190 offset:4096
	ds_read_b128 v[208:211], v190 offset:5120
	ds_read_b128 v[212:215], v190 offset:6144
	ds_read_b128 v[216:219], v190 offset:7168
	global_load_lds_dwordx4 v164, s[28:29]
	s_add_i32 m0, s39, 0xe000
	s_nop 0
	global_load_lds_dwordx4 v166, s[28:29]
	s_waitcnt vmcnt(8)
	s_waitcnt lgkmcnt(0)
	s_barrier
	s_waitcnt lgkmcnt(0)
	v_mfma_f32_16x16x32_bf16 v[124:127], v[128:131], v[180:183], 0
	v_mfma_f32_16x16x32_bf16 v[120:123], v[136:139], v[180:183], 0
	v_mfma_f32_16x16x32_bf16 v[108:111], v[128:131], v[196:199], 0
	v_mfma_f32_16x16x32_bf16 v[104:107], v[136:139], v[196:199], 0
	v_mfma_f32_16x16x32_bf16 v[92:95], v[128:131], v[204:207], 0
	v_mfma_f32_16x16x32_bf16 v[88:91], v[136:139], v[204:207], 0
	v_mfma_f32_16x16x32_bf16 v[76:79], v[128:131], v[212:215], 0
	v_mfma_f32_16x16x32_bf16 v[72:75], v[136:139], v[212:215], 0
	v_mfma_f32_16x16x32_bf16 v[124:127], v[132:135], v[192:195], v[124:127]
	v_mfma_f32_16x16x32_bf16 v[120:123], v[140:143], v[192:195], v[120:123]
	v_mfma_f32_16x16x32_bf16 v[108:111], v[132:135], v[200:203], v[108:111]
	v_mfma_f32_16x16x32_bf16 v[104:107], v[140:143], v[200:203], v[104:107]
	v_mfma_f32_16x16x32_bf16 v[92:95], v[132:135], v[208:211], v[92:95]
	v_mfma_f32_16x16x32_bf16 v[88:91], v[140:143], v[208:211], v[88:91]
	v_mfma_f32_16x16x32_bf16 v[76:79], v[132:135], v[216:219], v[76:79]
	v_mfma_f32_16x16x32_bf16 v[72:75], v[140:143], v[216:219], v[72:75]
	v_mfma_f32_16x16x32_bf16 v[116:119], v[144:147], v[180:183], 0
	v_mfma_f32_16x16x32_bf16 v[112:115], v[172:175], v[180:183], 0
	v_mfma_f32_16x16x32_bf16 v[100:103], v[144:147], v[196:199], 0
	v_mfma_f32_16x16x32_bf16 v[96:99], v[172:175], v[196:199], 0
	v_mfma_f32_16x16x32_bf16 v[84:87], v[144:147], v[204:207], 0
	v_mfma_f32_16x16x32_bf16 v[80:83], v[172:175], v[204:207], 0
	v_mfma_f32_16x16x32_bf16 v[68:71], v[144:147], v[212:215], 0
	v_mfma_f32_16x16x32_bf16 v[64:67], v[172:175], v[212:215], 0
	v_mfma_f32_16x16x32_bf16 v[116:119], v[148:151], v[192:195], v[116:119]
	v_mfma_f32_16x16x32_bf16 v[112:115], v[176:179], v[192:195], v[112:115]
	v_mfma_f32_16x16x32_bf16 v[100:103], v[148:151], v[200:203], v[100:103]
	v_mfma_f32_16x16x32_bf16 v[96:99], v[176:179], v[200:203], v[96:99]
	v_mfma_f32_16x16x32_bf16 v[84:87], v[148:151], v[208:211], v[84:87]
	v_mfma_f32_16x16x32_bf16 v[80:83], v[176:179], v[208:211], v[80:83]
	v_mfma_f32_16x16x32_bf16 v[68:71], v[148:151], v[216:219], v[68:71]
	v_mfma_f32_16x16x32_bf16 v[64:67], v[176:179], v[216:219], v[64:67]
	s_barrier
	s_add_i32 s54, s49, s38
	s_mov_b32 m0, s54
	ds_read_b128 v[180:183], v190 offset:16384
	ds_read_b128 v[192:195], v190 offset:17408
	ds_read_b128 v[196:199], v190 offset:18432
	ds_read_b128 v[200:203], v190 offset:19456
	ds_read_b128 v[204:207], v190 offset:20480
	ds_read_b128 v[208:211], v190 offset:21504
	ds_read_b128 v[212:215], v190 offset:22528
	ds_read_b128 v[216:219], v190 offset:23552
	global_load_lds_dwordx4 v154, s[30:31]
	s_add_i32 m0, s54, 0x2000
	s_add_u32 s54, s30, 0x40000
	s_addc_u32 s55, s31, 0
	s_add_i32 s56, s50, s38
	global_load_lds_dwordx4 v158, s[30:31]
	s_mov_b32 m0, s56
	global_load_lds_dwordx4 v154, s[54:55]
	s_add_i32 m0, s56, 0x2000
	s_nop 0
	global_load_lds_dwordx4 v158, s[54:55]
	s_mov_b32 m0, s39
	s_nop 0
	global_load_lds_dwordx4 v152, s[34:35]
	s_mov_b32 m0, s40
	s_nop 0
	global_load_lds_dwordx4 v156, s[34:35]
	s_add_u32 s98, s30, s12
	s_addc_u32 s99, s31, s13
	s_add_u32 s100, s34, s12
	s_addc_u32 s101, s35, s13
	s_waitcnt vmcnt(8)
	s_waitcnt lgkmcnt(0)
	s_barrier
	s_waitcnt lgkmcnt(0)
	v_mfma_f32_16x16x32_bf16 v[60:63], v[128:131], v[180:183], 0
	v_mfma_f32_16x16x32_bf16 v[56:59], v[136:139], v[180:183], 0
	v_mfma_f32_16x16x32_bf16 v[44:47], v[128:131], v[196:199], 0
	v_mfma_f32_16x16x32_bf16 v[40:43], v[136:139], v[196:199], 0
	v_mfma_f32_16x16x32_bf16 v[28:31], v[128:131], v[204:207], 0
	v_mfma_f32_16x16x32_bf16 v[24:27], v[136:139], v[204:207], 0
	v_mfma_f32_16x16x32_bf16 v[12:15], v[128:131], v[212:215], 0
	v_mfma_f32_16x16x32_bf16 v[8:11], v[136:139], v[212:215], 0
	v_mfma_f32_16x16x32_bf16 v[60:63], v[132:135], v[192:195], v[60:63]
	v_mfma_f32_16x16x32_bf16 v[56:59], v[140:143], v[192:195], v[56:59]
	v_mfma_f32_16x16x32_bf16 v[44:47], v[132:135], v[200:203], v[44:47]
	v_mfma_f32_16x16x32_bf16 v[40:43], v[140:143], v[200:203], v[40:43]
	v_mfma_f32_16x16x32_bf16 v[28:31], v[132:135], v[208:211], v[28:31]
	v_mfma_f32_16x16x32_bf16 v[24:27], v[140:143], v[208:211], v[24:27]
	v_mfma_f32_16x16x32_bf16 v[12:15], v[132:135], v[216:219], v[12:15]
	v_mfma_f32_16x16x32_bf16 v[8:11], v[140:143], v[216:219], v[8:11]
	v_mfma_f32_16x16x32_bf16 v[52:55], v[144:147], v[180:183], 0
	v_mfma_f32_16x16x32_bf16 v[48:51], v[172:175], v[180:183], 0
	v_mfma_f32_16x16x32_bf16 v[36:39], v[144:147], v[196:199], 0
	v_mfma_f32_16x16x32_bf16 v[32:35], v[172:175], v[196:199], 0
	v_mfma_f32_16x16x32_bf16 v[20:23], v[144:147], v[204:207], 0
	v_mfma_f32_16x16x32_bf16 v[16:19], v[172:175], v[204:207], 0
	v_mfma_f32_16x16x32_bf16 v[4:7], v[144:147], v[212:215], 0
	v_mfma_f32_16x16x32_bf16 v[0:3], v[172:175], v[212:215], 0
	v_mfma_f32_16x16x32_bf16 v[52:55], v[148:151], v[192:195], v[52:55]
	v_mfma_f32_16x16x32_bf16 v[48:51], v[176:179], v[192:195], v[48:51]
	v_mfma_f32_16x16x32_bf16 v[36:39], v[148:151], v[200:203], v[36:39]
	v_mfma_f32_16x16x32_bf16 v[32:35], v[176:179], v[200:203], v[32:35]
	v_mfma_f32_16x16x32_bf16 v[20:23], v[148:151], v[208:211], v[20:23]
	v_mfma_f32_16x16x32_bf16 v[16:19], v[176:179], v[208:211], v[16:19]
	v_mfma_f32_16x16x32_bf16 v[4:7], v[148:151], v[216:219], v[4:7]
	v_mfma_f32_16x16x32_bf16 v[0:3], v[176:179], v[216:219], v[0:3]
	s_barrier
	s_add_i32 s54, 0, 0x18000
	s_add_i32 s55, 0, 0x1c000
	v_add_u32_e32 v140, s54, v184
	v_add_u32_e32 v176, s55, v184
	ds_read_b128 v[128:131], v140
	ds_read_b128 v[132:135], v140 offset:1024
	ds_read_b128 v[136:139], v140 offset:2048
	ds_read_b128 v[140:143], v140 offset:3072
	ds_read_b128 v[144:147], v176
	ds_read_b128 v[148:151], v176 offset:1024
	ds_read_b128 v[172:175], v176 offset:2048
	ds_read_b128 v[176:179], v176 offset:3072
	s_add_u32 s34, s34, 0x40000
	s_addc_u32 s35, s35, 0
	s_mov_b32 m0, s41
	ds_read_b128 v[180:183], v190 offset:32768
	ds_read_b128 v[192:195], v190 offset:33792
	ds_read_b128 v[196:199], v190 offset:34816
	ds_read_b128 v[200:203], v190 offset:35840
	ds_read_b128 v[204:207], v190 offset:36864
	ds_read_b128 v[208:211], v190 offset:37888
	ds_read_b128 v[212:215], v190 offset:38912
	ds_read_b128 v[216:219], v190 offset:39936
	global_load_lds_dwordx4 v152, s[34:35]
	s_mov_b32 m0, s42
	s_nop 0
	global_load_lds_dwordx4 v156, s[34:35]
	s_waitcnt vmcnt(8)
	s_waitcnt lgkmcnt(0)
	s_barrier
	s_waitcnt lgkmcnt(0)
	v_mfma_f32_16x16x32_bf16 v[124:127], v[128:131], v[180:183], v[124:127]
	v_mfma_f32_16x16x32_bf16 v[120:123], v[136:139], v[180:183], v[120:123]
	v_mfma_f32_16x16x32_bf16 v[108:111], v[128:131], v[196:199], v[108:111]
	v_mfma_f32_16x16x32_bf16 v[104:107], v[136:139], v[196:199], v[104:107]
	v_mfma_f32_16x16x32_bf16 v[92:95], v[128:131], v[204:207], v[92:95]
	v_mfma_f32_16x16x32_bf16 v[88:91], v[136:139], v[204:207], v[88:91]
	v_mfma_f32_16x16x32_bf16 v[76:79], v[128:131], v[212:215], v[76:79]
	v_mfma_f32_16x16x32_bf16 v[72:75], v[136:139], v[212:215], v[72:75]
	v_mfma_f32_16x16x32_bf16 v[124:127], v[132:135], v[192:195], v[124:127]
	v_mfma_f32_16x16x32_bf16 v[120:123], v[140:143], v[192:195], v[120:123]
	v_mfma_f32_16x16x32_bf16 v[108:111], v[132:135], v[200:203], v[108:111]
	v_mfma_f32_16x16x32_bf16 v[104:107], v[140:143], v[200:203], v[104:107]
	v_mfma_f32_16x16x32_bf16 v[92:95], v[132:135], v[208:211], v[92:95]
	v_mfma_f32_16x16x32_bf16 v[88:91], v[140:143], v[208:211], v[88:91]
	v_mfma_f32_16x16x32_bf16 v[76:79], v[132:135], v[216:219], v[76:79]
	v_mfma_f32_16x16x32_bf16 v[72:75], v[140:143], v[216:219], v[72:75]
	v_mfma_f32_16x16x32_bf16 v[116:119], v[144:147], v[180:183], v[116:119]
	v_mfma_f32_16x16x32_bf16 v[112:115], v[172:175], v[180:183], v[112:115]
	v_mfma_f32_16x16x32_bf16 v[100:103], v[144:147], v[196:199], v[100:103]
	v_mfma_f32_16x16x32_bf16 v[96:99], v[172:175], v[196:199], v[96:99]
	v_mfma_f32_16x16x32_bf16 v[84:87], v[144:147], v[204:207], v[84:87]
	v_mfma_f32_16x16x32_bf16 v[80:83], v[172:175], v[204:207], v[80:83]
	v_mfma_f32_16x16x32_bf16 v[68:71], v[144:147], v[212:215], v[68:71]
	v_mfma_f32_16x16x32_bf16 v[64:67], v[172:175], v[212:215], v[64:67]
	v_mfma_f32_16x16x32_bf16 v[116:119], v[148:151], v[192:195], v[116:119]
	v_mfma_f32_16x16x32_bf16 v[112:115], v[176:179], v[192:195], v[112:115]
	v_mfma_f32_16x16x32_bf16 v[100:103], v[148:151], v[200:203], v[100:103]
	v_mfma_f32_16x16x32_bf16 v[96:99], v[176:179], v[200:203], v[96:99]
	v_mfma_f32_16x16x32_bf16 v[84:87], v[148:151], v[208:211], v[84:87]
	v_mfma_f32_16x16x32_bf16 v[80:83], v[176:179], v[208:211], v[80:83]
	v_mfma_f32_16x16x32_bf16 v[68:71], v[148:151], v[216:219], v[68:71]
	v_mfma_f32_16x16x32_bf16 v[64:67], v[176:179], v[216:219], v[64:67]
	s_barrier
	s_add_i32 s34, s54, s38
	s_mov_b32 m0, s34
	ds_read_b128 v[180:183], v190 offset:49152
	ds_read_b128 v[192:195], v190 offset:50176
	ds_read_b128 v[196:199], v190 offset:51200
	ds_read_b128 v[200:203], v190 offset:52224
	ds_read_b128 v[204:207], v190 offset:53248
	ds_read_b128 v[208:211], v190 offset:54272
	ds_read_b128 v[212:215], v190 offset:55296
	ds_read_b128 v[216:219], v190 offset:56320
	global_load_lds_dwordx4 v154, s[98:99]
	s_add_i32 m0, s34, 0x2000
	s_add_u32 s30, s30, 0x40080
	s_addc_u32 s31, s31, 0
	s_add_i32 s34, s55, s38
	global_load_lds_dwordx4 v158, s[98:99]
	s_mov_b32 m0, s34
	s_nop 0
	global_load_lds_dwordx4 v154, s[30:31]
	s_add_i32 m0, s34, 0x2000
	s_nop 0
	global_load_lds_dwordx4 v158, s[30:31]
	s_mov_b32 m0, s44
	s_nop 0
	global_load_lds_dwordx4 v152, s[100:101]
	s_mov_b32 m0, s45
	s_nop 0
	global_load_lds_dwordx4 v156, s[100:101]
	s_waitcnt vmcnt(8)
	s_waitcnt lgkmcnt(0)
	s_barrier
	s_waitcnt lgkmcnt(0)
	v_mfma_f32_16x16x32_bf16 v[60:63], v[128:131], v[180:183], v[60:63]
	v_mfma_f32_16x16x32_bf16 v[56:59], v[136:139], v[180:183], v[56:59]
	v_mfma_f32_16x16x32_bf16 v[44:47], v[128:131], v[196:199], v[44:47]
	v_mfma_f32_16x16x32_bf16 v[40:43], v[136:139], v[196:199], v[40:43]
	v_mfma_f32_16x16x32_bf16 v[28:31], v[128:131], v[204:207], v[28:31]
	v_mfma_f32_16x16x32_bf16 v[24:27], v[136:139], v[204:207], v[24:27]
	v_mfma_f32_16x16x32_bf16 v[12:15], v[128:131], v[212:215], v[12:15]
	v_mfma_f32_16x16x32_bf16 v[8:11], v[136:139], v[212:215], v[8:11]
	v_mfma_f32_16x16x32_bf16 v[60:63], v[132:135], v[192:195], v[60:63]
	v_mfma_f32_16x16x32_bf16 v[56:59], v[140:143], v[192:195], v[56:59]
	v_mfma_f32_16x16x32_bf16 v[44:47], v[132:135], v[200:203], v[44:47]
	v_mfma_f32_16x16x32_bf16 v[40:43], v[140:143], v[200:203], v[40:43]
	v_mfma_f32_16x16x32_bf16 v[28:31], v[132:135], v[208:211], v[28:31]
	v_mfma_f32_16x16x32_bf16 v[24:27], v[140:143], v[208:211], v[24:27]
	v_mfma_f32_16x16x32_bf16 v[12:15], v[132:135], v[216:219], v[12:15]
	v_mfma_f32_16x16x32_bf16 v[8:11], v[140:143], v[216:219], v[8:11]
	v_mfma_f32_16x16x32_bf16 v[52:55], v[144:147], v[180:183], v[52:55]
	v_mfma_f32_16x16x32_bf16 v[48:51], v[172:175], v[180:183], v[48:51]
	v_mfma_f32_16x16x32_bf16 v[36:39], v[144:147], v[196:199], v[36:39]
	v_mfma_f32_16x16x32_bf16 v[32:35], v[172:175], v[196:199], v[32:35]
	v_mfma_f32_16x16x32_bf16 v[20:23], v[144:147], v[204:207], v[20:23]
	v_mfma_f32_16x16x32_bf16 v[16:19], v[172:175], v[204:207], v[16:19]
	v_mfma_f32_16x16x32_bf16 v[4:7], v[144:147], v[212:215], v[4:7]
	v_mfma_f32_16x16x32_bf16 v[0:3], v[172:175], v[212:215], v[0:3]
	v_mfma_f32_16x16x32_bf16 v[52:55], v[148:151], v[192:195], v[52:55]
	v_mfma_f32_16x16x32_bf16 v[48:51], v[176:179], v[192:195], v[48:51]
	v_mfma_f32_16x16x32_bf16 v[36:39], v[148:151], v[200:203], v[36:39]
	v_mfma_f32_16x16x32_bf16 v[32:35], v[176:179], v[200:203], v[32:35]
	v_mfma_f32_16x16x32_bf16 v[20:23], v[148:151], v[208:211], v[20:23]
	v_mfma_f32_16x16x32_bf16 v[16:19], v[176:179], v[208:211], v[16:19]
	v_mfma_f32_16x16x32_bf16 v[4:7], v[148:151], v[216:219], v[4:7]
	v_mfma_f32_16x16x32_bf16 v[0:3], v[176:179], v[216:219], v[0:3]
	s_barrier
	s_add_i32 s53, s53, 2
	s_add_u32 s28, s28, 0x100
	s_addc_u32 s29, s29, 0
	s_add_u32 s51, s51, 0x100
	s_addc_u32 s52, s52, 0
	s_cmp_gt_u32 s53, 13
	s_cbranch_scc1 .Lpeel_exit_1886

.Lpeel_exit_1886:
	s_and_b64 vcc, exec, s[14:15]
	s_cbranch_vccz .LBB0_1889
	s_barrier

.LBB0_1974:
	s_ashr_i32 s15, s14, 31
	s_lshl_b64 s[18:19], s[14:15], 19
	s_add_u32 s18, s82, s18
	s_addc_u32 s19, s83, s19
	s_and_b64 s[20:21], s[4:5], exec
	s_cselect_b32 s15, s19, s25
	s_cselect_b32 s47, s18, s24
	s_ashr_i32 s17, s16, 31
	s_lshl_b64 s[20:21], s[16:17], 19
	s_add_u32 s20, s3, s20
	s_addc_u32 s21, s30, s21
	s_and_b64 s[28:29], s[4:5], exec
	s_cselect_b32 s17, s21, s27
	s_cselect_b32 s48, s20, s26
	s_add_u32 s24, s24, 0x40080
	s_addc_u32 s25, s25, 0
	s_add_u32 s49, s26, 0x100
	s_addc_u32 s50, s27, 0
	s_mov_b32 s51, -2
	ds_read_b128 v[144:147], v155
	ds_read_b128 v[160:163], v155 offset:1024
	ds_read_b128 v[164:167], v155 offset:2048
	ds_read_b128 v[168:171], v155 offset:3072
	ds_read_b128 v[172:175], v157
	ds_read_b128 v[176:179], v157 offset:1024
	ds_read_b128 v[180:183], v157 offset:2048
	ds_read_b128 v[186:189], v157 offset:3072
	s_add_u32 s26, s24, 0xfffc0080
	s_addc_u32 s27, s25, -1
	s_cmp_eq_u32 s51, 12
	s_cselect_b32 s29, s15, s27
	s_cselect_b32 s28, s47, s26
	s_cselect_b32 s27, s17, s50
	s_cselect_b32 s26, s48, s49
	s_add_i32 m0, s23, 0xc000
	ds_read_b128 v[190:193], v158
	ds_read_b128 v[194:197], v158 offset:1024
	ds_read_b128 v[198:201], v158 offset:2048
	ds_read_b128 v[202:205], v158 offset:3072
	ds_read_b128 v[206:209], v158 offset:4096
	ds_read_b128 v[210:213], v158 offset:5120
	ds_read_b128 v[214:217], v158 offset:6144
	ds_read_b128 v[218:221], v158 offset:7168
	global_load_lds_dwordx4 v136, s[24:25]
	s_add_i32 m0, s23, 0xe000
	s_nop 0
	global_load_lds_dwordx4 v138, s[24:25]
	s_waitcnt vmcnt(8)
	s_waitcnt lgkmcnt(0)
	s_barrier
	s_waitcnt lgkmcnt(0)
	v_mfma_f32_16x16x32_bf16 v[124:127], v[144:147], v[190:193], 0
	v_mfma_f32_16x16x32_bf16 v[120:123], v[164:167], v[190:193], 0
	v_mfma_f32_16x16x32_bf16 v[116:119], v[144:147], v[198:201], 0
	v_mfma_f32_16x16x32_bf16 v[104:107], v[164:167], v[198:201], 0
	v_mfma_f32_16x16x32_bf16 v[92:95], v[144:147], v[206:209], 0
	v_mfma_f32_16x16x32_bf16 v[88:91], v[164:167], v[206:209], 0
	v_mfma_f32_16x16x32_bf16 v[76:79], v[144:147], v[214:217], 0
	v_mfma_f32_16x16x32_bf16 v[72:75], v[164:167], v[214:217], 0
	v_mfma_f32_16x16x32_bf16 v[124:127], v[160:163], v[194:197], v[124:127]
	v_mfma_f32_16x16x32_bf16 v[120:123], v[168:171], v[194:197], v[120:123]
	v_mfma_f32_16x16x32_bf16 v[116:119], v[160:163], v[202:205], v[116:119]
	v_mfma_f32_16x16x32_bf16 v[104:107], v[168:171], v[202:205], v[104:107]
	v_mfma_f32_16x16x32_bf16 v[92:95], v[160:163], v[210:213], v[92:95]
	v_mfma_f32_16x16x32_bf16 v[88:91], v[168:171], v[210:213], v[88:91]
	v_mfma_f32_16x16x32_bf16 v[76:79], v[160:163], v[218:221], v[76:79]
	v_mfma_f32_16x16x32_bf16 v[72:75], v[168:171], v[218:221], v[72:75]
	v_mfma_f32_16x16x32_bf16 v[112:115], v[172:175], v[190:193], 0
	v_mfma_f32_16x16x32_bf16 v[108:111], v[180:183], v[190:193], 0
	v_mfma_f32_16x16x32_bf16 v[100:103], v[172:175], v[198:201], 0
	v_mfma_f32_16x16x32_bf16 v[96:99], v[180:183], v[198:201], 0
	v_mfma_f32_16x16x32_bf16 v[84:87], v[172:175], v[206:209], 0
	v_mfma_f32_16x16x32_bf16 v[80:83], v[180:183], v[206:209], 0
	v_mfma_f32_16x16x32_bf16 v[68:71], v[172:175], v[214:217], 0
	v_mfma_f32_16x16x32_bf16 v[64:67], v[180:183], v[214:217], 0
	v_mfma_f32_16x16x32_bf16 v[112:115], v[176:179], v[194:197], v[112:115]
	v_mfma_f32_16x16x32_bf16 v[108:111], v[186:189], v[194:197], v[108:111]
	v_mfma_f32_16x16x32_bf16 v[100:103], v[176:179], v[202:205], v[100:103]
	v_mfma_f32_16x16x32_bf16 v[96:99], v[186:189], v[202:205], v[96:99]
	v_mfma_f32_16x16x32_bf16 v[84:87], v[176:179], v[210:213], v[84:87]
	v_mfma_f32_16x16x32_bf16 v[80:83], v[186:189], v[210:213], v[80:83]
	v_mfma_f32_16x16x32_bf16 v[68:71], v[176:179], v[218:221], v[68:71]
	v_mfma_f32_16x16x32_bf16 v[64:67], v[186:189], v[218:221], v[64:67]
	s_barrier
	s_add_i32 s52, s43, s31
	s_mov_b32 m0, s52
	ds_read_b128 v[190:193], v158 offset:16384
	ds_read_b128 v[194:197], v158 offset:17408
	ds_read_b128 v[198:201], v158 offset:18432
	ds_read_b128 v[202:205], v158 offset:19456
	ds_read_b128 v[206:209], v158 offset:20480
	ds_read_b128 v[210:213], v158 offset:21504
	ds_read_b128 v[214:217], v158 offset:22528
	ds_read_b128 v[218:221], v158 offset:23552
	global_load_lds_dwordx4 v132, s[26:27]
	s_add_i32 m0, s52, 0x2000
	s_add_u32 s52, s26, 0x40000
	s_addc_u32 s53, s27, 0
	s_add_i32 s54, s44, s31
	global_load_lds_dwordx4 v128, s[26:27]
	s_mov_b32 m0, s54
	global_load_lds_dwordx4 v132, s[52:53]
	s_add_i32 m0, s54, 0x2000
	s_nop 0
	global_load_lds_dwordx4 v128, s[52:53]
	s_mov_b32 m0, s23
	s_nop 0
	global_load_lds_dwordx4 v134, s[28:29]
	s_mov_b32 m0, s35
	s_nop 0
	global_load_lds_dwordx4 v130, s[28:29]
	s_add_u32 s98, s26, s10
	s_addc_u32 s99, s27, s11
	s_add_u32 s100, s28, s10
	s_addc_u32 s101, s29, s11
	s_waitcnt vmcnt(8)
	s_waitcnt lgkmcnt(0)
	s_barrier
	s_waitcnt lgkmcnt(0)
	v_mfma_f32_16x16x32_bf16 v[60:63], v[144:147], v[190:193], 0
	v_mfma_f32_16x16x32_bf16 v[56:59], v[164:167], v[190:193], 0
	v_mfma_f32_16x16x32_bf16 v[44:47], v[144:147], v[198:201], 0
	v_mfma_f32_16x16x32_bf16 v[40:43], v[164:167], v[198:201], 0
	v_mfma_f32_16x16x32_bf16 v[28:31], v[144:147], v[206:209], 0
	v_mfma_f32_16x16x32_bf16 v[24:27], v[164:167], v[206:209], 0
	v_mfma_f32_16x16x32_bf16 v[12:15], v[144:147], v[214:217], 0
	v_mfma_f32_16x16x32_bf16 v[8:11], v[164:167], v[214:217], 0
	v_mfma_f32_16x16x32_bf16 v[60:63], v[160:163], v[194:197], v[60:63]
	v_mfma_f32_16x16x32_bf16 v[56:59], v[168:171], v[194:197], v[56:59]
	v_mfma_f32_16x16x32_bf16 v[44:47], v[160:163], v[202:205], v[44:47]
	v_mfma_f32_16x16x32_bf16 v[40:43], v[168:171], v[202:205], v[40:43]
	v_mfma_f32_16x16x32_bf16 v[28:31], v[160:163], v[210:213], v[28:31]
	v_mfma_f32_16x16x32_bf16 v[24:27], v[168:171], v[210:213], v[24:27]
	v_mfma_f32_16x16x32_bf16 v[12:15], v[160:163], v[218:221], v[12:15]
	v_mfma_f32_16x16x32_bf16 v[8:11], v[168:171], v[218:221], v[8:11]
	v_mfma_f32_16x16x32_bf16 v[52:55], v[172:175], v[190:193], 0
	v_mfma_f32_16x16x32_bf16 v[48:51], v[180:183], v[190:193], 0
	v_mfma_f32_16x16x32_bf16 v[36:39], v[172:175], v[198:201], 0
	v_mfma_f32_16x16x32_bf16 v[32:35], v[180:183], v[198:201], 0
	v_mfma_f32_16x16x32_bf16 v[20:23], v[172:175], v[206:209], 0
	v_mfma_f32_16x16x32_bf16 v[16:19], v[180:183], v[206:209], 0
	v_mfma_f32_16x16x32_bf16 v[4:7], v[172:175], v[214:217], 0
	v_mfma_f32_16x16x32_bf16 v[0:3], v[180:183], v[214:217], 0
	v_mfma_f32_16x16x32_bf16 v[52:55], v[176:179], v[194:197], v[52:55]
	v_mfma_f32_16x16x32_bf16 v[48:51], v[186:189], v[194:197], v[48:51]
	v_mfma_f32_16x16x32_bf16 v[36:39], v[176:179], v[202:205], v[36:39]
	v_mfma_f32_16x16x32_bf16 v[32:35], v[186:189], v[202:205], v[32:35]
	v_mfma_f32_16x16x32_bf16 v[20:23], v[176:179], v[210:213], v[20:23]
	v_mfma_f32_16x16x32_bf16 v[16:19], v[186:189], v[210:213], v[16:19]
	v_mfma_f32_16x16x32_bf16 v[4:7], v[176:179], v[218:221], v[4:7]
	v_mfma_f32_16x16x32_bf16 v[0:3], v[186:189], v[218:221], v[0:3]
	s_barrier
	s_add_i32 s52, 0, 0x18000
	v_add_u32_e32 v148, s52, v151
	s_add_i32 s53, 0, 0x1c000
	ds_read_b128 v[144:147], v148
	ds_read_b128 v[160:163], v148 offset:1024
	ds_read_b128 v[164:167], v148 offset:2048
	ds_read_b128 v[168:171], v148 offset:3072
	v_add_u32_e32 v148, s53, v151
	ds_read_b128 v[172:175], v148
	ds_read_b128 v[176:179], v148 offset:1024
	ds_read_b128 v[180:183], v148 offset:2048
	ds_read_b128 v[186:189], v148 offset:3072
	s_add_u32 s28, s28, 0x40000
	s_addc_u32 s29, s29, 0
	s_mov_b32 m0, s36
	ds_read_b128 v[190:193], v158 offset:32768
	ds_read_b128 v[194:197], v158 offset:33792
	ds_read_b128 v[198:201], v158 offset:34816
	ds_read_b128 v[202:205], v158 offset:35840
	ds_read_b128 v[206:209], v158 offset:36864
	ds_read_b128 v[210:213], v158 offset:37888
	ds_read_b128 v[214:217], v158 offset:38912
	ds_read_b128 v[218:221], v158 offset:39936
	global_load_lds_dwordx4 v134, s[28:29]
	s_mov_b32 m0, s37
	s_nop 0
	global_load_lds_dwordx4 v130, s[28:29]
	s_waitcnt vmcnt(8)
	s_waitcnt lgkmcnt(0)
	s_barrier
	s_waitcnt lgkmcnt(0)
	v_mfma_f32_16x16x32_bf16 v[124:127], v[144:147], v[190:193], v[124:127]
	v_mfma_f32_16x16x32_bf16 v[120:123], v[164:167], v[190:193], v[120:123]
	v_mfma_f32_16x16x32_bf16 v[116:119], v[144:147], v[198:201], v[116:119]
	v_mfma_f32_16x16x32_bf16 v[104:107], v[164:167], v[198:201], v[104:107]
	v_mfma_f32_16x16x32_bf16 v[92:95], v[144:147], v[206:209], v[92:95]
	v_mfma_f32_16x16x32_bf16 v[88:91], v[164:167], v[206:209], v[88:91]
	v_mfma_f32_16x16x32_bf16 v[76:79], v[144:147], v[214:217], v[76:79]
	v_mfma_f32_16x16x32_bf16 v[72:75], v[164:167], v[214:217], v[72:75]
	v_mfma_f32_16x16x32_bf16 v[124:127], v[160:163], v[194:197], v[124:127]
	v_mfma_f32_16x16x32_bf16 v[120:123], v[168:171], v[194:197], v[120:123]
	v_mfma_f32_16x16x32_bf16 v[116:119], v[160:163], v[202:205], v[116:119]
	v_mfma_f32_16x16x32_bf16 v[104:107], v[168:171], v[202:205], v[104:107]
	v_mfma_f32_16x16x32_bf16 v[92:95], v[160:163], v[210:213], v[92:95]
	v_mfma_f32_16x16x32_bf16 v[88:91], v[168:171], v[210:213], v[88:91]
	v_mfma_f32_16x16x32_bf16 v[76:79], v[160:163], v[218:221], v[76:79]
	v_mfma_f32_16x16x32_bf16 v[72:75], v[168:171], v[218:221], v[72:75]
	v_mfma_f32_16x16x32_bf16 v[112:115], v[172:175], v[190:193], v[112:115]
	v_mfma_f32_16x16x32_bf16 v[108:111], v[180:183], v[190:193], v[108:111]
	v_mfma_f32_16x16x32_bf16 v[100:103], v[172:175], v[198:201], v[100:103]
	v_mfma_f32_16x16x32_bf16 v[96:99], v[180:183], v[198:201], v[96:99]
	v_mfma_f32_16x16x32_bf16 v[84:87], v[172:175], v[206:209], v[84:87]
	v_mfma_f32_16x16x32_bf16 v[80:83], v[180:183], v[206:209], v[80:83]
	v_mfma_f32_16x16x32_bf16 v[68:71], v[172:175], v[214:217], v[68:71]
	v_mfma_f32_16x16x32_bf16 v[64:67], v[180:183], v[214:217], v[64:67]
	v_mfma_f32_16x16x32_bf16 v[112:115], v[176:179], v[194:197], v[112:115]
	v_mfma_f32_16x16x32_bf16 v[108:111], v[186:189], v[194:197], v[108:111]
	v_mfma_f32_16x16x32_bf16 v[100:103], v[176:179], v[202:205], v[100:103]
	v_mfma_f32_16x16x32_bf16 v[96:99], v[186:189], v[202:205], v[96:99]
	v_mfma_f32_16x16x32_bf16 v[84:87], v[176:179], v[210:213], v[84:87]
	v_mfma_f32_16x16x32_bf16 v[80:83], v[186:189], v[210:213], v[80:83]
	v_mfma_f32_16x16x32_bf16 v[68:71], v[176:179], v[218:221], v[68:71]
	v_mfma_f32_16x16x32_bf16 v[64:67], v[186:189], v[218:221], v[64:67]
	s_barrier
	s_add_i32 s28, s52, s31
	s_mov_b32 m0, s28
	ds_read_b128 v[190:193], v158 offset:49152
	ds_read_b128 v[194:197], v158 offset:50176
	ds_read_b128 v[198:201], v158 offset:51200
	ds_read_b128 v[202:205], v158 offset:52224
	ds_read_b128 v[206:209], v158 offset:53248
	ds_read_b128 v[210:213], v158 offset:54272
	ds_read_b128 v[214:217], v158 offset:55296
	ds_read_b128 v[218:221], v158 offset:56320
	global_load_lds_dwordx4 v132, s[98:99]
	s_add_i32 m0, s28, 0x2000
	s_add_u32 s26, s26, 0x40080
	s_addc_u32 s27, s27, 0
	s_add_i32 s28, s53, s31
	global_load_lds_dwordx4 v128, s[98:99]
	s_mov_b32 m0, s28
	s_nop 0
	global_load_lds_dwordx4 v132, s[26:27]
	s_add_i32 m0, s28, 0x2000
	s_nop 0
	global_load_lds_dwordx4 v128, s[26:27]
	s_mov_b32 m0, s39
	s_nop 0
	global_load_lds_dwordx4 v134, s[100:101]
	s_mov_b32 m0, s40
	s_nop 0
	global_load_lds_dwordx4 v130, s[100:101]
	s_waitcnt vmcnt(8)
	s_waitcnt lgkmcnt(0)
	s_barrier
	s_waitcnt lgkmcnt(0)
	v_mfma_f32_16x16x32_bf16 v[60:63], v[144:147], v[190:193], v[60:63]
	v_mfma_f32_16x16x32_bf16 v[56:59], v[164:167], v[190:193], v[56:59]
	v_mfma_f32_16x16x32_bf16 v[44:47], v[144:147], v[198:201], v[44:47]
	v_mfma_f32_16x16x32_bf16 v[40:43], v[164:167], v[198:201], v[40:43]
	v_mfma_f32_16x16x32_bf16 v[28:31], v[144:147], v[206:209], v[28:31]
	v_mfma_f32_16x16x32_bf16 v[24:27], v[164:167], v[206:209], v[24:27]
	v_mfma_f32_16x16x32_bf16 v[12:15], v[144:147], v[214:217], v[12:15]
	v_mfma_f32_16x16x32_bf16 v[8:11], v[164:167], v[214:217], v[8:11]
	v_mfma_f32_16x16x32_bf16 v[60:63], v[160:163], v[194:197], v[60:63]
	v_mfma_f32_16x16x32_bf16 v[56:59], v[168:171], v[194:197], v[56:59]
	v_mfma_f32_16x16x32_bf16 v[44:47], v[160:163], v[202:205], v[44:47]
	v_mfma_f32_16x16x32_bf16 v[40:43], v[168:171], v[202:205], v[40:43]
	v_mfma_f32_16x16x32_bf16 v[28:31], v[160:163], v[210:213], v[28:31]
	v_mfma_f32_16x16x32_bf16 v[24:27], v[168:171], v[210:213], v[24:27]
	v_mfma_f32_16x16x32_bf16 v[12:15], v[160:163], v[218:221], v[12:15]
	v_mfma_f32_16x16x32_bf16 v[8:11], v[168:171], v[218:221], v[8:11]
	v_mfma_f32_16x16x32_bf16 v[52:55], v[172:175], v[190:193], v[52:55]
	v_mfma_f32_16x16x32_bf16 v[48:51], v[180:183], v[190:193], v[48:51]
	v_mfma_f32_16x16x32_bf16 v[36:39], v[172:175], v[198:201], v[36:39]
	v_mfma_f32_16x16x32_bf16 v[32:35], v[180:183], v[198:201], v[32:35]
	v_mfma_f32_16x16x32_bf16 v[20:23], v[172:175], v[206:209], v[20:23]
	v_mfma_f32_16x16x32_bf16 v[16:19], v[180:183], v[206:209], v[16:19]
	v_mfma_f32_16x16x32_bf16 v[4:7], v[172:175], v[214:217], v[4:7]
	v_mfma_f32_16x16x32_bf16 v[0:3], v[180:183], v[214:217], v[0:3]
	v_mfma_f32_16x16x32_bf16 v[52:55], v[176:179], v[194:197], v[52:55]
	v_mfma_f32_16x16x32_bf16 v[48:51], v[186:189], v[194:197], v[48:51]
	v_mfma_f32_16x16x32_bf16 v[36:39], v[176:179], v[202:205], v[36:39]
	v_mfma_f32_16x16x32_bf16 v[32:35], v[186:189], v[202:205], v[32:35]
	v_mfma_f32_16x16x32_bf16 v[20:23], v[176:179], v[210:213], v[20:23]
	v_mfma_f32_16x16x32_bf16 v[16:19], v[186:189], v[210:213], v[16:19]
	v_mfma_f32_16x16x32_bf16 v[4:7], v[176:179], v[218:221], v[4:7]
	v_mfma_f32_16x16x32_bf16 v[0:3], v[186:189], v[218:221], v[0:3]
	s_barrier
	s_add_i32 s51, s51, 2
	s_add_u32 s24, s24, 0x100
	s_addc_u32 s25, s25, 0
	s_add_u32 s49, s49, 0x100
	s_addc_u32 s50, s50, 0
	s_cmp_gt_u32 s51, 13
	s_cbranch_scc1 .Lpeel_exit_1975
.LBB0_1975:
	ds_read_b128 v[144:147], v155
	ds_read_b128 v[160:163], v155 offset:1024
	ds_read_b128 v[164:167], v155 offset:2048
	ds_read_b128 v[168:171], v155 offset:3072
	ds_read_b128 v[172:175], v157
	ds_read_b128 v[176:179], v157 offset:1024
	ds_read_b128 v[180:183], v157 offset:2048
	ds_read_b128 v[186:189], v157 offset:3072
	s_add_u32 s26, s24, 0xfffc0080
	s_addc_u32 s27, s25, -1
	s_cmp_eq_u32 s51, 12
	s_cselect_b32 s29, s15, s27
	s_cselect_b32 s28, s47, s26
	s_cselect_b32 s27, s17, s50
	s_cselect_b32 s26, s48, s49
	s_add_i32 m0, s23, 0xc000
	ds_read_b128 v[190:193], v158
	ds_read_b128 v[194:197], v158 offset:1024
	ds_read_b128 v[198:201], v158 offset:2048
	ds_read_b128 v[202:205], v158 offset:3072
	ds_read_b128 v[206:209], v158 offset:4096
	ds_read_b128 v[210:213], v158 offset:5120
	ds_read_b128 v[214:217], v158 offset:6144
	ds_read_b128 v[218:221], v158 offset:7168
	global_load_lds_dwordx4 v136, s[24:25]
	s_add_i32 m0, s23, 0xe000
	s_nop 0
	global_load_lds_dwordx4 v138, s[24:25]
	s_waitcnt vmcnt(8)
	s_waitcnt lgkmcnt(0)
	s_barrier
	s_waitcnt lgkmcnt(0)
	v_mfma_f32_16x16x32_bf16 v[124:127], v[144:147], v[190:193], v[124:127]
	v_mfma_f32_16x16x32_bf16 v[120:123], v[164:167], v[190:193], v[120:123]
	v_mfma_f32_16x16x32_bf16 v[116:119], v[144:147], v[198:201], v[116:119]
	v_mfma_f32_16x16x32_bf16 v[104:107], v[164:167], v[198:201], v[104:107]
	v_mfma_f32_16x16x32_bf16 v[92:95], v[144:147], v[206:209], v[92:95]
	v_mfma_f32_16x16x32_bf16 v[88:91], v[164:167], v[206:209], v[88:91]
	v_mfma_f32_16x16x32_bf16 v[76:79], v[144:147], v[214:217], v[76:79]
	v_mfma_f32_16x16x32_bf16 v[72:75], v[164:167], v[214:217], v[72:75]
	v_mfma_f32_16x16x32_bf16 v[124:127], v[160:163], v[194:197], v[124:127]
	v_mfma_f32_16x16x32_bf16 v[120:123], v[168:171], v[194:197], v[120:123]
	v_mfma_f32_16x16x32_bf16 v[116:119], v[160:163], v[202:205], v[116:119]
	v_mfma_f32_16x16x32_bf16 v[104:107], v[168:171], v[202:205], v[104:107]
	v_mfma_f32_16x16x32_bf16 v[92:95], v[160:163], v[210:213], v[92:95]
	v_mfma_f32_16x16x32_bf16 v[88:91], v[168:171], v[210:213], v[88:91]
	v_mfma_f32_16x16x32_bf16 v[76:79], v[160:163], v[218:221], v[76:79]
	v_mfma_f32_16x16x32_bf16 v[72:75], v[168:171], v[218:221], v[72:75]
	v_mfma_f32_16x16x32_bf16 v[112:115], v[172:175], v[190:193], v[112:115]
	v_mfma_f32_16x16x32_bf16 v[108:111], v[180:183], v[190:193], v[108:111]
	v_mfma_f32_16x16x32_bf16 v[100:103], v[172:175], v[198:201], v[100:103]
	v_mfma_f32_16x16x32_bf16 v[96:99], v[180:183], v[198:201], v[96:99]
	v_mfma_f32_16x16x32_bf16 v[84:87], v[172:175], v[206:209], v[84:87]
	v_mfma_f32_16x16x32_bf16 v[80:83], v[180:183], v[206:209], v[80:83]
	v_mfma_f32_16x16x32_bf16 v[68:71], v[172:175], v[214:217], v[68:71]
	v_mfma_f32_16x16x32_bf16 v[64:67], v[180:183], v[214:217], v[64:67]
	v_mfma_f32_16x16x32_bf16 v[112:115], v[176:179], v[194:197], v[112:115]
	v_mfma_f32_16x16x32_bf16 v[108:111], v[186:189], v[194:197], v[108:111]
	v_mfma_f32_16x16x32_bf16 v[100:103], v[176:179], v[202:205], v[100:103]
	v_mfma_f32_16x16x32_bf16 v[96:99], v[186:189], v[202:205], v[96:99]
	v_mfma_f32_16x16x32_bf16 v[84:87], v[176:179], v[210:213], v[84:87]
	v_mfma_f32_16x16x32_bf16 v[80:83], v[186:189], v[210:213], v[80:83]
	v_mfma_f32_16x16x32_bf16 v[68:71], v[176:179], v[218:221], v[68:71]
	v_mfma_f32_16x16x32_bf16 v[64:67], v[186:189], v[218:221], v[64:67]
	s_barrier
	s_add_i32 s52, s43, s31
	s_mov_b32 m0, s52
	ds_read_b128 v[190:193], v158 offset:16384
	ds_read_b128 v[194:197], v158 offset:17408
	ds_read_b128 v[198:201], v158 offset:18432
	ds_read_b128 v[202:205], v158 offset:19456
	ds_read_b128 v[206:209], v158 offset:20480
	ds_read_b128 v[210:213], v158 offset:21504
	ds_read_b128 v[214:217], v158 offset:22528
	ds_read_b128 v[218:221], v158 offset:23552
	global_load_lds_dwordx4 v132, s[26:27]
	s_add_i32 m0, s52, 0x2000
	s_add_u32 s52, s26, 0x40000
	s_addc_u32 s53, s27, 0
	s_add_i32 s54, s44, s31
	global_load_lds_dwordx4 v128, s[26:27]
	s_mov_b32 m0, s54
	global_load_lds_dwordx4 v132, s[52:53]
	s_add_i32 m0, s54, 0x2000
	s_nop 0
	global_load_lds_dwordx4 v128, s[52:53]
	s_mov_b32 m0, s23
	s_nop 0
	global_load_lds_dwordx4 v134, s[28:29]
	s_mov_b32 m0, s35
	s_nop 0
	global_load_lds_dwordx4 v130, s[28:29]
	s_add_u32 s98, s26, s10
	s_addc_u32 s99, s27, s11
	s_add_u32 s100, s28, s10
	s_addc_u32 s101, s29, s11
	s_waitcnt vmcnt(8)
	s_waitcnt lgkmcnt(0)
	s_barrier
	s_waitcnt lgkmcnt(0)
	v_mfma_f32_16x16x32_bf16 v[60:63], v[144:147], v[190:193], v[60:63]
	v_mfma_f32_16x16x32_bf16 v[56:59], v[164:167], v[190:193], v[56:59]
	v_mfma_f32_16x16x32_bf16 v[44:47], v[144:147], v[198:201], v[44:47]
	v_mfma_f32_16x16x32_bf16 v[40:43], v[164:167], v[198:201], v[40:43]
	v_mfma_f32_16x16x32_bf16 v[28:31], v[144:147], v[206:209], v[28:31]
	v_mfma_f32_16x16x32_bf16 v[24:27], v[164:167], v[206:209], v[24:27]
	v_mfma_f32_16x16x32_bf16 v[12:15], v[144:147], v[214:217], v[12:15]
	v_mfma_f32_16x16x32_bf16 v[8:11], v[164:167], v[214:217], v[8:11]
	v_mfma_f32_16x16x32_bf16 v[60:63], v[160:163], v[194:197], v[60:63]
	v_mfma_f32_16x16x32_bf16 v[56:59], v[168:171], v[194:197], v[56:59]
	v_mfma_f32_16x16x32_bf16 v[44:47], v[160:163], v[202:205], v[44:47]
	v_mfma_f32_16x16x32_bf16 v[40:43], v[168:171], v[202:205], v[40:43]
	v_mfma_f32_16x16x32_bf16 v[28:31], v[160:163], v[210:213], v[28:31]
	v_mfma_f32_16x16x32_bf16 v[24:27], v[168:171], v[210:213], v[24:27]
	v_mfma_f32_16x16x32_bf16 v[12:15], v[160:163], v[218:221], v[12:15]
	v_mfma_f32_16x16x32_bf16 v[8:11], v[168:171], v[218:221], v[8:11]
	v_mfma_f32_16x16x32_bf16 v[52:55], v[172:175], v[190:193], v[52:55]
	v_mfma_f32_16x16x32_bf16 v[48:51], v[180:183], v[190:193], v[48:51]
	v_mfma_f32_16x16x32_bf16 v[36:39], v[172:175], v[198:201], v[36:39]
	v_mfma_f32_16x16x32_bf16 v[32:35], v[180:183], v[198:201], v[32:35]
	v_mfma_f32_16x16x32_bf16 v[20:23], v[172:175], v[206:209], v[20:23]
	v_mfma_f32_16x16x32_bf16 v[16:19], v[180:183], v[206:209], v[16:19]
	v_mfma_f32_16x16x32_bf16 v[4:7], v[172:175], v[214:217], v[4:7]
	v_mfma_f32_16x16x32_bf16 v[0:3], v[180:183], v[214:217], v[0:3]
	v_mfma_f32_16x16x32_bf16 v[52:55], v[176:179], v[194:197], v[52:55]
	v_mfma_f32_16x16x32_bf16 v[48:51], v[186:189], v[194:197], v[48:51]
	v_mfma_f32_16x16x32_bf16 v[36:39], v[176:179], v[202:205], v[36:39]
	v_mfma_f32_16x16x32_bf16 v[32:35], v[186:189], v[202:205], v[32:35]
	v_mfma_f32_16x16x32_bf16 v[20:23], v[176:179], v[210:213], v[20:23]
	v_mfma_f32_16x16x32_bf16 v[16:19], v[186:189], v[210:213], v[16:19]
	v_mfma_f32_16x16x32_bf16 v[4:7], v[176:179], v[218:221], v[4:7]
	v_mfma_f32_16x16x32_bf16 v[0:3], v[186:189], v[218:221], v[0:3]
	s_barrier
	s_add_i32 s52, 0, 0x18000
	v_add_u32_e32 v148, s52, v151
	s_add_i32 s53, 0, 0x1c000
	ds_read_b128 v[144:147], v148
	ds_read_b128 v[160:163], v148 offset:1024
	ds_read_b128 v[164:167], v148 offset:2048
	ds_read_b128 v[168:171], v148 offset:3072
	v_add_u32_e32 v148, s53, v151
	ds_read_b128 v[172:175], v148
	ds_read_b128 v[176:179], v148 offset:1024
	ds_read_b128 v[180:183], v148 offset:2048
	ds_read_b128 v[186:189], v148 offset:3072
	s_add_u32 s28, s28, 0x40000
	s_addc_u32 s29, s29, 0
	s_mov_b32 m0, s36
	ds_read_b128 v[190:193], v158 offset:32768
	ds_read_b128 v[194:197], v158 offset:33792
	ds_read_b128 v[198:201], v158 offset:34816
	ds_read_b128 v[202:205], v158 offset:35840
	ds_read_b128 v[206:209], v158 offset:36864
	ds_read_b128 v[210:213], v158 offset:37888
	ds_read_b128 v[214:217], v158 offset:38912
	ds_read_b128 v[218:221], v158 offset:39936
	global_load_lds_dwordx4 v134, s[28:29]
	s_mov_b32 m0, s37
	s_nop 0
	global_load_lds_dwordx4 v130, s[28:29]
	s_waitcnt vmcnt(8)
	s_waitcnt lgkmcnt(0)
	s_barrier
	s_waitcnt lgkmcnt(0)
	v_mfma_f32_16x16x32_bf16 v[124:127], v[144:147], v[190:193], v[124:127]
	v_mfma_f32_16x16x32_bf16 v[120:123], v[164:167], v[190:193], v[120:123]
	v_mfma_f32_16x16x32_bf16 v[116:119], v[144:147], v[198:201], v[116:119]
	v_mfma_f32_16x16x32_bf16 v[104:107], v[164:167], v[198:201], v[104:107]
	v_mfma_f32_16x16x32_bf16 v[92:95], v[144:147], v[206:209], v[92:95]
	v_mfma_f32_16x16x32_bf16 v[88:91], v[164:167], v[206:209], v[88:91]
	v_mfma_f32_16x16x32_bf16 v[76:79], v[144:147], v[214:217], v[76:79]
	v_mfma_f32_16x16x32_bf16 v[72:75], v[164:167], v[214:217], v[72:75]
	v_mfma_f32_16x16x32_bf16 v[124:127], v[160:163], v[194:197], v[124:127]
	v_mfma_f32_16x16x32_bf16 v[120:123], v[168:171], v[194:197], v[120:123]
	v_mfma_f32_16x16x32_bf16 v[116:119], v[160:163], v[202:205], v[116:119]
	v_mfma_f32_16x16x32_bf16 v[104:107], v[168:171], v[202:205], v[104:107]
	v_mfma_f32_16x16x32_bf16 v[92:95], v[160:163], v[210:213], v[92:95]
	v_mfma_f32_16x16x32_bf16 v[88:91], v[168:171], v[210:213], v[88:91]
	v_mfma_f32_16x16x32_bf16 v[76:79], v[160:163], v[218:221], v[76:79]
	v_mfma_f32_16x16x32_bf16 v[72:75], v[168:171], v[218:221], v[72:75]
	v_mfma_f32_16x16x32_bf16 v[112:115], v[172:175], v[190:193], v[112:115]
	v_mfma_f32_16x16x32_bf16 v[108:111], v[180:183], v[190:193], v[108:111]
	v_mfma_f32_16x16x32_bf16 v[100:103], v[172:175], v[198:201], v[100:103]
	v_mfma_f32_16x16x32_bf16 v[96:99], v[180:183], v[198:201], v[96:99]
	v_mfma_f32_16x16x32_bf16 v[84:87], v[172:175], v[206:209], v[84:87]
	v_mfma_f32_16x16x32_bf16 v[80:83], v[180:183], v[206:209], v[80:83]
	v_mfma_f32_16x16x32_bf16 v[68:71], v[172:175], v[214:217], v[68:71]
	v_mfma_f32_16x16x32_bf16 v[64:67], v[180:183], v[214:217], v[64:67]
	v_mfma_f32_16x16x32_bf16 v[112:115], v[176:179], v[194:197], v[112:115]
	v_mfma_f32_16x16x32_bf16 v[108:111], v[186:189], v[194:197], v[108:111]
	v_mfma_f32_16x16x32_bf16 v[100:103], v[176:179], v[202:205], v[100:103]
	v_mfma_f32_16x16x32_bf16 v[96:99], v[186:189], v[202:205], v[96:99]
	v_mfma_f32_16x16x32_bf16 v[84:87], v[176:179], v[210:213], v[84:87]
	v_mfma_f32_16x16x32_bf16 v[80:83], v[186:189], v[210:213], v[80:83]
	v_mfma_f32_16x16x32_bf16 v[68:71], v[176:179], v[218:221], v[68:71]
	v_mfma_f32_16x16x32_bf16 v[64:67], v[186:189], v[218:221], v[64:67]
	s_barrier
	s_add_i32 s28, s52, s31
	s_mov_b32 m0, s28
	ds_read_b128 v[190:193], v158 offset:49152
	ds_read_b128 v[194:197], v158 offset:50176
	ds_read_b128 v[198:201], v158 offset:51200
	ds_read_b128 v[202:205], v158 offset:52224
	ds_read_b128 v[206:209], v158 offset:53248
	ds_read_b128 v[210:213], v158 offset:54272
	ds_read_b128 v[214:217], v158 offset:55296
	ds_read_b128 v[218:221], v158 offset:56320
	global_load_lds_dwordx4 v132, s[98:99]
	s_add_i32 m0, s28, 0x2000
	s_add_u32 s26, s26, 0x40080
	s_addc_u32 s27, s27, 0
	s_add_i32 s28, s53, s31
	global_load_lds_dwordx4 v128, s[98:99]
	s_mov_b32 m0, s28
	s_nop 0
	global_load_lds_dwordx4 v132, s[26:27]
	s_add_i32 m0, s28, 0x2000
	s_nop 0
	global_load_lds_dwordx4 v128, s[26:27]
	s_mov_b32 m0, s39
	s_nop 0
	global_load_lds_dwordx4 v134, s[100:101]
	s_mov_b32 m0, s40
	s_nop 0
	global_load_lds_dwordx4 v130, s[100:101]
	s_waitcnt vmcnt(8)
	s_waitcnt lgkmcnt(0)
	s_barrier
	s_waitcnt lgkmcnt(0)
	v_mfma_f32_16x16x32_bf16 v[60:63], v[144:147], v[190:193], v[60:63]
	v_mfma_f32_16x16x32_bf16 v[56:59], v[164:167], v[190:193], v[56:59]
	v_mfma_f32_16x16x32_bf16 v[44:47], v[144:147], v[198:201], v[44:47]
	v_mfma_f32_16x16x32_bf16 v[40:43], v[164:167], v[198:201], v[40:43]
	v_mfma_f32_16x16x32_bf16 v[28:31], v[144:147], v[206:209], v[28:31]
	v_mfma_f32_16x16x32_bf16 v[24:27], v[164:167], v[206:209], v[24:27]
	v_mfma_f32_16x16x32_bf16 v[12:15], v[144:147], v[214:217], v[12:15]
	v_mfma_f32_16x16x32_bf16 v[8:11], v[164:167], v[214:217], v[8:11]
	v_mfma_f32_16x16x32_bf16 v[60:63], v[160:163], v[194:197], v[60:63]
	v_mfma_f32_16x16x32_bf16 v[56:59], v[168:171], v[194:197], v[56:59]
	v_mfma_f32_16x16x32_bf16 v[44:47], v[160:163], v[202:205], v[44:47]
	v_mfma_f32_16x16x32_bf16 v[40:43], v[168:171], v[202:205], v[40:43]
	v_mfma_f32_16x16x32_bf16 v[28:31], v[160:163], v[210:213], v[28:31]
	v_mfma_f32_16x16x32_bf16 v[24:27], v[168:171], v[210:213], v[24:27]
	v_mfma_f32_16x16x32_bf16 v[12:15], v[160:163], v[218:221], v[12:15]
	v_mfma_f32_16x16x32_bf16 v[8:11], v[168:171], v[218:221], v[8:11]
	v_mfma_f32_16x16x32_bf16 v[52:55], v[172:175], v[190:193], v[52:55]
	v_mfma_f32_16x16x32_bf16 v[48:51], v[180:183], v[190:193], v[48:51]
	v_mfma_f32_16x16x32_bf16 v[36:39], v[172:175], v[198:201], v[36:39]
	v_mfma_f32_16x16x32_bf16 v[32:35], v[180:183], v[198:201], v[32:35]
	v_mfma_f32_16x16x32_bf16 v[20:23], v[172:175], v[206:209], v[20:23]
	v_mfma_f32_16x16x32_bf16 v[16:19], v[180:183], v[206:209], v[16:19]
	v_mfma_f32_16x16x32_bf16 v[4:7], v[172:175], v[214:217], v[4:7]
	v_mfma_f32_16x16x32_bf16 v[0:3], v[180:183], v[214:217], v[0:3]
	v_mfma_f32_16x16x32_bf16 v[52:55], v[176:179], v[194:197], v[52:55]
	v_mfma_f32_16x16x32_bf16 v[48:51], v[186:189], v[194:197], v[48:51]
	v_mfma_f32_16x16x32_bf16 v[36:39], v[176:179], v[202:205], v[36:39]
	v_mfma_f32_16x16x32_bf16 v[32:35], v[186:189], v[202:205], v[32:35]
	v_mfma_f32_16x16x32_bf16 v[20:23], v[176:179], v[210:213], v[20:23]
	v_mfma_f32_16x16x32_bf16 v[16:19], v[186:189], v[210:213], v[16:19]
	v_mfma_f32_16x16x32_bf16 v[4:7], v[176:179], v[218:221], v[4:7]
	v_mfma_f32_16x16x32_bf16 v[0:3], v[186:189], v[218:221], v[0:3]
	s_barrier
	s_add_i32 s51, s51, 2
	s_add_u32 s24, s24, 0x100
	s_addc_u32 s25, s25, 0
	s_add_u32 s49, s49, 0x100
	s_addc_u32 s50, s50, 0
	s_cmp_gt_u32 s51, 13
	s_cbranch_scc0 .LBB0_1975

.LBB0_2057:
	s_add_u32 s18, s18, 0xb0080
	s_addc_u32 s19, s19, 0
	s_add_u32 s17, s20, 0x100
	s_addc_u32 s42, s21, 0
	s_mov_b32 s43, -2
	ds_read_b128 v[146:149], v155
	ds_read_b128 v[150:153], v155 offset:1024
	ds_read_b128 v[158:161], v155 offset:2048
	ds_read_b128 v[162:165], v155 offset:3072
	ds_read_b128 v[166:169], v156
	ds_read_b128 v[170:173], v156 offset:1024
	ds_read_b128 v[174:177], v156 offset:2048
	ds_read_b128 v[178:181], v156 offset:3072
	s_add_u32 s20, s18, 0xfff50080
	s_addc_u32 s21, s19, -1
	s_cmp_eq_u32 s43, 40
	s_cselect_b32 s23, s5, s21
	s_cselect_b32 s22, s4, s20
	s_cselect_b32 s21, s15, s42
	s_cselect_b32 s20, s14, s17
	s_add_i32 m0, s27, 0xc000
	ds_read_b128 v[182:185], v157
	ds_read_b128 v[186:189], v157 offset:1024
	ds_read_b128 v[190:193], v157 offset:2048
	ds_read_b128 v[194:197], v157 offset:3072
	ds_read_b128 v[198:201], v157 offset:4096
	ds_read_b128 v[202:205], v157 offset:5120
	ds_read_b128 v[206:209], v157 offset:6144
	ds_read_b128 v[210:213], v157 offset:7168
	global_load_lds_dwordx4 v138, s[18:19]
	s_add_i32 m0, s27, 0xe000
	s_nop 0
	global_load_lds_dwordx4 v140, s[18:19]
	s_waitcnt vmcnt(8)
	s_waitcnt lgkmcnt(0)
	s_barrier
	s_waitcnt lgkmcnt(0)
	v_mfma_f32_16x16x32_bf16 v[124:127], v[146:149], v[182:185], 0
	v_mfma_f32_16x16x32_bf16 v[120:123], v[158:161], v[182:185], 0
	v_mfma_f32_16x16x32_bf16 v[116:119], v[146:149], v[190:193], 0
	v_mfma_f32_16x16x32_bf16 v[112:115], v[158:161], v[190:193], 0
	v_mfma_f32_16x16x32_bf16 v[96:99], v[146:149], v[198:201], 0
	v_mfma_f32_16x16x32_bf16 v[88:91], v[158:161], v[198:201], 0
	v_mfma_f32_16x16x32_bf16 v[80:83], v[146:149], v[206:209], 0
	v_mfma_f32_16x16x32_bf16 v[72:75], v[158:161], v[206:209], 0
	v_mfma_f32_16x16x32_bf16 v[124:127], v[150:153], v[186:189], v[124:127]
	v_mfma_f32_16x16x32_bf16 v[120:123], v[162:165], v[186:189], v[120:123]
	v_mfma_f32_16x16x32_bf16 v[116:119], v[150:153], v[194:197], v[116:119]
	v_mfma_f32_16x16x32_bf16 v[112:115], v[162:165], v[194:197], v[112:115]
	v_mfma_f32_16x16x32_bf16 v[96:99], v[150:153], v[202:205], v[96:99]
	v_mfma_f32_16x16x32_bf16 v[88:91], v[162:165], v[202:205], v[88:91]
	v_mfma_f32_16x16x32_bf16 v[80:83], v[150:153], v[210:213], v[80:83]
	v_mfma_f32_16x16x32_bf16 v[72:75], v[162:165], v[210:213], v[72:75]
	v_mfma_f32_16x16x32_bf16 v[108:111], v[166:169], v[182:185], 0
	v_mfma_f32_16x16x32_bf16 v[104:107], v[174:177], v[182:185], 0
	v_mfma_f32_16x16x32_bf16 v[100:103], v[166:169], v[190:193], 0
	v_mfma_f32_16x16x32_bf16 v[92:95], v[174:177], v[190:193], 0
	v_mfma_f32_16x16x32_bf16 v[84:87], v[166:169], v[198:201], 0
	v_mfma_f32_16x16x32_bf16 v[76:79], v[174:177], v[198:201], 0
	v_mfma_f32_16x16x32_bf16 v[68:71], v[166:169], v[206:209], 0
	v_mfma_f32_16x16x32_bf16 v[64:67], v[174:177], v[206:209], 0
	v_mfma_f32_16x16x32_bf16 v[108:111], v[170:173], v[186:189], v[108:111]
	v_mfma_f32_16x16x32_bf16 v[104:107], v[178:181], v[186:189], v[104:107]
	v_mfma_f32_16x16x32_bf16 v[100:103], v[170:173], v[194:197], v[100:103]
	v_mfma_f32_16x16x32_bf16 v[92:95], v[178:181], v[194:197], v[92:95]
	v_mfma_f32_16x16x32_bf16 v[84:87], v[170:173], v[202:205], v[84:87]
	v_mfma_f32_16x16x32_bf16 v[76:79], v[178:181], v[202:205], v[76:79]
	v_mfma_f32_16x16x32_bf16 v[68:71], v[170:173], v[210:213], v[68:71]
	v_mfma_f32_16x16x32_bf16 v[64:67], v[178:181], v[210:213], v[64:67]
	s_barrier
	s_add_i32 s44, s37, s26
	s_mov_b32 m0, s44
	ds_read_b128 v[182:185], v157 offset:16384
	ds_read_b128 v[186:189], v157 offset:17408
	ds_read_b128 v[190:193], v157 offset:18432
	ds_read_b128 v[194:197], v157 offset:19456
	ds_read_b128 v[198:201], v157 offset:20480
	ds_read_b128 v[202:205], v157 offset:21504
	ds_read_b128 v[206:209], v157 offset:22528
	ds_read_b128 v[210:213], v157 offset:23552
	global_load_lds_dwordx4 v130, s[20:21]
	s_add_i32 m0, s44, 0x2000
	s_add_u32 s44, s20, 0xb0000
	s_addc_u32 s45, s21, 0
	s_add_i32 s46, s38, s26
	global_load_lds_dwordx4 v134, s[20:21]
	s_mov_b32 m0, s46
	global_load_lds_dwordx4 v130, s[44:45]
	s_add_i32 m0, s46, 0x2000
	s_nop 0
	global_load_lds_dwordx4 v134, s[44:45]
	s_mov_b32 m0, s27
	s_nop 0
	global_load_lds_dwordx4 v128, s[22:23]
	s_mov_b32 m0, s28
	s_nop 0
	global_load_lds_dwordx4 v132, s[22:23]
	s_add_u32 s98, s20, s10
	s_addc_u32 s99, s21, s11
	s_add_u32 s100, s22, s10
	s_addc_u32 s101, s23, s11
	s_waitcnt vmcnt(8)
	s_waitcnt lgkmcnt(0)
	s_barrier
	s_waitcnt lgkmcnt(0)
	v_mfma_f32_16x16x32_bf16 v[60:63], v[146:149], v[182:185], 0
	v_mfma_f32_16x16x32_bf16 v[56:59], v[158:161], v[182:185], 0
	v_mfma_f32_16x16x32_bf16 v[48:51], v[146:149], v[190:193], 0
	v_mfma_f32_16x16x32_bf16 v[40:43], v[158:161], v[190:193], 0
	v_mfma_f32_16x16x32_bf16 v[32:35], v[146:149], v[198:201], 0
	v_mfma_f32_16x16x32_bf16 v[24:27], v[158:161], v[198:201], 0
	v_mfma_f32_16x16x32_bf16 v[16:19], v[146:149], v[206:209], 0
	v_mfma_f32_16x16x32_bf16 v[8:11], v[158:161], v[206:209], 0
	v_mfma_f32_16x16x32_bf16 v[60:63], v[150:153], v[186:189], v[60:63]
	v_mfma_f32_16x16x32_bf16 v[56:59], v[162:165], v[186:189], v[56:59]
	v_mfma_f32_16x16x32_bf16 v[48:51], v[150:153], v[194:197], v[48:51]
	v_mfma_f32_16x16x32_bf16 v[40:43], v[162:165], v[194:197], v[40:43]
	v_mfma_f32_16x16x32_bf16 v[32:35], v[150:153], v[202:205], v[32:35]
	v_mfma_f32_16x16x32_bf16 v[24:27], v[162:165], v[202:205], v[24:27]
	v_mfma_f32_16x16x32_bf16 v[16:19], v[150:153], v[210:213], v[16:19]
	v_mfma_f32_16x16x32_bf16 v[8:11], v[162:165], v[210:213], v[8:11]
	v_mfma_f32_16x16x32_bf16 v[52:55], v[166:169], v[182:185], 0
	v_mfma_f32_16x16x32_bf16 v[44:47], v[174:177], v[182:185], 0
	v_mfma_f32_16x16x32_bf16 v[36:39], v[166:169], v[190:193], 0
	v_mfma_f32_16x16x32_bf16 v[28:31], v[174:177], v[190:193], 0
	v_mfma_f32_16x16x32_bf16 v[20:23], v[166:169], v[198:201], 0
	v_mfma_f32_16x16x32_bf16 v[12:15], v[174:177], v[198:201], 0
	v_mfma_f32_16x16x32_bf16 v[4:7], v[166:169], v[206:209], 0
	v_mfma_f32_16x16x32_bf16 v[0:3], v[174:177], v[206:209], 0
	v_mfma_f32_16x16x32_bf16 v[52:55], v[170:173], v[186:189], v[52:55]
	v_mfma_f32_16x16x32_bf16 v[44:47], v[178:181], v[186:189], v[44:47]
	v_mfma_f32_16x16x32_bf16 v[36:39], v[170:173], v[194:197], v[36:39]
	v_mfma_f32_16x16x32_bf16 v[28:31], v[178:181], v[194:197], v[28:31]
	v_mfma_f32_16x16x32_bf16 v[20:23], v[170:173], v[202:205], v[20:23]
	v_mfma_f32_16x16x32_bf16 v[12:15], v[178:181], v[202:205], v[12:15]
	v_mfma_f32_16x16x32_bf16 v[4:7], v[170:173], v[210:213], v[4:7]
	v_mfma_f32_16x16x32_bf16 v[0:3], v[178:181], v[210:213], v[0:3]
	s_barrier
	s_add_i32 s44, 0, 0x18000
	s_add_i32 s45, 0, 0x1c000
	v_add_u32_e32 v162, s44, v154
	v_add_u32_e32 v178, s45, v154
	ds_read_b128 v[146:149], v162
	ds_read_b128 v[150:153], v162 offset:1024
	ds_read_b128 v[158:161], v162 offset:2048
	ds_read_b128 v[162:165], v162 offset:3072
	ds_read_b128 v[166:169], v178
	ds_read_b128 v[170:173], v178 offset:1024
	ds_read_b128 v[174:177], v178 offset:2048
	ds_read_b128 v[178:181], v178 offset:3072
	s_add_u32 s22, s22, 0xb0000
	s_addc_u32 s23, s23, 0
	s_mov_b32 m0, s29
	ds_read_b128 v[182:185], v157 offset:32768
	ds_read_b128 v[186:189], v157 offset:33792
	ds_read_b128 v[190:193], v157 offset:34816
	ds_read_b128 v[194:197], v157 offset:35840
	ds_read_b128 v[198:201], v157 offset:36864
	ds_read_b128 v[202:205], v157 offset:37888
	ds_read_b128 v[206:209], v157 offset:38912
	ds_read_b128 v[210:213], v157 offset:39936
	global_load_lds_dwordx4 v128, s[22:23]
	s_mov_b32 m0, s30
	s_nop 0
	global_load_lds_dwordx4 v132, s[22:23]
	s_waitcnt vmcnt(8)
	s_waitcnt lgkmcnt(0)
	s_barrier
	s_waitcnt lgkmcnt(0)
	v_mfma_f32_16x16x32_bf16 v[124:127], v[146:149], v[182:185], v[124:127]
	v_mfma_f32_16x16x32_bf16 v[120:123], v[158:161], v[182:185], v[120:123]
	v_mfma_f32_16x16x32_bf16 v[116:119], v[146:149], v[190:193], v[116:119]
	v_mfma_f32_16x16x32_bf16 v[112:115], v[158:161], v[190:193], v[112:115]
	v_mfma_f32_16x16x32_bf16 v[96:99], v[146:149], v[198:201], v[96:99]
	v_mfma_f32_16x16x32_bf16 v[88:91], v[158:161], v[198:201], v[88:91]
	v_mfma_f32_16x16x32_bf16 v[80:83], v[146:149], v[206:209], v[80:83]
	v_mfma_f32_16x16x32_bf16 v[72:75], v[158:161], v[206:209], v[72:75]
	v_mfma_f32_16x16x32_bf16 v[124:127], v[150:153], v[186:189], v[124:127]
	v_mfma_f32_16x16x32_bf16 v[120:123], v[162:165], v[186:189], v[120:123]
	v_mfma_f32_16x16x32_bf16 v[116:119], v[150:153], v[194:197], v[116:119]
	v_mfma_f32_16x16x32_bf16 v[112:115], v[162:165], v[194:197], v[112:115]
	v_mfma_f32_16x16x32_bf16 v[96:99], v[150:153], v[202:205], v[96:99]
	v_mfma_f32_16x16x32_bf16 v[88:91], v[162:165], v[202:205], v[88:91]
	v_mfma_f32_16x16x32_bf16 v[80:83], v[150:153], v[210:213], v[80:83]
	v_mfma_f32_16x16x32_bf16 v[72:75], v[162:165], v[210:213], v[72:75]
	v_mfma_f32_16x16x32_bf16 v[108:111], v[166:169], v[182:185], v[108:111]
	v_mfma_f32_16x16x32_bf16 v[104:107], v[174:177], v[182:185], v[104:107]
	v_mfma_f32_16x16x32_bf16 v[100:103], v[166:169], v[190:193], v[100:103]
	v_mfma_f32_16x16x32_bf16 v[92:95], v[174:177], v[190:193], v[92:95]
	v_mfma_f32_16x16x32_bf16 v[84:87], v[166:169], v[198:201], v[84:87]
	v_mfma_f32_16x16x32_bf16 v[76:79], v[174:177], v[198:201], v[76:79]
	v_mfma_f32_16x16x32_bf16 v[68:71], v[166:169], v[206:209], v[68:71]
	v_mfma_f32_16x16x32_bf16 v[64:67], v[174:177], v[206:209], v[64:67]
	v_mfma_f32_16x16x32_bf16 v[108:111], v[170:173], v[186:189], v[108:111]
	v_mfma_f32_16x16x32_bf16 v[104:107], v[178:181], v[186:189], v[104:107]
	v_mfma_f32_16x16x32_bf16 v[100:103], v[170:173], v[194:197], v[100:103]
	v_mfma_f32_16x16x32_bf16 v[92:95], v[178:181], v[194:197], v[92:95]
	v_mfma_f32_16x16x32_bf16 v[84:87], v[170:173], v[202:205], v[84:87]
	v_mfma_f32_16x16x32_bf16 v[76:79], v[178:181], v[202:205], v[76:79]
	v_mfma_f32_16x16x32_bf16 v[68:71], v[170:173], v[210:213], v[68:71]
	v_mfma_f32_16x16x32_bf16 v[64:67], v[178:181], v[210:213], v[64:67]
	s_barrier
	s_add_i32 s22, s44, s26
	s_mov_b32 m0, s22
	ds_read_b128 v[182:185], v157 offset:49152
	ds_read_b128 v[186:189], v157 offset:50176
	ds_read_b128 v[190:193], v157 offset:51200
	ds_read_b128 v[194:197], v157 offset:52224
	ds_read_b128 v[198:201], v157 offset:53248
	ds_read_b128 v[202:205], v157 offset:54272
	ds_read_b128 v[206:209], v157 offset:55296
	ds_read_b128 v[210:213], v157 offset:56320
	global_load_lds_dwordx4 v130, s[98:99]
	s_add_i32 m0, s22, 0x2000
	s_add_u32 s20, s20, 0xb0080
	s_addc_u32 s21, s21, 0
	s_add_i32 s22, s45, s26
	global_load_lds_dwordx4 v134, s[98:99]
	s_mov_b32 m0, s22
	s_nop 0
	global_load_lds_dwordx4 v130, s[20:21]
	s_add_i32 m0, s22, 0x2000
	s_nop 0
	global_load_lds_dwordx4 v134, s[20:21]
	s_mov_b32 m0, s33
	s_nop 0
	global_load_lds_dwordx4 v128, s[100:101]
	s_mov_b32 m0, s34
	s_nop 0
	global_load_lds_dwordx4 v132, s[100:101]
	s_waitcnt vmcnt(8)
	s_waitcnt lgkmcnt(0)
	s_barrier
	s_waitcnt lgkmcnt(0)
	v_mfma_f32_16x16x32_bf16 v[60:63], v[146:149], v[182:185], v[60:63]
	v_mfma_f32_16x16x32_bf16 v[56:59], v[158:161], v[182:185], v[56:59]
	v_mfma_f32_16x16x32_bf16 v[48:51], v[146:149], v[190:193], v[48:51]
	v_mfma_f32_16x16x32_bf16 v[40:43], v[158:161], v[190:193], v[40:43]
	v_mfma_f32_16x16x32_bf16 v[32:35], v[146:149], v[198:201], v[32:35]
	v_mfma_f32_16x16x32_bf16 v[24:27], v[158:161], v[198:201], v[24:27]
	v_mfma_f32_16x16x32_bf16 v[16:19], v[146:149], v[206:209], v[16:19]
	v_mfma_f32_16x16x32_bf16 v[8:11], v[158:161], v[206:209], v[8:11]
	v_mfma_f32_16x16x32_bf16 v[60:63], v[150:153], v[186:189], v[60:63]
	v_mfma_f32_16x16x32_bf16 v[56:59], v[162:165], v[186:189], v[56:59]
	v_mfma_f32_16x16x32_bf16 v[48:51], v[150:153], v[194:197], v[48:51]
	v_mfma_f32_16x16x32_bf16 v[40:43], v[162:165], v[194:197], v[40:43]
	v_mfma_f32_16x16x32_bf16 v[32:35], v[150:153], v[202:205], v[32:35]
	v_mfma_f32_16x16x32_bf16 v[24:27], v[162:165], v[202:205], v[24:27]
	v_mfma_f32_16x16x32_bf16 v[16:19], v[150:153], v[210:213], v[16:19]
	v_mfma_f32_16x16x32_bf16 v[8:11], v[162:165], v[210:213], v[8:11]
	v_mfma_f32_16x16x32_bf16 v[52:55], v[166:169], v[182:185], v[52:55]
	v_mfma_f32_16x16x32_bf16 v[44:47], v[174:177], v[182:185], v[44:47]
	v_mfma_f32_16x16x32_bf16 v[36:39], v[166:169], v[190:193], v[36:39]
	v_mfma_f32_16x16x32_bf16 v[28:31], v[174:177], v[190:193], v[28:31]
	v_mfma_f32_16x16x32_bf16 v[20:23], v[166:169], v[198:201], v[20:23]
	v_mfma_f32_16x16x32_bf16 v[12:15], v[174:177], v[198:201], v[12:15]
	v_mfma_f32_16x16x32_bf16 v[4:7], v[166:169], v[206:209], v[4:7]
	v_mfma_f32_16x16x32_bf16 v[0:3], v[174:177], v[206:209], v[0:3]
	v_mfma_f32_16x16x32_bf16 v[52:55], v[170:173], v[186:189], v[52:55]
	v_mfma_f32_16x16x32_bf16 v[44:47], v[178:181], v[186:189], v[44:47]
	v_mfma_f32_16x16x32_bf16 v[36:39], v[170:173], v[194:197], v[36:39]
	v_mfma_f32_16x16x32_bf16 v[28:31], v[178:181], v[194:197], v[28:31]
	v_mfma_f32_16x16x32_bf16 v[20:23], v[170:173], v[202:205], v[20:23]
	v_mfma_f32_16x16x32_bf16 v[12:15], v[178:181], v[202:205], v[12:15]
	v_mfma_f32_16x16x32_bf16 v[4:7], v[170:173], v[210:213], v[4:7]
	v_mfma_f32_16x16x32_bf16 v[0:3], v[178:181], v[210:213], v[0:3]
	s_barrier
	s_add_i32 s43, s43, 2
	s_add_u32 s18, s18, 0x100
	s_addc_u32 s19, s19, 0
	s_add_u32 s17, s17, 0x100
	s_addc_u32 s42, s42, 0
	s_cmp_gt_u32 s43, 41
	s_cbranch_scc1 .Lpeel_exit_2058
